# K-loops: A-operand refills (SA00, SA10) issued one phase earlier, right after the buffer's read phase, waits recounted
# baseline (speedup 1.0000x reference)
.Lpk_wait_ret:
	s_add_u32 s14, s12, 0x100
	s_addc_u32 s15, s13, 0
	s_add_i32 s34, 0, 0x10000
	v_add_u32_e32 v0, s34, v165
	ds_read_b128 v[90:93], v0
	ds_read_b128 v[94:97], v0 offset:1024
	ds_read_b128 v[98:101], v0 offset:2048
	ds_read_b128 v[102:105], v0 offset:3072
	s_cmp_eq_u32 s50, 40
	s_cselect_b32 s3, s1, s15
	s_cselect_b32 s2, s0, s14
	s_cselect_b32 s17, s11, s39
	s_cselect_b32 s16, s10, s38
	v_lshl_add_u64 v[162:163], s[12:13], 0, v[150:151]
	s_add_i32 m0, s51, 0xc000
	ds_read_b128 v[154:157], v167
	ds_read_b128 v[158:161], v167 offset:1024
	ds_read_b128 v[168:171], v167 offset:2048
	ds_read_b128 v[172:175], v167 offset:3072
	ds_read_b128 v[176:179], v167 offset:4096
	ds_read_b128 v[180:183], v167 offset:5120
	ds_read_b128 v[184:187], v167 offset:6144
	ds_read_b128 v[188:191], v167 offset:7168
	global_load_lds_dwordx4 v[162:163], off
	v_lshl_add_u64 v[162:163], s[12:13], 0, v[152:153]
	s_add_i32 m0, s51, 0xe000
	s_nop 0
	global_load_lds_dwordx4 v[162:163], off
	s_waitcnt vmcnt(10)
	s_waitcnt lgkmcnt(8)
	s_barrier
	s_waitcnt lgkmcnt(0)
	s_setprio 1
	s_waitcnt lgkmcnt(0)
	v_mfma_f32_16x16x32_bf16 v[142:145], v[90:93], v[154:157], v[142:145]
	v_mfma_f32_16x16x32_bf16 v[138:141], v[98:101], v[154:157], v[138:141]
	v_mfma_f32_16x16x32_bf16 v[126:129], v[90:93], v[168:171], v[126:129]
	v_mfma_f32_16x16x32_bf16 v[122:125], v[98:101], v[168:171], v[122:125]
	v_mfma_f32_16x16x32_bf16 v[110:113], v[90:93], v[176:179], v[110:113]
	v_mfma_f32_16x16x32_bf16 v[106:109], v[98:101], v[176:179], v[106:109]
	v_mfma_f32_16x16x32_bf16 v[78:81], v[90:93], v[184:187], v[78:81]
	v_mfma_f32_16x16x32_bf16 v[74:77], v[98:101], v[184:187], v[74:77]
	v_mfma_f32_16x16x32_bf16 v[142:145], v[94:97], v[158:161], v[142:145]
	v_mfma_f32_16x16x32_bf16 v[138:141], v[102:105], v[158:161], v[138:141]
	v_mfma_f32_16x16x32_bf16 v[126:129], v[94:97], v[172:175], v[126:129]
	v_mfma_f32_16x16x32_bf16 v[122:125], v[102:105], v[172:175], v[122:125]
	v_mfma_f32_16x16x32_bf16 v[110:113], v[94:97], v[180:183], v[110:113]
	v_mfma_f32_16x16x32_bf16 v[106:109], v[102:105], v[180:183], v[106:109]
	v_mfma_f32_16x16x32_bf16 v[78:81], v[94:97], v[188:191], v[78:81]
	v_mfma_f32_16x16x32_bf16 v[74:77], v[102:105], v[188:191], v[74:77]
	s_setprio 0
	s_barrier
	s_add_i32 s35, 0, 0x14000
	s_add_i32 s12, s34, s45
	v_add_u32_e32 v0, s35, v165
	v_lshl_add_u64 v[162:163], s[16:17], 0, v[148:149]
	s_mov_b32 m0, s12
	ds_read_b128 v[196:199], v0
	ds_read_b128 v[200:203], v0 offset:1024
	ds_read_b128 v[206:209], v0 offset:2048
	ds_read_b128 v[210:213], v0 offset:3072
	global_load_lds_dwordx4 v[162:163], off
	v_lshl_add_u64 v[192:193], s[16:17], 0, v[146:147]
	s_add_i32 m0, s12, 0x2000
	s_nop 0
	global_load_lds_dwordx4 v[192:193], off
	s_mov_b32 m0, s51
	v_lshl_add_u64 v[214:215], s[2:3], 0, v[148:149]
	global_load_lds_dwordx4 v[214:215], off
	v_lshl_add_u64 v[216:217], s[2:3], 0, v[146:147]
	s_mov_b32 m0, s52
	s_nop 0
	global_load_lds_dwordx4 v[216:217], off
	s_waitcnt vmcnt(12)
	s_barrier
	s_waitcnt lgkmcnt(0)
	s_setprio 1
	s_waitcnt lgkmcnt(0)
	v_mfma_f32_16x16x32_bf16 v[134:137], v[196:199], v[154:157], v[134:137]
	v_mfma_f32_16x16x32_bf16 v[130:133], v[206:209], v[154:157], v[130:133]
	v_mfma_f32_16x16x32_bf16 v[118:121], v[196:199], v[168:171], v[118:121]
	v_mfma_f32_16x16x32_bf16 v[114:117], v[206:209], v[168:171], v[114:117]
	v_mfma_f32_16x16x32_bf16 v[86:89], v[196:199], v[176:179], v[86:89]
	v_mfma_f32_16x16x32_bf16 v[82:85], v[206:209], v[176:179], v[82:85]
	v_mfma_f32_16x16x32_bf16 v[70:73], v[196:199], v[184:187], v[70:73]
	v_mfma_f32_16x16x32_bf16 v[66:69], v[206:209], v[184:187], v[66:69]
	v_mfma_f32_16x16x32_bf16 v[134:137], v[200:203], v[158:161], v[134:137]
	v_mfma_f32_16x16x32_bf16 v[130:133], v[210:213], v[158:161], v[130:133]
	v_mfma_f32_16x16x32_bf16 v[118:121], v[200:203], v[172:175], v[118:121]
	v_mfma_f32_16x16x32_bf16 v[114:117], v[210:213], v[172:175], v[114:117]
	v_mfma_f32_16x16x32_bf16 v[86:89], v[200:203], v[180:183], v[86:89]
	v_mfma_f32_16x16x32_bf16 v[82:85], v[210:213], v[180:183], v[82:85]
	v_mfma_f32_16x16x32_bf16 v[70:73], v[200:203], v[188:191], v[70:73]
	v_mfma_f32_16x16x32_bf16 v[66:69], v[210:213], v[188:191], v[66:69]
	s_setprio 0
	s_barrier
	ds_read_b128 v[154:157], v167 offset:16384
	ds_read_b128 v[158:161], v167 offset:17408
	ds_read_b128 v[168:171], v167 offset:18432
	ds_read_b128 v[172:175], v167 offset:19456
	ds_read_b128 v[176:179], v167 offset:20480
	ds_read_b128 v[180:183], v167 offset:21504
	ds_read_b128 v[184:187], v167 offset:22528
	ds_read_b128 v[188:191], v167 offset:23552
	s_barrier
	s_waitcnt lgkmcnt(0)
	s_setprio 1
	s_waitcnt lgkmcnt(0)
	v_mfma_f32_16x16x32_bf16 v[62:65], v[90:93], v[154:157], v[62:65]
	v_mfma_f32_16x16x32_bf16 v[58:61], v[98:101], v[154:157], v[58:61]
	v_mfma_f32_16x16x32_bf16 v[54:57], v[90:93], v[168:171], v[54:57]
	v_mfma_f32_16x16x32_bf16 v[50:53], v[98:101], v[168:171], v[50:53]
	v_mfma_f32_16x16x32_bf16 v[30:33], v[90:93], v[176:179], v[30:33]
	v_mfma_f32_16x16x32_bf16 v[26:29], v[98:101], v[176:179], v[26:29]
	v_mfma_f32_16x16x32_bf16 v[22:25], v[90:93], v[184:187], v[22:25]
	v_mfma_f32_16x16x32_bf16 v[18:21], v[98:101], v[184:187], v[18:21]
	v_mfma_f32_16x16x32_bf16 v[62:65], v[94:97], v[158:161], v[62:65]
	v_mfma_f32_16x16x32_bf16 v[58:61], v[102:105], v[158:161], v[58:61]
	v_mfma_f32_16x16x32_bf16 v[54:57], v[94:97], v[172:175], v[54:57]
	v_mfma_f32_16x16x32_bf16 v[50:53], v[102:105], v[172:175], v[50:53]
	v_mfma_f32_16x16x32_bf16 v[30:33], v[94:97], v[180:183], v[30:33]
	v_mfma_f32_16x16x32_bf16 v[26:29], v[102:105], v[180:183], v[26:29]
	v_mfma_f32_16x16x32_bf16 v[22:25], v[94:97], v[188:191], v[22:25]
	v_mfma_f32_16x16x32_bf16 v[18:21], v[102:105], v[188:191], v[18:21]
	s_setprio 0
	s_barrier
	s_add_u32 s12, s16, 0xb0000
	s_addc_u32 s13, s17, 0
	s_add_i32 s34, s35, s45
	v_lshl_add_u64 v[90:91], s[12:13], 0, v[148:149]
	s_mov_b32 m0, s34
	s_nop 0
	global_load_lds_dwordx4 v[90:91], off
	v_lshl_add_u64 v[90:91], s[12:13], 0, v[146:147]
	s_add_i32 m0, s34, 0x2000
	s_nop 0
	global_load_lds_dwordx4 v[90:91], off
	s_waitcnt vmcnt(10)
	s_barrier
	s_setprio 1
	v_mfma_f32_16x16x32_bf16 v[46:49], v[196:199], v[154:157], v[46:49]
	v_mfma_f32_16x16x32_bf16 v[42:45], v[206:209], v[154:157], v[42:45]
	v_mfma_f32_16x16x32_bf16 v[38:41], v[196:199], v[168:171], v[38:41]
	v_mfma_f32_16x16x32_bf16 v[34:37], v[206:209], v[168:171], v[34:37]
	v_mfma_f32_16x16x32_bf16 v[14:17], v[196:199], v[176:179], v[14:17]
	v_mfma_f32_16x16x32_bf16 v[10:13], v[206:209], v[176:179], v[10:13]
	v_mfma_f32_16x16x32_bf16 v[6:9], v[196:199], v[184:187], v[6:9]
	v_mfma_f32_16x16x32_bf16 v[2:5], v[206:209], v[184:187], v[2:5]
	v_mfma_f32_16x16x32_bf16 v[46:49], v[200:203], v[158:161], v[46:49]
	v_mfma_f32_16x16x32_bf16 v[42:45], v[210:213], v[158:161], v[42:45]
	v_mfma_f32_16x16x32_bf16 v[38:41], v[200:203], v[172:175], v[38:41]
	v_mfma_f32_16x16x32_bf16 v[34:37], v[210:213], v[172:175], v[34:37]
	v_mfma_f32_16x16x32_bf16 v[14:17], v[200:203], v[180:183], v[14:17]
	v_mfma_f32_16x16x32_bf16 v[10:13], v[210:213], v[180:183], v[10:13]
	v_mfma_f32_16x16x32_bf16 v[6:9], v[200:203], v[188:191], v[6:9]
	v_mfma_f32_16x16x32_bf16 v[2:5], v[210:213], v[188:191], v[2:5]
	s_setprio 0
	s_add_i32 s12, 0, 0x18000
	v_add_u32_e32 v0, s12, v165
	s_barrier
	ds_read_b128 v[90:93], v0
	ds_read_b128 v[94:97], v0 offset:1024
	ds_read_b128 v[98:101], v0 offset:2048
	ds_read_b128 v[102:105], v0 offset:3072
	s_add_u32 s2, s2, 0xb0000
	s_addc_u32 s3, s3, 0
	s_mov_b32 m0, s53
	v_lshl_add_u64 v[196:197], s[2:3], 0, v[148:149]
	ds_read_b128 v[154:157], v167 offset:32768
	ds_read_b128 v[158:161], v167 offset:33792
	ds_read_b128 v[168:171], v167 offset:34816
	ds_read_b128 v[172:175], v167 offset:35840
	ds_read_b128 v[176:179], v167 offset:36864
	ds_read_b128 v[180:183], v167 offset:37888
	ds_read_b128 v[184:187], v167 offset:38912
	ds_read_b128 v[188:191], v167 offset:39936
	global_load_lds_dwordx4 v[196:197], off
	v_lshl_add_u64 v[196:197], s[2:3], 0, v[146:147]
	s_mov_b32 m0, s59
	s_nop 0
	global_load_lds_dwordx4 v[196:197], off
	s_waitcnt vmcnt(10)
	s_waitcnt lgkmcnt(8)
	s_barrier
	s_waitcnt lgkmcnt(0)
	s_setprio 1
	s_waitcnt lgkmcnt(0)
	v_mfma_f32_16x16x32_bf16 v[142:145], v[90:93], v[154:157], v[142:145]
	v_mfma_f32_16x16x32_bf16 v[138:141], v[98:101], v[154:157], v[138:141]
	v_mfma_f32_16x16x32_bf16 v[126:129], v[90:93], v[168:171], v[126:129]
	v_mfma_f32_16x16x32_bf16 v[122:125], v[98:101], v[168:171], v[122:125]
	v_mfma_f32_16x16x32_bf16 v[110:113], v[90:93], v[176:179], v[110:113]
	v_mfma_f32_16x16x32_bf16 v[106:109], v[98:101], v[176:179], v[106:109]
	v_mfma_f32_16x16x32_bf16 v[78:81], v[90:93], v[184:187], v[78:81]
	v_mfma_f32_16x16x32_bf16 v[74:77], v[98:101], v[184:187], v[74:77]
	v_mfma_f32_16x16x32_bf16 v[142:145], v[94:97], v[158:161], v[142:145]
	v_mfma_f32_16x16x32_bf16 v[138:141], v[102:105], v[158:161], v[138:141]
	v_mfma_f32_16x16x32_bf16 v[126:129], v[94:97], v[172:175], v[126:129]
	v_mfma_f32_16x16x32_bf16 v[122:125], v[102:105], v[172:175], v[122:125]
	v_mfma_f32_16x16x32_bf16 v[110:113], v[94:97], v[180:183], v[110:113]
	v_mfma_f32_16x16x32_bf16 v[106:109], v[102:105], v[180:183], v[106:109]
	v_mfma_f32_16x16x32_bf16 v[78:81], v[94:97], v[188:191], v[78:81]
	v_mfma_f32_16x16x32_bf16 v[74:77], v[102:105], v[188:191], v[74:77]
	s_setprio 0
	s_barrier
	s_add_i32 s13, 0, 0x1c000
	s_add_i32 s2, s12, s45
	v_add_u32_e32 v0, s13, v165
	v_lshl_add_u64 v[162:163], v[162:163], 0, s[74:75]
	s_mov_b32 m0, s2
	ds_read_b128 v[196:199], v0
	ds_read_b128 v[200:203], v0 offset:1024
	ds_read_b128 v[206:209], v0 offset:2048
	ds_read_b128 v[210:213], v0 offset:3072
	global_load_lds_dwordx4 v[162:163], off
	v_lshl_add_u64 v[162:163], v[192:193], 0, s[74:75]
	s_add_i32 m0, s2, 0x2000
	s_nop 0
	global_load_lds_dwordx4 v[162:163], off
	s_mov_b32 m0, s67
	v_lshl_add_u64 v[162:163], v[214:215], 0, s[74:75]
	global_load_lds_dwordx4 v[162:163], off
	v_lshl_add_u64 v[162:163], v[216:217], 0, s[74:75]
	s_mov_b32 m0, s72
	s_nop 0
	global_load_lds_dwordx4 v[162:163], off
	s_waitcnt vmcnt(12)
	s_barrier
	s_waitcnt lgkmcnt(0)
	s_setprio 1
	s_waitcnt lgkmcnt(0)
	v_mfma_f32_16x16x32_bf16 v[134:137], v[196:199], v[154:157], v[134:137]
	v_mfma_f32_16x16x32_bf16 v[130:133], v[206:209], v[154:157], v[130:133]
	v_mfma_f32_16x16x32_bf16 v[118:121], v[196:199], v[168:171], v[118:121]
	v_mfma_f32_16x16x32_bf16 v[114:117], v[206:209], v[168:171], v[114:117]
	v_mfma_f32_16x16x32_bf16 v[86:89], v[196:199], v[176:179], v[86:89]
	v_mfma_f32_16x16x32_bf16 v[82:85], v[206:209], v[176:179], v[82:85]
	v_mfma_f32_16x16x32_bf16 v[70:73], v[196:199], v[184:187], v[70:73]
	v_mfma_f32_16x16x32_bf16 v[66:69], v[206:209], v[184:187], v[66:69]
	v_mfma_f32_16x16x32_bf16 v[134:137], v[200:203], v[158:161], v[134:137]
	v_mfma_f32_16x16x32_bf16 v[130:133], v[210:213], v[158:161], v[130:133]
	v_mfma_f32_16x16x32_bf16 v[118:121], v[200:203], v[172:175], v[118:121]
	v_mfma_f32_16x16x32_bf16 v[114:117], v[210:213], v[172:175], v[114:117]
	v_mfma_f32_16x16x32_bf16 v[86:89], v[200:203], v[180:183], v[86:89]
	v_mfma_f32_16x16x32_bf16 v[82:85], v[210:213], v[180:183], v[82:85]
	v_mfma_f32_16x16x32_bf16 v[70:73], v[200:203], v[188:191], v[70:73]
	v_mfma_f32_16x16x32_bf16 v[66:69], v[210:213], v[188:191], v[66:69]
	s_setprio 0
	s_barrier
	ds_read_b128 v[154:157], v167 offset:49152
	ds_read_b128 v[158:161], v167 offset:50176
	ds_read_b128 v[168:171], v167 offset:51200
	ds_read_b128 v[172:175], v167 offset:52224
	ds_read_b128 v[176:179], v167 offset:53248
	ds_read_b128 v[180:183], v167 offset:54272
	ds_read_b128 v[184:187], v167 offset:55296
	ds_read_b128 v[188:191], v167 offset:56320
	s_barrier
	s_waitcnt lgkmcnt(0)
	s_setprio 1
	s_waitcnt lgkmcnt(0)
	v_mfma_f32_16x16x32_bf16 v[62:65], v[90:93], v[154:157], v[62:65]
	v_mfma_f32_16x16x32_bf16 v[58:61], v[98:101], v[154:157], v[58:61]
	v_mfma_f32_16x16x32_bf16 v[54:57], v[90:93], v[168:171], v[54:57]
	v_mfma_f32_16x16x32_bf16 v[50:53], v[98:101], v[168:171], v[50:53]
	v_mfma_f32_16x16x32_bf16 v[30:33], v[90:93], v[176:179], v[30:33]
	v_mfma_f32_16x16x32_bf16 v[26:29], v[98:101], v[176:179], v[26:29]
	v_mfma_f32_16x16x32_bf16 v[22:25], v[90:93], v[184:187], v[22:25]
	v_mfma_f32_16x16x32_bf16 v[18:21], v[98:101], v[184:187], v[18:21]
	v_mfma_f32_16x16x32_bf16 v[62:65], v[94:97], v[158:161], v[62:65]
	v_mfma_f32_16x16x32_bf16 v[58:61], v[102:105], v[158:161], v[58:61]
	v_mfma_f32_16x16x32_bf16 v[54:57], v[94:97], v[172:175], v[54:57]
	v_mfma_f32_16x16x32_bf16 v[50:53], v[102:105], v[172:175], v[50:53]
	v_mfma_f32_16x16x32_bf16 v[30:33], v[94:97], v[180:183], v[30:33]
	v_mfma_f32_16x16x32_bf16 v[26:29], v[102:105], v[180:183], v[26:29]
	v_mfma_f32_16x16x32_bf16 v[22:25], v[94:97], v[188:191], v[22:25]
	v_mfma_f32_16x16x32_bf16 v[18:21], v[102:105], v[188:191], v[18:21]
	s_setprio 0
	s_barrier
	s_add_u32 s2, s16, 0xb0080
	s_addc_u32 s3, s17, 0
	s_add_i32 s12, s13, s45
	v_lshl_add_u64 v[90:91], s[2:3], 0, v[148:149]
	s_mov_b32 m0, s12
	s_nop 0
	global_load_lds_dwordx4 v[90:91], off
	v_lshl_add_u64 v[90:91], s[2:3], 0, v[146:147]
	s_add_i32 m0, s12, 0x2000
	s_nop 0
	global_load_lds_dwordx4 v[90:91], off
	s_waitcnt vmcnt(10)
	s_barrier
	s_setprio 1
	v_mfma_f32_16x16x32_bf16 v[46:49], v[196:199], v[154:157], v[46:49]
	v_mfma_f32_16x16x32_bf16 v[42:45], v[206:209], v[154:157], v[42:45]
	v_mfma_f32_16x16x32_bf16 v[38:41], v[196:199], v[168:171], v[38:41]
	v_mfma_f32_16x16x32_bf16 v[34:37], v[206:209], v[168:171], v[34:37]
	v_mfma_f32_16x16x32_bf16 v[14:17], v[196:199], v[176:179], v[14:17]
	v_mfma_f32_16x16x32_bf16 v[10:13], v[206:209], v[176:179], v[10:13]
	v_mfma_f32_16x16x32_bf16 v[6:9], v[196:199], v[184:187], v[6:9]
	v_mfma_f32_16x16x32_bf16 v[2:5], v[206:209], v[184:187], v[2:5]
	v_mfma_f32_16x16x32_bf16 v[46:49], v[200:203], v[158:161], v[46:49]
	v_mfma_f32_16x16x32_bf16 v[42:45], v[210:213], v[158:161], v[42:45]
	v_mfma_f32_16x16x32_bf16 v[38:41], v[200:203], v[172:175], v[38:41]
	v_mfma_f32_16x16x32_bf16 v[34:37], v[210:213], v[172:175], v[34:37]
	v_mfma_f32_16x16x32_bf16 v[14:17], v[200:203], v[180:183], v[14:17]
	v_mfma_f32_16x16x32_bf16 v[10:13], v[210:213], v[180:183], v[10:13]
	v_mfma_f32_16x16x32_bf16 v[6:9], v[200:203], v[188:191], v[6:9]
	v_mfma_f32_16x16x32_bf16 v[2:5], v[210:213], v[188:191], v[2:5]
	s_setprio 0
	s_add_i32 s50, s50, 2
	s_add_u32 s38, s38, 0x100
	s_addc_u32 s39, s39, 0
	s_cmp_gt_u32 s50, 41
	s_mov_b64 s[12:13], s[14:15]
	s_barrier
	s_cbranch_scc0 .LBB0_40
	v_lshl_add_u32 v156, s54, 8, v164
	v_add_u32_e32 v158, 0xffffe000, v156
	v_lshrrev_b32_e32 v0, 11, v158
	s_movk_i32 s2, 0x1800
	v_mad_u32_u24 v0, v0, s2, s2
	v_cmp_lt_i32_e32 vcc, s40, v156
	v_lshl_or_b32 v154, s49, 8, v166
	v_ashrrev_i32_e32 v155, 31, v154
	v_cndmask_b32_e32 v0, 0, v0, vcc
	v_lshl_add_u64 v[90:91], v[0:1], 2, s[8:9]
	v_lshl_add_u64 v[90:91], v[154:155], 2, v[90:91]
	global_load_dwordx4 v[102:105], v[90:91], off
	global_load_dwordx4 v[98:101], v[90:91], off offset:64
	global_load_dwordx4 v[94:97], v[90:91], off offset:512
	s_nop 0
	global_load_dwordx4 v[90:93], v[90:91], off offset:576
	s_and_saveexec_b64 s[2:3], vcc
	s_xor_b64 s[2:3], exec, s[2:3]
	s_cbranch_execz .LBB0_43
	v_mov_b32_e32 v159, v1
	v_readlane_b32 s12, v249, 10
	v_lshlrev_b64 v[158:159], 12, v[158:159]
	v_readlane_b32 s13, v249, 11
	v_mov_b32_e32 v157, v1
	v_lshlrev_b64 v[160:161], 12, v[156:157]
	v_lshl_add_u64 v[162:163], s[12:13], 0, v[158:159]

.LBB0_113:
	s_add_u32 s2, s14, 0xfffc0080
	s_addc_u32 s3, s15, -1
	s_add_i32 s34, 0, 0x10000
	v_add_u32_e32 v145, s34, v143
	ds_read_b128 v[146:149], v145
	ds_read_b128 v[150:153], v145 offset:1024
	ds_read_b128 v[154:157], v145 offset:2048
	ds_read_b128 v[158:161], v145 offset:3072
	s_cmp_eq_u32 s56, 12
	s_cselect_b32 s3, s9, s3
	s_cselect_b32 s2, s49, s2
	s_cselect_b32 s17, s7, s50
	s_cselect_b32 s16, s54, s55
	v_lshl_add_u64 v[196:197], s[14:15], 0, v[138:139]
	s_add_i32 m0, s39, 0xc000
	ds_read_b128 v[162:165], v144
	ds_read_b128 v[166:169], v144 offset:1024
	ds_read_b128 v[170:173], v144 offset:2048
	ds_read_b128 v[174:177], v144 offset:3072
	ds_read_b128 v[178:181], v144 offset:4096
	ds_read_b128 v[182:185], v144 offset:5120
	ds_read_b128 v[186:189], v144 offset:6144
	ds_read_b128 v[190:193], v144 offset:7168
	global_load_lds_dwordx4 v[196:197], off
	v_lshl_add_u64 v[196:197], s[14:15], 0, v[140:141]
	s_add_i32 m0, s39, 0xe000
	s_nop 0
	global_load_lds_dwordx4 v[196:197], off
	s_waitcnt vmcnt(10)
	s_waitcnt lgkmcnt(8)
	s_barrier
	s_waitcnt lgkmcnt(0)
	s_setprio 1
	s_waitcnt lgkmcnt(0)
	v_mfma_f32_16x16x32_bf16 v[126:129], v[146:149], v[162:165], v[126:129]
	v_mfma_f32_16x16x32_bf16 v[118:121], v[154:157], v[162:165], v[118:121]
	v_mfma_f32_16x16x32_bf16 v[110:113], v[146:149], v[170:173], v[110:113]
	v_mfma_f32_16x16x32_bf16 v[102:105], v[154:157], v[170:173], v[102:105]
	v_mfma_f32_16x16x32_bf16 v[94:97], v[146:149], v[178:181], v[94:97]
	v_mfma_f32_16x16x32_bf16 v[86:89], v[154:157], v[178:181], v[86:89]
	v_mfma_f32_16x16x32_bf16 v[78:81], v[146:149], v[186:189], v[78:81]
	v_mfma_f32_16x16x32_bf16 v[70:73], v[154:157], v[186:189], v[70:73]
	v_mfma_f32_16x16x32_bf16 v[126:129], v[150:153], v[166:169], v[126:129]
	v_mfma_f32_16x16x32_bf16 v[118:121], v[158:161], v[166:169], v[118:121]
	v_mfma_f32_16x16x32_bf16 v[110:113], v[150:153], v[174:177], v[110:113]
	v_mfma_f32_16x16x32_bf16 v[102:105], v[158:161], v[174:177], v[102:105]
	v_mfma_f32_16x16x32_bf16 v[94:97], v[150:153], v[182:185], v[94:97]
	v_mfma_f32_16x16x32_bf16 v[86:89], v[158:161], v[182:185], v[86:89]
	v_mfma_f32_16x16x32_bf16 v[78:81], v[150:153], v[190:193], v[78:81]
	v_mfma_f32_16x16x32_bf16 v[70:73], v[158:161], v[190:193], v[70:73]
	s_setprio 0
	s_barrier
	s_add_i32 s40, 0, 0x14000
	s_add_i32 s34, s34, s38
	v_add_u32_e32 v145, s40, v143
	v_lshl_add_u64 v[214:215], s[16:17], 0, v[134:135]
	s_mov_b32 m0, s34
	ds_read_b128 v[196:199], v145
	ds_read_b128 v[200:203], v145 offset:1024
	ds_read_b128 v[206:209], v145 offset:2048
	ds_read_b128 v[210:213], v145 offset:3072
	global_load_lds_dwordx4 v[214:215], off
	v_lshl_add_u64 v[216:217], s[16:17], 0, v[130:131]
	s_add_i32 m0, s34, 0x2000
	s_nop 0
	global_load_lds_dwordx4 v[216:217], off
	s_mov_b32 m0, s39
	v_lshl_add_u64 v[218:219], s[2:3], 0, v[136:137]
	global_load_lds_dwordx4 v[218:219], off
	v_lshl_add_u64 v[220:221], s[2:3], 0, v[132:133]
	s_mov_b32 m0, s45
	s_nop 0
	global_load_lds_dwordx4 v[220:221], off
	s_waitcnt vmcnt(12)
	s_barrier
	s_waitcnt lgkmcnt(0)
	s_setprio 1
	s_waitcnt lgkmcnt(0)
	v_mfma_f32_16x16x32_bf16 v[122:125], v[196:199], v[162:165], v[122:125]
	v_mfma_f32_16x16x32_bf16 v[114:117], v[206:209], v[162:165], v[114:117]
	v_mfma_f32_16x16x32_bf16 v[106:109], v[196:199], v[170:173], v[106:109]
	v_mfma_f32_16x16x32_bf16 v[98:101], v[206:209], v[170:173], v[98:101]
	v_mfma_f32_16x16x32_bf16 v[90:93], v[196:199], v[178:181], v[90:93]
	v_mfma_f32_16x16x32_bf16 v[82:85], v[206:209], v[178:181], v[82:85]
	v_mfma_f32_16x16x32_bf16 v[74:77], v[196:199], v[186:189], v[74:77]
	v_mfma_f32_16x16x32_bf16 v[66:69], v[206:209], v[186:189], v[66:69]
	v_mfma_f32_16x16x32_bf16 v[122:125], v[200:203], v[166:169], v[122:125]
	v_mfma_f32_16x16x32_bf16 v[114:117], v[210:213], v[166:169], v[114:117]
	v_mfma_f32_16x16x32_bf16 v[106:109], v[200:203], v[174:177], v[106:109]
	v_mfma_f32_16x16x32_bf16 v[98:101], v[210:213], v[174:177], v[98:101]
	v_mfma_f32_16x16x32_bf16 v[90:93], v[200:203], v[182:185], v[90:93]
	v_mfma_f32_16x16x32_bf16 v[82:85], v[210:213], v[182:185], v[82:85]
	v_mfma_f32_16x16x32_bf16 v[74:77], v[200:203], v[190:193], v[74:77]
	v_mfma_f32_16x16x32_bf16 v[66:69], v[210:213], v[190:193], v[66:69]
	s_setprio 0
	s_barrier
	ds_read_b128 v[162:165], v144 offset:16384
	ds_read_b128 v[166:169], v144 offset:17408
	ds_read_b128 v[170:173], v144 offset:18432
	ds_read_b128 v[174:177], v144 offset:19456
	ds_read_b128 v[178:181], v144 offset:20480
	ds_read_b128 v[182:185], v144 offset:21504
	ds_read_b128 v[186:189], v144 offset:22528
	ds_read_b128 v[190:193], v144 offset:23552
	s_barrier
	s_waitcnt lgkmcnt(0)
	s_setprio 1
	s_waitcnt lgkmcnt(0)
	v_mfma_f32_16x16x32_bf16 v[62:65], v[146:149], v[162:165], v[62:65]
	v_mfma_f32_16x16x32_bf16 v[54:57], v[154:157], v[162:165], v[54:57]
	v_mfma_f32_16x16x32_bf16 v[46:49], v[146:149], v[170:173], v[46:49]
	v_mfma_f32_16x16x32_bf16 v[38:41], v[154:157], v[170:173], v[38:41]
	v_mfma_f32_16x16x32_bf16 v[30:33], v[146:149], v[178:181], v[30:33]
	v_mfma_f32_16x16x32_bf16 v[22:25], v[154:157], v[178:181], v[22:25]
	v_mfma_f32_16x16x32_bf16 v[14:17], v[146:149], v[186:189], v[14:17]
	v_mfma_f32_16x16x32_bf16 v[6:9], v[154:157], v[186:189], v[6:9]
	v_mfma_f32_16x16x32_bf16 v[62:65], v[150:153], v[166:169], v[62:65]
	v_mfma_f32_16x16x32_bf16 v[54:57], v[158:161], v[166:169], v[54:57]
	v_mfma_f32_16x16x32_bf16 v[46:49], v[150:153], v[174:177], v[46:49]
	v_mfma_f32_16x16x32_bf16 v[38:41], v[158:161], v[174:177], v[38:41]
	v_mfma_f32_16x16x32_bf16 v[30:33], v[150:153], v[182:185], v[30:33]
	v_mfma_f32_16x16x32_bf16 v[22:25], v[158:161], v[182:185], v[22:25]
	v_mfma_f32_16x16x32_bf16 v[14:17], v[150:153], v[190:193], v[14:17]
	v_mfma_f32_16x16x32_bf16 v[6:9], v[158:161], v[190:193], v[6:9]
	s_setprio 0
	s_barrier
	s_add_u32 s34, s16, 0x40000
	s_addc_u32 s35, s17, 0
	s_add_i32 s40, s40, s38
	v_lshl_add_u64 v[146:147], s[34:35], 0, v[134:135]
	s_mov_b32 m0, s40
	s_nop 0
	global_load_lds_dwordx4 v[146:147], off
	v_lshl_add_u64 v[146:147], s[34:35], 0, v[130:131]
	s_add_i32 m0, s40, 0x2000
	s_nop 0
	global_load_lds_dwordx4 v[146:147], off
	s_waitcnt vmcnt(10)
	s_barrier
	s_setprio 1
	v_mfma_f32_16x16x32_bf16 v[58:61], v[196:199], v[162:165], v[58:61]
	v_mfma_f32_16x16x32_bf16 v[50:53], v[206:209], v[162:165], v[50:53]
	v_mfma_f32_16x16x32_bf16 v[42:45], v[196:199], v[170:173], v[42:45]
	v_mfma_f32_16x16x32_bf16 v[34:37], v[206:209], v[170:173], v[34:37]
	v_mfma_f32_16x16x32_bf16 v[26:29], v[196:199], v[178:181], v[26:29]
	v_mfma_f32_16x16x32_bf16 v[18:21], v[206:209], v[178:181], v[18:21]
	v_mfma_f32_16x16x32_bf16 v[10:13], v[196:199], v[186:189], v[10:13]
	v_mfma_f32_16x16x32_bf16 v[2:5], v[206:209], v[186:189], v[2:5]
	v_mfma_f32_16x16x32_bf16 v[58:61], v[200:203], v[166:169], v[58:61]
	v_mfma_f32_16x16x32_bf16 v[50:53], v[210:213], v[166:169], v[50:53]
	v_mfma_f32_16x16x32_bf16 v[42:45], v[200:203], v[174:177], v[42:45]
	v_mfma_f32_16x16x32_bf16 v[34:37], v[210:213], v[174:177], v[34:37]
	v_mfma_f32_16x16x32_bf16 v[26:29], v[200:203], v[182:185], v[26:29]
	v_mfma_f32_16x16x32_bf16 v[18:21], v[210:213], v[182:185], v[18:21]
	v_mfma_f32_16x16x32_bf16 v[10:13], v[200:203], v[190:193], v[10:13]
	v_mfma_f32_16x16x32_bf16 v[2:5], v[210:213], v[190:193], v[2:5]
	s_setprio 0
	s_add_i32 s34, 0, 0x18000
	v_add_u32_e32 v145, s34, v143
	s_barrier
	ds_read_b128 v[146:149], v145
	ds_read_b128 v[150:153], v145 offset:1024
	ds_read_b128 v[154:157], v145 offset:2048
	ds_read_b128 v[158:161], v145 offset:3072
	s_add_u32 s2, s2, 0x40000
	s_addc_u32 s3, s3, 0
	s_mov_b32 m0, s51
	v_lshl_add_u64 v[196:197], s[2:3], 0, v[136:137]
	ds_read_b128 v[162:165], v144 offset:32768
	ds_read_b128 v[166:169], v144 offset:33792
	ds_read_b128 v[170:173], v144 offset:34816
	ds_read_b128 v[174:177], v144 offset:35840
	ds_read_b128 v[178:181], v144 offset:36864
	ds_read_b128 v[182:185], v144 offset:37888
	ds_read_b128 v[186:189], v144 offset:38912
	ds_read_b128 v[190:193], v144 offset:39936
	global_load_lds_dwordx4 v[196:197], off
	v_lshl_add_u64 v[196:197], s[2:3], 0, v[132:133]
	s_mov_b32 m0, s52
	s_nop 0
	global_load_lds_dwordx4 v[196:197], off
	s_waitcnt vmcnt(10)
	s_waitcnt lgkmcnt(8)
	s_barrier
	s_waitcnt lgkmcnt(0)
	s_setprio 1
	s_waitcnt lgkmcnt(0)
	v_mfma_f32_16x16x32_bf16 v[126:129], v[146:149], v[162:165], v[126:129]
	v_mfma_f32_16x16x32_bf16 v[118:121], v[154:157], v[162:165], v[118:121]
	v_mfma_f32_16x16x32_bf16 v[110:113], v[146:149], v[170:173], v[110:113]
	v_mfma_f32_16x16x32_bf16 v[102:105], v[154:157], v[170:173], v[102:105]
	v_mfma_f32_16x16x32_bf16 v[94:97], v[146:149], v[178:181], v[94:97]
	v_mfma_f32_16x16x32_bf16 v[86:89], v[154:157], v[178:181], v[86:89]
	v_mfma_f32_16x16x32_bf16 v[78:81], v[146:149], v[186:189], v[78:81]
	v_mfma_f32_16x16x32_bf16 v[70:73], v[154:157], v[186:189], v[70:73]
	v_mfma_f32_16x16x32_bf16 v[126:129], v[150:153], v[166:169], v[126:129]
	v_mfma_f32_16x16x32_bf16 v[118:121], v[158:161], v[166:169], v[118:121]
	v_mfma_f32_16x16x32_bf16 v[110:113], v[150:153], v[174:177], v[110:113]
	v_mfma_f32_16x16x32_bf16 v[102:105], v[158:161], v[174:177], v[102:105]
	v_mfma_f32_16x16x32_bf16 v[94:97], v[150:153], v[182:185], v[94:97]
	v_mfma_f32_16x16x32_bf16 v[86:89], v[158:161], v[182:185], v[86:89]
	v_mfma_f32_16x16x32_bf16 v[78:81], v[150:153], v[190:193], v[78:81]
	v_mfma_f32_16x16x32_bf16 v[70:73], v[158:161], v[190:193], v[70:73]
	s_setprio 0
	s_barrier
	s_add_i32 s35, 0, 0x1c000
	s_add_i32 s2, s34, s38
	v_add_u32_e32 v145, s35, v143
	v_lshl_add_u64 v[214:215], v[214:215], 0, s[74:75]
	s_mov_b32 m0, s2
	ds_read_b128 v[196:199], v145
	ds_read_b128 v[200:203], v145 offset:1024
	ds_read_b128 v[206:209], v145 offset:2048
	ds_read_b128 v[210:213], v145 offset:3072
	global_load_lds_dwordx4 v[214:215], off
	v_lshl_add_u64 v[214:215], v[216:217], 0, s[74:75]
	s_add_i32 m0, s2, 0x2000
	s_nop 0
	global_load_lds_dwordx4 v[214:215], off
	s_mov_b32 m0, s53
	v_lshl_add_u64 v[214:215], v[218:219], 0, s[74:75]
	global_load_lds_dwordx4 v[214:215], off
	v_lshl_add_u64 v[214:215], v[220:221], 0, s[74:75]
	s_mov_b32 m0, s59
	s_nop 0
	global_load_lds_dwordx4 v[214:215], off
	s_waitcnt vmcnt(12)
	s_barrier
	s_waitcnt lgkmcnt(0)
	s_setprio 1
	s_waitcnt lgkmcnt(0)
	v_mfma_f32_16x16x32_bf16 v[122:125], v[196:199], v[162:165], v[122:125]
	v_mfma_f32_16x16x32_bf16 v[114:117], v[206:209], v[162:165], v[114:117]
	v_mfma_f32_16x16x32_bf16 v[106:109], v[196:199], v[170:173], v[106:109]
	v_mfma_f32_16x16x32_bf16 v[98:101], v[206:209], v[170:173], v[98:101]
	v_mfma_f32_16x16x32_bf16 v[90:93], v[196:199], v[178:181], v[90:93]
	v_mfma_f32_16x16x32_bf16 v[82:85], v[206:209], v[178:181], v[82:85]
	v_mfma_f32_16x16x32_bf16 v[74:77], v[196:199], v[186:189], v[74:77]
	v_mfma_f32_16x16x32_bf16 v[66:69], v[206:209], v[186:189], v[66:69]
	v_mfma_f32_16x16x32_bf16 v[122:125], v[200:203], v[166:169], v[122:125]
	v_mfma_f32_16x16x32_bf16 v[114:117], v[210:213], v[166:169], v[114:117]
	v_mfma_f32_16x16x32_bf16 v[106:109], v[200:203], v[174:177], v[106:109]
	v_mfma_f32_16x16x32_bf16 v[98:101], v[210:213], v[174:177], v[98:101]
	v_mfma_f32_16x16x32_bf16 v[90:93], v[200:203], v[182:185], v[90:93]
	v_mfma_f32_16x16x32_bf16 v[82:85], v[210:213], v[182:185], v[82:85]
	v_mfma_f32_16x16x32_bf16 v[74:77], v[200:203], v[190:193], v[74:77]
	v_mfma_f32_16x16x32_bf16 v[66:69], v[210:213], v[190:193], v[66:69]
	s_setprio 0
	s_barrier
	ds_read_b128 v[162:165], v144 offset:49152
	ds_read_b128 v[166:169], v144 offset:50176
	ds_read_b128 v[170:173], v144 offset:51200
	ds_read_b128 v[174:177], v144 offset:52224
	ds_read_b128 v[178:181], v144 offset:53248
	ds_read_b128 v[182:185], v144 offset:54272
	ds_read_b128 v[186:189], v144 offset:55296
	ds_read_b128 v[190:193], v144 offset:56320
	s_barrier
	s_waitcnt lgkmcnt(0)
	s_setprio 1
	s_waitcnt lgkmcnt(0)
	v_mfma_f32_16x16x32_bf16 v[62:65], v[146:149], v[162:165], v[62:65]
	v_mfma_f32_16x16x32_bf16 v[54:57], v[154:157], v[162:165], v[54:57]
	v_mfma_f32_16x16x32_bf16 v[46:49], v[146:149], v[170:173], v[46:49]
	v_mfma_f32_16x16x32_bf16 v[38:41], v[154:157], v[170:173], v[38:41]
	v_mfma_f32_16x16x32_bf16 v[30:33], v[146:149], v[178:181], v[30:33]
	v_mfma_f32_16x16x32_bf16 v[22:25], v[154:157], v[178:181], v[22:25]
	v_mfma_f32_16x16x32_bf16 v[14:17], v[146:149], v[186:189], v[14:17]
	v_mfma_f32_16x16x32_bf16 v[6:9], v[154:157], v[186:189], v[6:9]
	v_mfma_f32_16x16x32_bf16 v[62:65], v[150:153], v[166:169], v[62:65]
	v_mfma_f32_16x16x32_bf16 v[54:57], v[158:161], v[166:169], v[54:57]
	v_mfma_f32_16x16x32_bf16 v[46:49], v[150:153], v[174:177], v[46:49]
	v_mfma_f32_16x16x32_bf16 v[38:41], v[158:161], v[174:177], v[38:41]
	v_mfma_f32_16x16x32_bf16 v[30:33], v[150:153], v[182:185], v[30:33]
	v_mfma_f32_16x16x32_bf16 v[22:25], v[158:161], v[182:185], v[22:25]
	v_mfma_f32_16x16x32_bf16 v[14:17], v[150:153], v[190:193], v[14:17]
	v_mfma_f32_16x16x32_bf16 v[6:9], v[158:161], v[190:193], v[6:9]
	s_setprio 0
	s_barrier
	s_add_u32 s2, s16, 0x40080
	s_addc_u32 s3, s17, 0
	s_add_i32 s16, s35, s38
	v_lshl_add_u64 v[146:147], s[2:3], 0, v[134:135]
	s_mov_b32 m0, s16
	s_nop 0
	global_load_lds_dwordx4 v[146:147], off
	v_lshl_add_u64 v[146:147], s[2:3], 0, v[130:131]
	s_add_i32 m0, s16, 0x2000
	s_nop 0
	global_load_lds_dwordx4 v[146:147], off
	s_waitcnt vmcnt(10)
	s_barrier
	s_setprio 1
	v_mfma_f32_16x16x32_bf16 v[58:61], v[196:199], v[162:165], v[58:61]
	v_mfma_f32_16x16x32_bf16 v[50:53], v[206:209], v[162:165], v[50:53]
	v_mfma_f32_16x16x32_bf16 v[42:45], v[196:199], v[170:173], v[42:45]
	v_mfma_f32_16x16x32_bf16 v[34:37], v[206:209], v[170:173], v[34:37]
	v_mfma_f32_16x16x32_bf16 v[26:29], v[196:199], v[178:181], v[26:29]
	v_mfma_f32_16x16x32_bf16 v[18:21], v[206:209], v[178:181], v[18:21]
	v_mfma_f32_16x16x32_bf16 v[10:13], v[196:199], v[186:189], v[10:13]
	v_mfma_f32_16x16x32_bf16 v[2:5], v[206:209], v[186:189], v[2:5]
	v_mfma_f32_16x16x32_bf16 v[58:61], v[200:203], v[166:169], v[58:61]
	v_mfma_f32_16x16x32_bf16 v[50:53], v[210:213], v[166:169], v[50:53]
	v_mfma_f32_16x16x32_bf16 v[42:45], v[200:203], v[174:177], v[42:45]
	v_mfma_f32_16x16x32_bf16 v[34:37], v[210:213], v[174:177], v[34:37]
	v_mfma_f32_16x16x32_bf16 v[26:29], v[200:203], v[182:185], v[26:29]
	v_mfma_f32_16x16x32_bf16 v[18:21], v[210:213], v[182:185], v[18:21]
	v_mfma_f32_16x16x32_bf16 v[10:13], v[200:203], v[190:193], v[10:13]
	v_mfma_f32_16x16x32_bf16 v[2:5], v[210:213], v[190:193], v[2:5]
	s_setprio 0
	s_add_i32 s56, s56, 2
	s_add_u32 s14, s14, 0x100
	s_addc_u32 s15, s15, 0
	s_add_u32 s55, s55, 0x100
	s_addc_u32 s50, s50, 0
	s_cmp_gt_u32 s56, 13
	s_barrier
	s_cbranch_scc0 .LBB0_113
	v_mul_f32_e32 v146, 0xbfb8aa3b, v126
	v_mul_f32_e32 v147, 0xbfb8aa3b, v127
	v_exp_f32_e32 v146, v146
	v_exp_f32_e32 v147, v147
	v_readlane_b32 s2, v249, 15
	v_readlane_b32 s3, v249, 16
	v_add_f32_e32 v146, 1.0, v146
	v_add_f32_e32 v147, 1.0, v147
	v_rcp_f32_e32 v146, v146
	v_rcp_f32_e32 v147, v147
	v_lshl_add_u32 v145, s18, 8, v142
	s_movk_i32 s7, 0x1600
	s_and_b64 vcc, exec, s[36:37]
	v_pk_mul_f32 v[126:127], v[126:127], v[146:147]
	s_mov_b32 s18, s8
	v_pk_mul_f32 v[122:123], v[126:127], v[122:123]
	s_nop 0
	v_cvt_pk_bf16_f32 v122, v122, v123
	v_mul_f32_e32 v123, 0xbfb8aa3b, v128
	v_exp_f32_e32 v123, v123
	s_nop 0
	v_add_f32_e32 v123, 1.0, v123
	v_rcp_f32_e32 v126, v123
	v_mul_f32_e32 v123, 0xbfb8aa3b, v129
	v_exp_f32_e32 v123, v123
	s_nop 0
	v_add_f32_e32 v123, 1.0, v123
	v_rcp_f32_e32 v127, v123
	s_nop 0
	v_pk_mul_f32 v[126:127], v[128:129], v[126:127]
	s_nop 0
	v_pk_mul_f32 v[124:125], v[126:127], v[124:125]
	s_nop 0
	v_cvt_pk_bf16_f32 v123, v124, v125
	v_mul_f32_e32 v124, 0xbfb8aa3b, v118
	v_mul_f32_e32 v125, 0xbfb8aa3b, v119
	v_exp_f32_e32 v124, v124
	v_exp_f32_e32 v125, v125
	v_add_f32_e32 v124, 1.0, v124
	v_add_f32_e32 v125, 1.0, v125
	v_rcp_f32_e32 v124, v124
	v_rcp_f32_e32 v125, v125
	s_nop 0
	v_pk_mul_f32 v[118:119], v[118:119], v[124:125]
	s_nop 0
	v_pk_mul_f32 v[114:115], v[118:119], v[114:115]
	v_or_b32_e32 v118, 16, v145
	v_cvt_pk_bf16_f32 v124, v114, v115
	v_mul_f32_e32 v114, 0xbfb8aa3b, v120
	v_mul_f32_e32 v115, 0xbfb8aa3b, v121
	v_exp_f32_e32 v114, v114
	v_exp_f32_e32 v115, v115
	v_add_f32_e32 v114, 1.0, v114
	v_add_f32_e32 v115, 1.0, v115
	v_rcp_f32_e32 v114, v114
	v_rcp_f32_e32 v115, v115
	s_nop 0
	v_pk_mul_f32 v[114:115], v[120:121], v[114:115]
	s_nop 0
	v_pk_mul_f32 v[114:115], v[114:115], v[116:117]
	s_nop 0
	v_cvt_pk_bf16_f32 v125, v114, v115
	v_mov_b64_e32 v[114:115], s[2:3]
	v_mad_i64_i32 v[116:117], s[2:3], v145, s7, v[114:115]
	s_lshl_b32 s2, s1, 7
	s_ashr_i32 s3, s2, 31
	s_lshl_b64 s[14:15], s[2:3], 1
	v_lshl_add_u64 v[116:117], v[116:117], 0, s[14:15]
	s_mov_b32 s1, s4
	v_lshl_add_u64 v[116:117], v[116:117], 0, s[0:1]
	v_lshl_add_u64 v[116:117], v[116:117], 0, v[0:1]
	global_store_dwordx4 v[116:117], v[122:125], off
	v_mul_f32_e32 v116, 0xbfb8aa3b, v110
	v_mul_f32_e32 v117, 0xbfb8aa3b, v111
	v_exp_f32_e32 v116, v116
	v_exp_f32_e32 v117, v117
	v_add_f32_e32 v116, 1.0, v116
	v_add_f32_e32 v117, 1.0, v117
	v_rcp_f32_e32 v116, v116
	v_rcp_f32_e32 v117, v117
	s_nop 0
	v_pk_mul_f32 v[110:111], v[110:111], v[116:117]
	s_nop 0
	v_pk_mul_f32 v[106:107], v[110:111], v[106:107]
	s_nop 0
	v_cvt_pk_bf16_f32 v106, v106, v107
	v_mul_f32_e32 v107, 0xbfb8aa3b, v112
	v_exp_f32_e32 v107, v107
	s_nop 0
	v_add_f32_e32 v107, 1.0, v107
	v_rcp_f32_e32 v110, v107
	v_mul_f32_e32 v107, 0xbfb8aa3b, v113
	v_exp_f32_e32 v107, v107
	s_nop 0
	v_add_f32_e32 v107, 1.0, v107
	v_rcp_f32_e32 v111, v107
	s_nop 0
	v_pk_mul_f32 v[110:111], v[112:113], v[110:111]
	s_nop 0
	v_pk_mul_f32 v[108:109], v[110:111], v[108:109]
	s_nop 0
	v_cvt_pk_bf16_f32 v107, v108, v109
	v_mul_f32_e32 v108, 0xbfb8aa3b, v102
	v_mul_f32_e32 v109, 0xbfb8aa3b, v103
	v_exp_f32_e32 v108, v108
	v_exp_f32_e32 v109, v109
	v_add_f32_e32 v108, 1.0, v108
	v_add_f32_e32 v109, 1.0, v109
	v_rcp_f32_e32 v108, v108
	v_rcp_f32_e32 v109, v109
	s_nop 0
	v_pk_mul_f32 v[102:103], v[102:103], v[108:109]
	s_nop 0
	v_pk_mul_f32 v[98:99], v[102:103], v[98:99]
	s_nop 0
	v_cvt_pk_bf16_f32 v108, v98, v99
	v_mul_f32_e32 v98, 0xbfb8aa3b, v104
	v_mul_f32_e32 v99, 0xbfb8aa3b, v105
	v_exp_f32_e32 v98, v98
	v_exp_f32_e32 v99, v99
	v_add_f32_e32 v98, 1.0, v98
	v_add_f32_e32 v99, 1.0, v99
	v_rcp_f32_e32 v98, v98
	v_rcp_f32_e32 v99, v99
	s_nop 0
	v_pk_mul_f32 v[98:99], v[104:105], v[98:99]
	s_nop 0
	v_pk_mul_f32 v[98:99], v[98:99], v[100:101]
	v_or_b32_e32 v100, 32, v145
	v_cvt_pk_bf16_f32 v109, v98, v99
	v_mad_i64_i32 v[98:99], s[2:3], v118, s7, v[114:115]
	v_lshl_add_u64 v[98:99], v[98:99], 0, s[14:15]
	v_lshl_add_u64 v[98:99], v[98:99], 0, s[0:1]
	v_lshl_add_u64 v[98:99], v[98:99], 0, v[0:1]
	global_store_dwordx4 v[98:99], v[106:109], off
	v_mul_f32_e32 v98, 0xbfb8aa3b, v94
	v_mul_f32_e32 v99, 0xbfb8aa3b, v95
	v_exp_f32_e32 v98, v98
	v_exp_f32_e32 v99, v99
	v_add_f32_e32 v98, 1.0, v98
	v_add_f32_e32 v99, 1.0, v99
	v_rcp_f32_e32 v98, v98
	v_rcp_f32_e32 v99, v99
	s_nop 0
	v_pk_mul_f32 v[94:95], v[94:95], v[98:99]
	s_nop 0
	v_pk_mul_f32 v[90:91], v[94:95], v[90:91]
	s_nop 0
	v_cvt_pk_bf16_f32 v90, v90, v91
	v_mul_f32_e32 v91, 0xbfb8aa3b, v96
	v_exp_f32_e32 v91, v91
	s_nop 0
	v_add_f32_e32 v91, 1.0, v91
	v_rcp_f32_e32 v94, v91
	v_mul_f32_e32 v91, 0xbfb8aa3b, v97
	v_exp_f32_e32 v91, v91
	s_nop 0
	v_add_f32_e32 v91, 1.0, v91
	v_rcp_f32_e32 v95, v91
	s_nop 0
	v_pk_mul_f32 v[94:95], v[96:97], v[94:95]
	s_nop 0
	v_pk_mul_f32 v[92:93], v[94:95], v[92:93]
	s_nop 0
	v_cvt_pk_bf16_f32 v91, v92, v93
	v_mul_f32_e32 v92, 0xbfb8aa3b, v86
	v_mul_f32_e32 v93, 0xbfb8aa3b, v87
	v_exp_f32_e32 v92, v92
	v_exp_f32_e32 v93, v93
	v_add_f32_e32 v92, 1.0, v92
	v_add_f32_e32 v93, 1.0, v93
	v_rcp_f32_e32 v92, v92
	v_rcp_f32_e32 v93, v93
	s_nop 0
	v_pk_mul_f32 v[86:87], v[86:87], v[92:93]
	s_nop 0
	v_pk_mul_f32 v[82:83], v[86:87], v[82:83]
	s_nop 0
	v_cvt_pk_bf16_f32 v92, v82, v83
	v_mul_f32_e32 v82, 0xbfb8aa3b, v88
	v_mul_f32_e32 v83, 0xbfb8aa3b, v89
	v_exp_f32_e32 v82, v82
	v_exp_f32_e32 v83, v83
	v_add_f32_e32 v82, 1.0, v82
	v_add_f32_e32 v83, 1.0, v83
	v_rcp_f32_e32 v82, v82
	v_rcp_f32_e32 v83, v83
	s_nop 0
	v_pk_mul_f32 v[82:83], v[88:89], v[82:83]
	s_nop 0
	v_pk_mul_f32 v[82:83], v[82:83], v[84:85]
	v_or_b32_e32 v84, 48, v145
	v_cvt_pk_bf16_f32 v93, v82, v83
	v_mad_i64_i32 v[82:83], s[2:3], v100, s7, v[114:115]
	v_lshl_add_u64 v[82:83], v[82:83], 0, s[14:15]
	v_lshl_add_u64 v[82:83], v[82:83], 0, s[0:1]
	v_lshl_add_u64 v[82:83], v[82:83], 0, v[0:1]
	global_store_dwordx4 v[82:83], v[90:93], off
	v_mul_f32_e32 v82, 0xbfb8aa3b, v78
	v_mul_f32_e32 v83, 0xbfb8aa3b, v79
	v_exp_f32_e32 v82, v82
	v_exp_f32_e32 v83, v83
	v_add_f32_e32 v82, 1.0, v82
	v_add_f32_e32 v83, 1.0, v83
	v_rcp_f32_e32 v82, v82
	v_rcp_f32_e32 v83, v83
	s_nop 0
	v_pk_mul_f32 v[78:79], v[78:79], v[82:83]
	s_nop 0
	v_pk_mul_f32 v[74:75], v[78:79], v[74:75]
	s_nop 0
	v_cvt_pk_bf16_f32 v74, v74, v75
	v_mul_f32_e32 v75, 0xbfb8aa3b, v80
	v_exp_f32_e32 v75, v75
	s_nop 0
	v_add_f32_e32 v75, 1.0, v75
	v_rcp_f32_e32 v78, v75
	v_mul_f32_e32 v75, 0xbfb8aa3b, v81
	v_exp_f32_e32 v75, v75
	s_nop 0
	v_add_f32_e32 v75, 1.0, v75
	v_rcp_f32_e32 v79, v75
	s_nop 0
	v_pk_mul_f32 v[78:79], v[80:81], v[78:79]
	s_nop 0
	v_pk_mul_f32 v[76:77], v[78:79], v[76:77]
	s_nop 0
	v_cvt_pk_bf16_f32 v75, v76, v77
	v_mul_f32_e32 v76, 0xbfb8aa3b, v70
	v_mul_f32_e32 v77, 0xbfb8aa3b, v71
	v_exp_f32_e32 v76, v76
	v_exp_f32_e32 v77, v77
	v_add_f32_e32 v76, 1.0, v76
	v_add_f32_e32 v77, 1.0, v77
	v_rcp_f32_e32 v76, v76
	v_rcp_f32_e32 v77, v77
	s_nop 0
	v_pk_mul_f32 v[70:71], v[70:71], v[76:77]
	s_nop 0
	v_pk_mul_f32 v[66:67], v[70:71], v[66:67]
	s_nop 0
	v_cvt_pk_bf16_f32 v76, v66, v67
	v_mul_f32_e32 v66, 0xbfb8aa3b, v72
	v_mul_f32_e32 v67, 0xbfb8aa3b, v73
	v_exp_f32_e32 v66, v66
	v_exp_f32_e32 v67, v67
	v_add_f32_e32 v66, 1.0, v66
	v_add_f32_e32 v67, 1.0, v67
	v_rcp_f32_e32 v66, v66
	v_rcp_f32_e32 v67, v67
	s_nop 0
	v_pk_mul_f32 v[66:67], v[72:73], v[66:67]
	s_nop 0
	v_pk_mul_f32 v[66:67], v[66:67], v[68:69]
	v_add_u32_e32 v68, 0x80, v145
	v_cvt_pk_bf16_f32 v77, v66, v67
	v_mad_i64_i32 v[66:67], s[2:3], v84, s7, v[114:115]
	v_lshl_add_u64 v[66:67], v[66:67], 0, s[14:15]
	v_lshl_add_u64 v[66:67], v[66:67], 0, s[0:1]
	v_lshl_add_u64 v[66:67], v[66:67], 0, v[0:1]
	global_store_dwordx4 v[66:67], v[74:77], off
	v_mul_f32_e32 v66, 0xbfb8aa3b, v62
	v_mul_f32_e32 v67, 0xbfb8aa3b, v63
	v_exp_f32_e32 v66, v66
	v_exp_f32_e32 v67, v67
	v_add_f32_e32 v66, 1.0, v66
	v_add_f32_e32 v67, 1.0, v67
	v_rcp_f32_e32 v66, v66
	v_rcp_f32_e32 v67, v67
	s_nop 0
	v_pk_mul_f32 v[62:63], v[62:63], v[66:67]
	s_nop 0
	v_pk_mul_f32 v[58:59], v[62:63], v[58:59]
	s_nop 0
	v_cvt_pk_bf16_f32 v58, v58, v59
	v_mul_f32_e32 v59, 0xbfb8aa3b, v64
	v_exp_f32_e32 v59, v59
	s_nop 0
	v_add_f32_e32 v59, 1.0, v59
	v_rcp_f32_e32 v62, v59
	v_mul_f32_e32 v59, 0xbfb8aa3b, v65
	v_exp_f32_e32 v59, v59
	s_nop 0
	v_add_f32_e32 v59, 1.0, v59
	v_rcp_f32_e32 v63, v59
	s_nop 0
	v_pk_mul_f32 v[62:63], v[64:65], v[62:63]
	s_nop 0
	v_pk_mul_f32 v[60:61], v[62:63], v[60:61]
	s_nop 0
	v_cvt_pk_bf16_f32 v59, v60, v61
	v_mul_f32_e32 v60, 0xbfb8aa3b, v54
	v_mul_f32_e32 v61, 0xbfb8aa3b, v55
	v_exp_f32_e32 v60, v60
	v_exp_f32_e32 v61, v61
	v_add_f32_e32 v60, 1.0, v60
	v_add_f32_e32 v61, 1.0, v61
	v_rcp_f32_e32 v60, v60
	v_rcp_f32_e32 v61, v61
	s_nop 0
	v_pk_mul_f32 v[54:55], v[54:55], v[60:61]
	s_nop 0
	v_pk_mul_f32 v[50:51], v[54:55], v[50:51]
	s_nop 0
	v_cvt_pk_bf16_f32 v60, v50, v51
	v_mul_f32_e32 v50, 0xbfb8aa3b, v56
	v_mul_f32_e32 v51, 0xbfb8aa3b, v57
	v_exp_f32_e32 v50, v50
	v_exp_f32_e32 v51, v51
	v_add_f32_e32 v50, 1.0, v50
	v_add_f32_e32 v51, 1.0, v51
	v_rcp_f32_e32 v50, v50
	v_rcp_f32_e32 v51, v51
	s_nop 0
	v_pk_mul_f32 v[50:51], v[56:57], v[50:51]
	s_nop 0
	v_pk_mul_f32 v[50:51], v[50:51], v[52:53]
	v_add_u32_e32 v52, 0x90, v145
	v_cvt_pk_bf16_f32 v61, v50, v51
	v_mad_i64_i32 v[50:51], s[2:3], v68, s7, v[114:115]
	v_lshl_add_u64 v[50:51], v[50:51], 0, s[14:15]
	v_lshl_add_u64 v[50:51], v[50:51], 0, s[0:1]
	v_lshl_add_u64 v[50:51], v[50:51], 0, v[0:1]
	global_store_dwordx4 v[50:51], v[58:61], off
	v_mul_f32_e32 v50, 0xbfb8aa3b, v46
	v_mul_f32_e32 v51, 0xbfb8aa3b, v47
	v_exp_f32_e32 v50, v50
	v_exp_f32_e32 v51, v51
	v_add_f32_e32 v50, 1.0, v50
	v_add_f32_e32 v51, 1.0, v51
	v_rcp_f32_e32 v50, v50
	v_rcp_f32_e32 v51, v51
	s_nop 0
	v_pk_mul_f32 v[46:47], v[46:47], v[50:51]
	s_nop 0
	v_pk_mul_f32 v[42:43], v[46:47], v[42:43]
	s_nop 0
	v_cvt_pk_bf16_f32 v42, v42, v43
	v_mul_f32_e32 v43, 0xbfb8aa3b, v48
	v_exp_f32_e32 v43, v43
	s_nop 0
	v_add_f32_e32 v43, 1.0, v43
	v_rcp_f32_e32 v46, v43
	v_mul_f32_e32 v43, 0xbfb8aa3b, v49
	v_exp_f32_e32 v43, v43
	s_nop 0
	v_add_f32_e32 v43, 1.0, v43
	v_rcp_f32_e32 v47, v43
	s_nop 0
	v_pk_mul_f32 v[46:47], v[48:49], v[46:47]
	s_nop 0
	v_pk_mul_f32 v[44:45], v[46:47], v[44:45]
	s_nop 0
	v_cvt_pk_bf16_f32 v43, v44, v45
	v_mul_f32_e32 v44, 0xbfb8aa3b, v38
	v_mul_f32_e32 v45, 0xbfb8aa3b, v39
	v_exp_f32_e32 v44, v44
	v_exp_f32_e32 v45, v45
	v_add_f32_e32 v44, 1.0, v44
	v_add_f32_e32 v45, 1.0, v45
	v_rcp_f32_e32 v44, v44
	v_rcp_f32_e32 v45, v45
	s_nop 0
	v_pk_mul_f32 v[38:39], v[38:39], v[44:45]
	s_nop 0
	v_pk_mul_f32 v[34:35], v[38:39], v[34:35]
	s_nop 0
	v_cvt_pk_bf16_f32 v44, v34, v35
	v_mul_f32_e32 v34, 0xbfb8aa3b, v40
	v_mul_f32_e32 v35, 0xbfb8aa3b, v41
	v_exp_f32_e32 v34, v34
	v_exp_f32_e32 v35, v35
	v_add_f32_e32 v34, 1.0, v34
	v_add_f32_e32 v35, 1.0, v35
	v_rcp_f32_e32 v34, v34
	v_rcp_f32_e32 v35, v35
	s_nop 0
	v_pk_mul_f32 v[34:35], v[40:41], v[34:35]
	s_nop 0
	v_pk_mul_f32 v[34:35], v[34:35], v[36:37]
	v_add_u32_e32 v36, 0xa0, v145
	v_cvt_pk_bf16_f32 v45, v34, v35
	v_mad_i64_i32 v[34:35], s[2:3], v52, s7, v[114:115]
	v_lshl_add_u64 v[34:35], v[34:35], 0, s[14:15]
	v_lshl_add_u64 v[34:35], v[34:35], 0, s[0:1]
	v_lshl_add_u64 v[34:35], v[34:35], 0, v[0:1]
	global_store_dwordx4 v[34:35], v[42:45], off
	v_mul_f32_e32 v34, 0xbfb8aa3b, v30
	v_mul_f32_e32 v35, 0xbfb8aa3b, v31
	v_exp_f32_e32 v34, v34
	v_exp_f32_e32 v35, v35
	v_add_f32_e32 v34, 1.0, v34
	v_add_f32_e32 v35, 1.0, v35
	v_rcp_f32_e32 v34, v34
	v_rcp_f32_e32 v35, v35
	s_nop 0
	v_pk_mul_f32 v[30:31], v[30:31], v[34:35]
	s_nop 0
	v_pk_mul_f32 v[26:27], v[30:31], v[26:27]
	s_nop 0
	v_cvt_pk_bf16_f32 v26, v26, v27
	v_mul_f32_e32 v27, 0xbfb8aa3b, v32
	v_exp_f32_e32 v27, v27
	s_nop 0
	v_add_f32_e32 v27, 1.0, v27
	v_rcp_f32_e32 v30, v27
	v_mul_f32_e32 v27, 0xbfb8aa3b, v33
	v_exp_f32_e32 v27, v27
	s_nop 0
	v_add_f32_e32 v27, 1.0, v27
	v_rcp_f32_e32 v31, v27
	s_nop 0
	v_pk_mul_f32 v[30:31], v[32:33], v[30:31]
	s_nop 0
	v_pk_mul_f32 v[28:29], v[30:31], v[28:29]
	s_nop 0
	v_cvt_pk_bf16_f32 v27, v28, v29
	v_mul_f32_e32 v28, 0xbfb8aa3b, v22
	v_mul_f32_e32 v29, 0xbfb8aa3b, v23
	v_exp_f32_e32 v28, v28
	v_exp_f32_e32 v29, v29
	v_add_f32_e32 v28, 1.0, v28
	v_add_f32_e32 v29, 1.0, v29
	v_rcp_f32_e32 v28, v28
	v_rcp_f32_e32 v29, v29
	s_nop 0
	v_pk_mul_f32 v[22:23], v[22:23], v[28:29]
	s_nop 0
	v_pk_mul_f32 v[18:19], v[22:23], v[18:19]
	s_nop 0
	v_cvt_pk_bf16_f32 v28, v18, v19
	v_mul_f32_e32 v18, 0xbfb8aa3b, v24
	v_mul_f32_e32 v19, 0xbfb8aa3b, v25
	v_exp_f32_e32 v18, v18
	v_exp_f32_e32 v19, v19
	v_add_f32_e32 v18, 1.0, v18
	v_add_f32_e32 v19, 1.0, v19
	v_rcp_f32_e32 v18, v18
	v_rcp_f32_e32 v19, v19
	s_nop 0
	v_pk_mul_f32 v[18:19], v[24:25], v[18:19]
	s_nop 0
	v_pk_mul_f32 v[18:19], v[18:19], v[20:21]
	v_add_u32_e32 v20, 0xb0, v145
	v_cvt_pk_bf16_f32 v29, v18, v19
	v_mad_i64_i32 v[18:19], s[2:3], v36, s7, v[114:115]
	v_lshl_add_u64 v[18:19], v[18:19], 0, s[14:15]
	v_lshl_add_u64 v[18:19], v[18:19], 0, s[0:1]
	v_lshl_add_u64 v[18:19], v[18:19], 0, v[0:1]
	global_store_dwordx4 v[18:19], v[26:29], off
	v_mul_f32_e32 v18, 0xbfb8aa3b, v14
	v_mul_f32_e32 v19, 0xbfb8aa3b, v15
	v_exp_f32_e32 v18, v18
	v_exp_f32_e32 v19, v19
	v_add_f32_e32 v18, 1.0, v18
	v_add_f32_e32 v19, 1.0, v19
	v_rcp_f32_e32 v18, v18
	v_rcp_f32_e32 v19, v19
	s_nop 0
	v_pk_mul_f32 v[14:15], v[14:15], v[18:19]
	s_nop 0
	v_pk_mul_f32 v[10:11], v[14:15], v[10:11]
	s_nop 0
	v_cvt_pk_bf16_f32 v10, v10, v11
	v_mul_f32_e32 v11, 0xbfb8aa3b, v16
	v_exp_f32_e32 v11, v11
	s_nop 0
	v_add_f32_e32 v11, 1.0, v11
	v_rcp_f32_e32 v14, v11
	v_mul_f32_e32 v11, 0xbfb8aa3b, v17
	v_exp_f32_e32 v11, v11
	s_nop 0
	v_add_f32_e32 v11, 1.0, v11
	v_rcp_f32_e32 v15, v11
	s_nop 0
	v_pk_mul_f32 v[14:15], v[16:17], v[14:15]
	s_nop 0
	v_pk_mul_f32 v[12:13], v[14:15], v[12:13]
	s_nop 0
	v_cvt_pk_bf16_f32 v11, v12, v13
	v_mul_f32_e32 v12, 0xbfb8aa3b, v6
	v_mul_f32_e32 v13, 0xbfb8aa3b, v7
	v_exp_f32_e32 v12, v12
	v_exp_f32_e32 v13, v13
	v_add_f32_e32 v12, 1.0, v12
	v_add_f32_e32 v13, 1.0, v13
	v_rcp_f32_e32 v12, v12
	v_rcp_f32_e32 v13, v13
	s_nop 0
	v_pk_mul_f32 v[6:7], v[6:7], v[12:13]
	s_nop 0
	v_pk_mul_f32 v[2:3], v[6:7], v[2:3]
	s_nop 0
	v_cvt_pk_bf16_f32 v12, v2, v3
	v_mul_f32_e32 v2, 0xbfb8aa3b, v8
	v_mul_f32_e32 v3, 0xbfb8aa3b, v9
	v_exp_f32_e32 v2, v2
	v_exp_f32_e32 v3, v3
	v_add_f32_e32 v2, 1.0, v2
	v_add_f32_e32 v3, 1.0, v3
	v_rcp_f32_e32 v2, v2
	v_rcp_f32_e32 v3, v3
	s_nop 0
	v_pk_mul_f32 v[2:3], v[8:9], v[2:3]
	s_nop 0
	v_pk_mul_f32 v[2:3], v[2:3], v[4:5]
	s_nop 0
	v_cvt_pk_bf16_f32 v13, v2, v3
	v_mad_i64_i32 v[2:3], s[2:3], v20, s7, v[114:115]
	v_lshl_add_u64 v[2:3], v[2:3], 0, s[14:15]
	v_lshl_add_u64 v[2:3], v[2:3], 0, s[0:1]
	v_lshl_add_u64 v[2:3], v[2:3], 0, v[0:1]
	s_mov_b32 s1, s6
	s_mov_b64 s[2:3], s[12:13]
	s_mov_b64 s[14:15], s[10:11]
	global_store_dwordx4 v[2:3], v[10:13], off
	s_cbranch_vccz .LBB0_110
	s_waitcnt vmcnt(0)
	s_cmpk_gt_u32 s5, 0xff
	v_readlane_b32 s50, v255, 53
	v_readlane_b32 s51, v255, 54
	s_cbranch_scc1 .LBB0_117
	s_barrier

.LBB0_136:
	s_add_u32 s2, s18, 0xfffc0080
	s_addc_u32 s3, s19, -1
	s_add_i32 s34, 0, 0x10000
	v_add_u32_e32 v0, s34, v165
	ds_read_b128 v[90:93], v0
	ds_read_b128 v[94:97], v0 offset:1024
	ds_read_b128 v[98:101], v0 offset:2048
	ds_read_b128 v[102:105], v0 offset:3072
	s_cmp_eq_u32 s58, 12
	s_cselect_b32 s3, s13, s3
	s_cselect_b32 s2, s55, s2
	s_cselect_b32 s39, s11, s50
	s_cselect_b32 s38, s56, s57
	v_lshl_add_u64 v[162:163], s[18:19], 0, v[150:151]
	s_add_i32 m0, s45, 0xc000
	ds_read_b128 v[154:157], v167
	ds_read_b128 v[158:161], v167 offset:1024
	ds_read_b128 v[168:171], v167 offset:2048
	ds_read_b128 v[172:175], v167 offset:3072
	ds_read_b128 v[176:179], v167 offset:4096
	ds_read_b128 v[180:183], v167 offset:5120
	ds_read_b128 v[184:187], v167 offset:6144
	ds_read_b128 v[188:191], v167 offset:7168
	global_load_lds_dwordx4 v[162:163], off
	v_lshl_add_u64 v[162:163], s[18:19], 0, v[152:153]
	s_add_i32 m0, s45, 0xe000
	s_nop 0
	global_load_lds_dwordx4 v[162:163], off
	s_waitcnt vmcnt(10)
	s_waitcnt lgkmcnt(8)
	s_barrier
	s_waitcnt lgkmcnt(0)
	s_setprio 1
	s_waitcnt lgkmcnt(0)
	v_mfma_f32_16x16x32_bf16 v[142:145], v[90:93], v[154:157], v[142:145]
	v_mfma_f32_16x16x32_bf16 v[138:141], v[98:101], v[154:157], v[138:141]
	v_mfma_f32_16x16x32_bf16 v[126:129], v[90:93], v[168:171], v[126:129]
	v_mfma_f32_16x16x32_bf16 v[122:125], v[98:101], v[168:171], v[122:125]
	v_mfma_f32_16x16x32_bf16 v[110:113], v[90:93], v[176:179], v[110:113]
	v_mfma_f32_16x16x32_bf16 v[106:109], v[98:101], v[176:179], v[106:109]
	v_mfma_f32_16x16x32_bf16 v[78:81], v[90:93], v[184:187], v[78:81]
	v_mfma_f32_16x16x32_bf16 v[74:77], v[98:101], v[184:187], v[74:77]
	v_mfma_f32_16x16x32_bf16 v[142:145], v[94:97], v[158:161], v[142:145]
	v_mfma_f32_16x16x32_bf16 v[138:141], v[102:105], v[158:161], v[138:141]
	v_mfma_f32_16x16x32_bf16 v[126:129], v[94:97], v[172:175], v[126:129]
	v_mfma_f32_16x16x32_bf16 v[122:125], v[102:105], v[172:175], v[122:125]
	v_mfma_f32_16x16x32_bf16 v[110:113], v[94:97], v[180:183], v[110:113]
	v_mfma_f32_16x16x32_bf16 v[106:109], v[102:105], v[180:183], v[106:109]
	v_mfma_f32_16x16x32_bf16 v[78:81], v[94:97], v[188:191], v[78:81]
	v_mfma_f32_16x16x32_bf16 v[74:77], v[102:105], v[188:191], v[74:77]
	s_setprio 0
	s_barrier
	s_add_i32 s40, 0, 0x14000
	s_add_i32 s34, s34, s44
	v_add_u32_e32 v0, s40, v165
	v_lshl_add_u64 v[162:163], s[38:39], 0, v[148:149]
	s_mov_b32 m0, s34
	ds_read_b128 v[196:199], v0
	ds_read_b128 v[200:203], v0 offset:1024
	ds_read_b128 v[206:209], v0 offset:2048
	ds_read_b128 v[210:213], v0 offset:3072
	global_load_lds_dwordx4 v[162:163], off
	v_lshl_add_u64 v[192:193], s[38:39], 0, v[146:147]
	s_add_i32 m0, s34, 0x2000
	s_nop 0
	global_load_lds_dwordx4 v[192:193], off
	s_mov_b32 m0, s45
	v_lshl_add_u64 v[214:215], s[2:3], 0, v[148:149]
	global_load_lds_dwordx4 v[214:215], off
	v_lshl_add_u64 v[216:217], s[2:3], 0, v[146:147]
	s_mov_b32 m0, s51
	s_nop 0
	global_load_lds_dwordx4 v[216:217], off
	s_waitcnt vmcnt(12)
	s_barrier
	s_waitcnt lgkmcnt(0)
	s_setprio 1
	s_waitcnt lgkmcnt(0)
	v_mfma_f32_16x16x32_bf16 v[134:137], v[196:199], v[154:157], v[134:137]
	v_mfma_f32_16x16x32_bf16 v[130:133], v[206:209], v[154:157], v[130:133]
	v_mfma_f32_16x16x32_bf16 v[118:121], v[196:199], v[168:171], v[118:121]
	v_mfma_f32_16x16x32_bf16 v[114:117], v[206:209], v[168:171], v[114:117]
	v_mfma_f32_16x16x32_bf16 v[86:89], v[196:199], v[176:179], v[86:89]
	v_mfma_f32_16x16x32_bf16 v[82:85], v[206:209], v[176:179], v[82:85]
	v_mfma_f32_16x16x32_bf16 v[70:73], v[196:199], v[184:187], v[70:73]
	v_mfma_f32_16x16x32_bf16 v[66:69], v[206:209], v[184:187], v[66:69]
	v_mfma_f32_16x16x32_bf16 v[134:137], v[200:203], v[158:161], v[134:137]
	v_mfma_f32_16x16x32_bf16 v[130:133], v[210:213], v[158:161], v[130:133]
	v_mfma_f32_16x16x32_bf16 v[118:121], v[200:203], v[172:175], v[118:121]
	v_mfma_f32_16x16x32_bf16 v[114:117], v[210:213], v[172:175], v[114:117]
	v_mfma_f32_16x16x32_bf16 v[86:89], v[200:203], v[180:183], v[86:89]
	v_mfma_f32_16x16x32_bf16 v[82:85], v[210:213], v[180:183], v[82:85]
	v_mfma_f32_16x16x32_bf16 v[70:73], v[200:203], v[188:191], v[70:73]
	v_mfma_f32_16x16x32_bf16 v[66:69], v[210:213], v[188:191], v[66:69]
	s_setprio 0
	s_barrier
	ds_read_b128 v[154:157], v167 offset:16384
	ds_read_b128 v[158:161], v167 offset:17408
	ds_read_b128 v[168:171], v167 offset:18432
	ds_read_b128 v[172:175], v167 offset:19456
	ds_read_b128 v[176:179], v167 offset:20480
	ds_read_b128 v[180:183], v167 offset:21504
	ds_read_b128 v[184:187], v167 offset:22528
	ds_read_b128 v[188:191], v167 offset:23552
	s_barrier
	s_waitcnt lgkmcnt(0)
	s_setprio 1
	s_waitcnt lgkmcnt(0)
	v_mfma_f32_16x16x32_bf16 v[62:65], v[90:93], v[154:157], v[62:65]
	v_mfma_f32_16x16x32_bf16 v[58:61], v[98:101], v[154:157], v[58:61]
	v_mfma_f32_16x16x32_bf16 v[54:57], v[90:93], v[168:171], v[54:57]
	v_mfma_f32_16x16x32_bf16 v[50:53], v[98:101], v[168:171], v[50:53]
	v_mfma_f32_16x16x32_bf16 v[30:33], v[90:93], v[176:179], v[30:33]
	v_mfma_f32_16x16x32_bf16 v[26:29], v[98:101], v[176:179], v[26:29]
	v_mfma_f32_16x16x32_bf16 v[22:25], v[90:93], v[184:187], v[22:25]
	v_mfma_f32_16x16x32_bf16 v[18:21], v[98:101], v[184:187], v[18:21]
	v_mfma_f32_16x16x32_bf16 v[62:65], v[94:97], v[158:161], v[62:65]
	v_mfma_f32_16x16x32_bf16 v[58:61], v[102:105], v[158:161], v[58:61]
	v_mfma_f32_16x16x32_bf16 v[54:57], v[94:97], v[172:175], v[54:57]
	v_mfma_f32_16x16x32_bf16 v[50:53], v[102:105], v[172:175], v[50:53]
	v_mfma_f32_16x16x32_bf16 v[30:33], v[94:97], v[180:183], v[30:33]
	v_mfma_f32_16x16x32_bf16 v[26:29], v[102:105], v[180:183], v[26:29]
	v_mfma_f32_16x16x32_bf16 v[22:25], v[94:97], v[188:191], v[22:25]
	v_mfma_f32_16x16x32_bf16 v[18:21], v[102:105], v[188:191], v[18:21]
	s_setprio 0
	s_barrier
	s_add_u32 s34, s38, 0x40000
	s_addc_u32 s35, s39, 0
	s_add_i32 s40, s40, s44
	v_lshl_add_u64 v[90:91], s[34:35], 0, v[148:149]
	s_mov_b32 m0, s40
	s_nop 0
	global_load_lds_dwordx4 v[90:91], off
	v_lshl_add_u64 v[90:91], s[34:35], 0, v[146:147]
	s_add_i32 m0, s40, 0x2000
	s_nop 0
	global_load_lds_dwordx4 v[90:91], off
	s_waitcnt vmcnt(10)
	s_barrier
	s_setprio 1
	v_mfma_f32_16x16x32_bf16 v[46:49], v[196:199], v[154:157], v[46:49]
	v_mfma_f32_16x16x32_bf16 v[42:45], v[206:209], v[154:157], v[42:45]
	v_mfma_f32_16x16x32_bf16 v[38:41], v[196:199], v[168:171], v[38:41]
	v_mfma_f32_16x16x32_bf16 v[34:37], v[206:209], v[168:171], v[34:37]
	v_mfma_f32_16x16x32_bf16 v[14:17], v[196:199], v[176:179], v[14:17]
	v_mfma_f32_16x16x32_bf16 v[10:13], v[206:209], v[176:179], v[10:13]
	v_mfma_f32_16x16x32_bf16 v[6:9], v[196:199], v[184:187], v[6:9]
	v_mfma_f32_16x16x32_bf16 v[2:5], v[206:209], v[184:187], v[2:5]
	v_mfma_f32_16x16x32_bf16 v[46:49], v[200:203], v[158:161], v[46:49]
	v_mfma_f32_16x16x32_bf16 v[42:45], v[210:213], v[158:161], v[42:45]
	v_mfma_f32_16x16x32_bf16 v[38:41], v[200:203], v[172:175], v[38:41]
	v_mfma_f32_16x16x32_bf16 v[34:37], v[210:213], v[172:175], v[34:37]
	v_mfma_f32_16x16x32_bf16 v[14:17], v[200:203], v[180:183], v[14:17]
	v_mfma_f32_16x16x32_bf16 v[10:13], v[210:213], v[180:183], v[10:13]
	v_mfma_f32_16x16x32_bf16 v[6:9], v[200:203], v[188:191], v[6:9]
	v_mfma_f32_16x16x32_bf16 v[2:5], v[210:213], v[188:191], v[2:5]
	s_setprio 0
	s_add_i32 s34, 0, 0x18000
	v_add_u32_e32 v0, s34, v165
	s_barrier
	ds_read_b128 v[90:93], v0
	ds_read_b128 v[94:97], v0 offset:1024
	ds_read_b128 v[98:101], v0 offset:2048
	ds_read_b128 v[102:105], v0 offset:3072
	s_add_u32 s2, s2, 0x40000
	s_addc_u32 s3, s3, 0
	s_mov_b32 m0, s52
	v_lshl_add_u64 v[196:197], s[2:3], 0, v[148:149]
	ds_read_b128 v[154:157], v167 offset:32768
	ds_read_b128 v[158:161], v167 offset:33792
	ds_read_b128 v[168:171], v167 offset:34816
	ds_read_b128 v[172:175], v167 offset:35840
	ds_read_b128 v[176:179], v167 offset:36864
	ds_read_b128 v[180:183], v167 offset:37888
	ds_read_b128 v[184:187], v167 offset:38912
	ds_read_b128 v[188:191], v167 offset:39936
	global_load_lds_dwordx4 v[196:197], off
	v_lshl_add_u64 v[196:197], s[2:3], 0, v[146:147]
	s_mov_b32 m0, s53
	s_nop 0
	global_load_lds_dwordx4 v[196:197], off
	s_waitcnt vmcnt(10)
	s_waitcnt lgkmcnt(8)
	s_barrier
	s_waitcnt lgkmcnt(0)
	s_setprio 1
	s_waitcnt lgkmcnt(0)
	v_mfma_f32_16x16x32_bf16 v[142:145], v[90:93], v[154:157], v[142:145]
	v_mfma_f32_16x16x32_bf16 v[138:141], v[98:101], v[154:157], v[138:141]
	v_mfma_f32_16x16x32_bf16 v[126:129], v[90:93], v[168:171], v[126:129]
	v_mfma_f32_16x16x32_bf16 v[122:125], v[98:101], v[168:171], v[122:125]
	v_mfma_f32_16x16x32_bf16 v[110:113], v[90:93], v[176:179], v[110:113]
	v_mfma_f32_16x16x32_bf16 v[106:109], v[98:101], v[176:179], v[106:109]
	v_mfma_f32_16x16x32_bf16 v[78:81], v[90:93], v[184:187], v[78:81]
	v_mfma_f32_16x16x32_bf16 v[74:77], v[98:101], v[184:187], v[74:77]
	v_mfma_f32_16x16x32_bf16 v[142:145], v[94:97], v[158:161], v[142:145]
	v_mfma_f32_16x16x32_bf16 v[138:141], v[102:105], v[158:161], v[138:141]
	v_mfma_f32_16x16x32_bf16 v[126:129], v[94:97], v[172:175], v[126:129]
	v_mfma_f32_16x16x32_bf16 v[122:125], v[102:105], v[172:175], v[122:125]
	v_mfma_f32_16x16x32_bf16 v[110:113], v[94:97], v[180:183], v[110:113]
	v_mfma_f32_16x16x32_bf16 v[106:109], v[102:105], v[180:183], v[106:109]
	v_mfma_f32_16x16x32_bf16 v[78:81], v[94:97], v[188:191], v[78:81]
	v_mfma_f32_16x16x32_bf16 v[74:77], v[102:105], v[188:191], v[74:77]
	s_setprio 0
	s_barrier
	s_add_i32 s35, 0, 0x1c000
	s_add_i32 s2, s34, s44
	v_add_u32_e32 v0, s35, v165
	v_lshl_add_u64 v[162:163], v[162:163], 0, s[74:75]
	s_mov_b32 m0, s2
	ds_read_b128 v[196:199], v0
	ds_read_b128 v[200:203], v0 offset:1024
	ds_read_b128 v[206:209], v0 offset:2048
	ds_read_b128 v[210:213], v0 offset:3072
	global_load_lds_dwordx4 v[162:163], off
	v_lshl_add_u64 v[162:163], v[192:193], 0, s[74:75]
	s_add_i32 m0, s2, 0x2000
	s_nop 0
	global_load_lds_dwordx4 v[162:163], off
	s_mov_b32 m0, s59
	v_lshl_add_u64 v[162:163], v[214:215], 0, s[74:75]
	global_load_lds_dwordx4 v[162:163], off
	v_lshl_add_u64 v[162:163], v[216:217], 0, s[74:75]
	s_mov_b32 m0, s67
	s_nop 0
	global_load_lds_dwordx4 v[162:163], off
	s_waitcnt vmcnt(12)
	s_barrier
	s_waitcnt lgkmcnt(0)
	s_setprio 1
	s_waitcnt lgkmcnt(0)
	v_mfma_f32_16x16x32_bf16 v[134:137], v[196:199], v[154:157], v[134:137]
	v_mfma_f32_16x16x32_bf16 v[130:133], v[206:209], v[154:157], v[130:133]
	v_mfma_f32_16x16x32_bf16 v[118:121], v[196:199], v[168:171], v[118:121]
	v_mfma_f32_16x16x32_bf16 v[114:117], v[206:209], v[168:171], v[114:117]
	v_mfma_f32_16x16x32_bf16 v[86:89], v[196:199], v[176:179], v[86:89]
	v_mfma_f32_16x16x32_bf16 v[82:85], v[206:209], v[176:179], v[82:85]
	v_mfma_f32_16x16x32_bf16 v[70:73], v[196:199], v[184:187], v[70:73]
	v_mfma_f32_16x16x32_bf16 v[66:69], v[206:209], v[184:187], v[66:69]
	v_mfma_f32_16x16x32_bf16 v[134:137], v[200:203], v[158:161], v[134:137]
	v_mfma_f32_16x16x32_bf16 v[130:133], v[210:213], v[158:161], v[130:133]
	v_mfma_f32_16x16x32_bf16 v[118:121], v[200:203], v[172:175], v[118:121]
	v_mfma_f32_16x16x32_bf16 v[114:117], v[210:213], v[172:175], v[114:117]
	v_mfma_f32_16x16x32_bf16 v[86:89], v[200:203], v[180:183], v[86:89]
	v_mfma_f32_16x16x32_bf16 v[82:85], v[210:213], v[180:183], v[82:85]
	v_mfma_f32_16x16x32_bf16 v[70:73], v[200:203], v[188:191], v[70:73]
	v_mfma_f32_16x16x32_bf16 v[66:69], v[210:213], v[188:191], v[66:69]
	s_setprio 0
	s_barrier
	ds_read_b128 v[154:157], v167 offset:49152
	ds_read_b128 v[158:161], v167 offset:50176
	ds_read_b128 v[168:171], v167 offset:51200
	ds_read_b128 v[172:175], v167 offset:52224
	ds_read_b128 v[176:179], v167 offset:53248
	ds_read_b128 v[180:183], v167 offset:54272
	ds_read_b128 v[184:187], v167 offset:55296
	ds_read_b128 v[188:191], v167 offset:56320
	s_barrier
	s_waitcnt lgkmcnt(0)
	s_setprio 1
	s_waitcnt lgkmcnt(0)
	v_mfma_f32_16x16x32_bf16 v[62:65], v[90:93], v[154:157], v[62:65]
	v_mfma_f32_16x16x32_bf16 v[58:61], v[98:101], v[154:157], v[58:61]
	v_mfma_f32_16x16x32_bf16 v[54:57], v[90:93], v[168:171], v[54:57]
	v_mfma_f32_16x16x32_bf16 v[50:53], v[98:101], v[168:171], v[50:53]
	v_mfma_f32_16x16x32_bf16 v[30:33], v[90:93], v[176:179], v[30:33]
	v_mfma_f32_16x16x32_bf16 v[26:29], v[98:101], v[176:179], v[26:29]
	v_mfma_f32_16x16x32_bf16 v[22:25], v[90:93], v[184:187], v[22:25]
	v_mfma_f32_16x16x32_bf16 v[18:21], v[98:101], v[184:187], v[18:21]
	v_mfma_f32_16x16x32_bf16 v[62:65], v[94:97], v[158:161], v[62:65]
	v_mfma_f32_16x16x32_bf16 v[58:61], v[102:105], v[158:161], v[58:61]
	v_mfma_f32_16x16x32_bf16 v[54:57], v[94:97], v[172:175], v[54:57]
	v_mfma_f32_16x16x32_bf16 v[50:53], v[102:105], v[172:175], v[50:53]
	v_mfma_f32_16x16x32_bf16 v[30:33], v[94:97], v[180:183], v[30:33]
	v_mfma_f32_16x16x32_bf16 v[26:29], v[102:105], v[180:183], v[26:29]
	v_mfma_f32_16x16x32_bf16 v[22:25], v[94:97], v[188:191], v[22:25]
	v_mfma_f32_16x16x32_bf16 v[18:21], v[102:105], v[188:191], v[18:21]
	s_setprio 0
	s_barrier
	s_add_u32 s2, s38, 0x40080
	s_addc_u32 s3, s39, 0
	s_add_i32 s34, s35, s44
	v_lshl_add_u64 v[90:91], s[2:3], 0, v[148:149]
	s_mov_b32 m0, s34
	s_nop 0
	global_load_lds_dwordx4 v[90:91], off
	v_lshl_add_u64 v[90:91], s[2:3], 0, v[146:147]
	s_add_i32 m0, s34, 0x2000
	s_nop 0
	global_load_lds_dwordx4 v[90:91], off
	s_waitcnt vmcnt(10)
	s_barrier
	s_setprio 1
	v_mfma_f32_16x16x32_bf16 v[46:49], v[196:199], v[154:157], v[46:49]
	v_mfma_f32_16x16x32_bf16 v[42:45], v[206:209], v[154:157], v[42:45]
	v_mfma_f32_16x16x32_bf16 v[38:41], v[196:199], v[168:171], v[38:41]
	v_mfma_f32_16x16x32_bf16 v[34:37], v[206:209], v[168:171], v[34:37]
	v_mfma_f32_16x16x32_bf16 v[14:17], v[196:199], v[176:179], v[14:17]
	v_mfma_f32_16x16x32_bf16 v[10:13], v[206:209], v[176:179], v[10:13]
	v_mfma_f32_16x16x32_bf16 v[6:9], v[196:199], v[184:187], v[6:9]
	v_mfma_f32_16x16x32_bf16 v[2:5], v[206:209], v[184:187], v[2:5]
	v_mfma_f32_16x16x32_bf16 v[46:49], v[200:203], v[158:161], v[46:49]
	v_mfma_f32_16x16x32_bf16 v[42:45], v[210:213], v[158:161], v[42:45]
	v_mfma_f32_16x16x32_bf16 v[38:41], v[200:203], v[172:175], v[38:41]
	v_mfma_f32_16x16x32_bf16 v[34:37], v[210:213], v[172:175], v[34:37]
	v_mfma_f32_16x16x32_bf16 v[14:17], v[200:203], v[180:183], v[14:17]
	v_mfma_f32_16x16x32_bf16 v[10:13], v[210:213], v[180:183], v[10:13]
	v_mfma_f32_16x16x32_bf16 v[6:9], v[200:203], v[188:191], v[6:9]
	v_mfma_f32_16x16x32_bf16 v[2:5], v[210:213], v[188:191], v[2:5]
	s_setprio 0
	s_add_i32 s58, s58, 2
	s_add_u32 s18, s18, 0x100
	s_addc_u32 s19, s19, 0
	s_add_u32 s57, s57, 0x100
	s_addc_u32 s50, s50, 0
	s_cmp_gt_u32 s58, 13
	s_barrier
	s_cbranch_scc0 .LBB0_136
	v_lshl_add_u32 v156, s54, 8, v164
	v_add_u32_e32 v158, 0xffffe000, v156
	v_lshrrev_b32_e32 v0, 11, v158
	s_movk_i32 s2, 0x1800
	v_mad_u32_u24 v0, v0, s2, s2
	s_movk_i32 s2, 0x1fff
	v_cmp_lt_i32_e32 vcc, s2, v156
	v_lshl_or_b32 v154, s49, 8, v166
	v_ashrrev_i32_e32 v155, 31, v154
	v_cndmask_b32_e32 v0, 0, v0, vcc
	v_lshl_add_u64 v[90:91], v[0:1], 2, s[0:1]
	v_lshl_add_u64 v[90:91], v[154:155], 2, v[90:91]
	global_load_dwordx4 v[102:105], v[90:91], off
	global_load_dwordx4 v[98:101], v[90:91], off offset:64
	global_load_dwordx4 v[94:97], v[90:91], off offset:512
	s_nop 0
	global_load_dwordx4 v[90:93], v[90:91], off offset:576
	s_and_saveexec_b64 s[2:3], vcc
	s_xor_b64 s[2:3], exec, s[2:3]
	v_mov_b32_e32 v159, v1
	v_lshlrev_b64 v[158:159], 12, v[158:159]
	v_mov_b32_e32 v157, v1
	v_lshl_add_u64 v[162:163], s[8:9], 0, v[158:159]
	v_lshlrev_b64 v[160:161], 12, v[156:157]
	s_or_saveexec_b64 s[2:3], s[2:3]
	v_ashrrev_i32_e32 v157, 31, v156
	v_readlane_b32 s57, v255, 48
	s_mov_b32 s35, 0x3fb8aa3b
	s_mov_b32 s34, 0xc2ce8ed0
	s_xor_b64 exec, exec, s[2:3]
	s_cbranch_execz .LBB0_132
	v_lshlrev_b64 v[160:161], 12, v[156:157]
	v_lshl_add_u64 v[162:163], s[6:7], 0, v[160:161]
	s_branch .LBB0_132

.LBB0_402:
	s_add_u32 s2, s12, 0xfffe0080
	s_addc_u32 s3, s13, -1
	s_add_i32 s34, 0, 0x10000
	v_add_u32_e32 v134, s34, v185
	ds_read_b128 v[106:109], v134
	ds_read_b128 v[110:113], v134 offset:1024
	ds_read_b128 v[126:129], v134 offset:2048
	ds_read_b128 v[134:137], v134 offset:3072
	s_cmp_eq_u32 s54, 4
	s_cselect_b32 s3, s7, s3
	s_cselect_b32 s2, s51, s2
	s_cselect_b32 s15, s1, s50
	s_cselect_b32 s14, s52, s53
	v_lshl_add_u64 v[192:193], s[12:13], 0, v[168:169]
	s_add_i32 m0, s18, 0xc000
	ds_read_b128 v[138:141], v187
	ds_read_b128 v[146:149], v187 offset:1024
	ds_read_b128 v[154:157], v187 offset:2048
	ds_read_b128 v[158:161], v187 offset:3072
	ds_read_b128 v[172:175], v187 offset:4096
	ds_read_b128 v[176:179], v187 offset:5120
	ds_read_b128 v[180:183], v187 offset:6144
	ds_read_b128 v[188:191], v187 offset:7168
	global_load_lds_dwordx4 v[192:193], off
	v_lshl_add_u64 v[192:193], s[12:13], 0, v[170:171]
	s_add_i32 m0, s18, 0xe000
	s_nop 0
	global_load_lds_dwordx4 v[192:193], off
	s_waitcnt vmcnt(10)
	s_waitcnt lgkmcnt(8)
	s_barrier
	s_waitcnt lgkmcnt(0)
	s_setprio 1
	s_waitcnt lgkmcnt(0)
	v_mfma_f32_16x16x32_bf16 v[150:153], v[106:109], v[138:141], v[150:153]
	v_mfma_f32_16x16x32_bf16 v[142:145], v[126:129], v[138:141], v[142:145]
	v_mfma_f32_16x16x32_bf16 v[118:121], v[106:109], v[154:157], v[118:121]
	v_mfma_f32_16x16x32_bf16 v[114:117], v[126:129], v[154:157], v[114:117]
	v_mfma_f32_16x16x32_bf16 v[94:97], v[106:109], v[172:175], v[94:97]
	v_mfma_f32_16x16x32_bf16 v[90:93], v[126:129], v[172:175], v[90:93]
	v_mfma_f32_16x16x32_bf16 v[78:81], v[106:109], v[180:183], v[78:81]
	v_mfma_f32_16x16x32_bf16 v[74:77], v[126:129], v[180:183], v[74:77]
	v_mfma_f32_16x16x32_bf16 v[150:153], v[110:113], v[146:149], v[150:153]
	v_mfma_f32_16x16x32_bf16 v[142:145], v[134:137], v[146:149], v[142:145]
	v_mfma_f32_16x16x32_bf16 v[118:121], v[110:113], v[158:161], v[118:121]
	v_mfma_f32_16x16x32_bf16 v[114:117], v[134:137], v[158:161], v[114:117]
	v_mfma_f32_16x16x32_bf16 v[94:97], v[110:113], v[176:179], v[94:97]
	v_mfma_f32_16x16x32_bf16 v[90:93], v[134:137], v[176:179], v[90:93]
	v_mfma_f32_16x16x32_bf16 v[78:81], v[110:113], v[188:191], v[78:81]
	v_mfma_f32_16x16x32_bf16 v[74:77], v[134:137], v[188:191], v[74:77]
	s_setprio 0
	s_barrier
	s_add_i32 s40, 0, 0x14000
	v_add_u32_e32 v192, s40, v185
	s_add_i32 s34, s34, s17
	ds_read_b128 v[196:199], v192
	ds_read_b128 v[200:203], v192 offset:1024
	ds_read_b128 v[206:209], v192 offset:2048
	ds_read_b128 v[210:213], v192 offset:3072
	v_lshl_add_u64 v[192:193], s[14:15], 0, v[0:1]
	s_mov_b32 m0, s34
	v_lshl_add_u64 v[214:215], s[14:15], 0, v[162:163]
	global_load_lds_dwordx4 v[192:193], off
	s_add_i32 m0, s34, 0x2000
	s_nop 0
	global_load_lds_dwordx4 v[214:215], off
	s_mov_b32 m0, s18
	v_lshl_add_u64 v[216:217], s[2:3], 0, v[166:167]
	global_load_lds_dwordx4 v[216:217], off
	v_lshl_add_u64 v[218:219], s[2:3], 0, v[164:165]
	s_mov_b32 m0, s19
	s_nop 0
	global_load_lds_dwordx4 v[218:219], off
	s_waitcnt vmcnt(12)
	s_barrier
	s_waitcnt lgkmcnt(0)
	s_setprio 1
	s_waitcnt lgkmcnt(0)
	v_mfma_f32_16x16x32_bf16 v[130:133], v[196:199], v[138:141], v[130:133]
	v_mfma_f32_16x16x32_bf16 v[122:125], v[206:209], v[138:141], v[122:125]
	v_mfma_f32_16x16x32_bf16 v[102:105], v[196:199], v[154:157], v[102:105]
	v_mfma_f32_16x16x32_bf16 v[98:101], v[206:209], v[154:157], v[98:101]
	v_mfma_f32_16x16x32_bf16 v[86:89], v[196:199], v[172:175], v[86:89]
	v_mfma_f32_16x16x32_bf16 v[82:85], v[206:209], v[172:175], v[82:85]
	v_mfma_f32_16x16x32_bf16 v[70:73], v[196:199], v[180:183], v[70:73]
	v_mfma_f32_16x16x32_bf16 v[66:69], v[206:209], v[180:183], v[66:69]
	v_mfma_f32_16x16x32_bf16 v[130:133], v[200:203], v[146:149], v[130:133]
	v_mfma_f32_16x16x32_bf16 v[122:125], v[210:213], v[146:149], v[122:125]
	v_mfma_f32_16x16x32_bf16 v[102:105], v[200:203], v[158:161], v[102:105]
	v_mfma_f32_16x16x32_bf16 v[98:101], v[210:213], v[158:161], v[98:101]
	v_mfma_f32_16x16x32_bf16 v[86:89], v[200:203], v[176:179], v[86:89]
	v_mfma_f32_16x16x32_bf16 v[82:85], v[210:213], v[176:179], v[82:85]
	v_mfma_f32_16x16x32_bf16 v[70:73], v[200:203], v[188:191], v[70:73]
	v_mfma_f32_16x16x32_bf16 v[66:69], v[210:213], v[188:191], v[66:69]
	s_setprio 0
	s_barrier
	ds_read_b128 v[138:141], v187 offset:16384
	ds_read_b128 v[146:149], v187 offset:17408
	ds_read_b128 v[154:157], v187 offset:18432
	ds_read_b128 v[158:161], v187 offset:19456
	ds_read_b128 v[172:175], v187 offset:20480
	ds_read_b128 v[176:179], v187 offset:21504
	ds_read_b128 v[180:183], v187 offset:22528
	ds_read_b128 v[188:191], v187 offset:23552
	s_barrier
	s_waitcnt lgkmcnt(0)
	s_setprio 1
	s_waitcnt lgkmcnt(0)
	v_mfma_f32_16x16x32_bf16 v[62:65], v[106:109], v[138:141], v[62:65]
	v_mfma_f32_16x16x32_bf16 v[58:61], v[126:129], v[138:141], v[58:61]
	v_mfma_f32_16x16x32_bf16 v[46:49], v[106:109], v[154:157], v[46:49]
	v_mfma_f32_16x16x32_bf16 v[42:45], v[126:129], v[154:157], v[42:45]
	v_mfma_f32_16x16x32_bf16 v[30:33], v[106:109], v[172:175], v[30:33]
	v_mfma_f32_16x16x32_bf16 v[26:29], v[126:129], v[172:175], v[26:29]
	v_mfma_f32_16x16x32_bf16 v[14:17], v[106:109], v[180:183], v[14:17]
	v_mfma_f32_16x16x32_bf16 v[10:13], v[126:129], v[180:183], v[10:13]
	v_mfma_f32_16x16x32_bf16 v[62:65], v[110:113], v[146:149], v[62:65]
	v_mfma_f32_16x16x32_bf16 v[58:61], v[134:137], v[146:149], v[58:61]
	v_mfma_f32_16x16x32_bf16 v[46:49], v[110:113], v[158:161], v[46:49]
	v_mfma_f32_16x16x32_bf16 v[42:45], v[134:137], v[158:161], v[42:45]
	v_mfma_f32_16x16x32_bf16 v[30:33], v[110:113], v[176:179], v[30:33]
	v_mfma_f32_16x16x32_bf16 v[26:29], v[134:137], v[176:179], v[26:29]
	v_mfma_f32_16x16x32_bf16 v[14:17], v[110:113], v[188:191], v[14:17]
	v_mfma_f32_16x16x32_bf16 v[10:13], v[134:137], v[188:191], v[10:13]
	s_setprio 0
	s_barrier
	s_add_u32 s34, s14, 0x20000
	s_addc_u32 s35, s15, 0
	s_add_i32 s40, s40, s17
	v_lshl_add_u64 v[106:107], s[34:35], 0, v[0:1]
	s_mov_b32 m0, s40
	s_nop 0
	global_load_lds_dwordx4 v[106:107], off
	v_lshl_add_u64 v[106:107], s[34:35], 0, v[162:163]
	s_add_i32 m0, s40, 0x2000
	s_nop 0
	global_load_lds_dwordx4 v[106:107], off
	s_waitcnt vmcnt(10)
	s_barrier
	s_setprio 1
	v_mfma_f32_16x16x32_bf16 v[54:57], v[196:199], v[138:141], v[54:57]
	v_mfma_f32_16x16x32_bf16 v[50:53], v[206:209], v[138:141], v[50:53]
	v_mfma_f32_16x16x32_bf16 v[38:41], v[196:199], v[154:157], v[38:41]
	v_mfma_f32_16x16x32_bf16 v[34:37], v[206:209], v[154:157], v[34:37]
	v_mfma_f32_16x16x32_bf16 v[22:25], v[196:199], v[172:175], v[22:25]
	v_mfma_f32_16x16x32_bf16 v[18:21], v[206:209], v[172:175], v[18:21]
	v_mfma_f32_16x16x32_bf16 v[6:9], v[196:199], v[180:183], v[6:9]
	v_mfma_f32_16x16x32_bf16 v[2:5], v[206:209], v[180:183], v[2:5]
	v_mfma_f32_16x16x32_bf16 v[54:57], v[200:203], v[146:149], v[54:57]
	v_mfma_f32_16x16x32_bf16 v[50:53], v[210:213], v[146:149], v[50:53]
	v_mfma_f32_16x16x32_bf16 v[38:41], v[200:203], v[158:161], v[38:41]
	v_mfma_f32_16x16x32_bf16 v[34:37], v[210:213], v[158:161], v[34:37]
	v_mfma_f32_16x16x32_bf16 v[22:25], v[200:203], v[176:179], v[22:25]
	v_mfma_f32_16x16x32_bf16 v[18:21], v[210:213], v[176:179], v[18:21]
	v_mfma_f32_16x16x32_bf16 v[6:9], v[200:203], v[188:191], v[6:9]
	v_mfma_f32_16x16x32_bf16 v[2:5], v[210:213], v[188:191], v[2:5]
	s_setprio 0
	s_add_i32 s34, 0, 0x18000
	v_add_u32_e32 v134, s34, v185
	s_barrier
	ds_read_b128 v[106:109], v134
	ds_read_b128 v[110:113], v134 offset:1024
	ds_read_b128 v[126:129], v134 offset:2048
	ds_read_b128 v[134:137], v134 offset:3072
	s_add_u32 s2, s2, 0x20000
	s_addc_u32 s3, s3, 0
	s_mov_b32 m0, s38
	v_lshl_add_u64 v[196:197], s[2:3], 0, v[166:167]
	ds_read_b128 v[138:141], v187 offset:32768
	ds_read_b128 v[146:149], v187 offset:33792
	ds_read_b128 v[154:157], v187 offset:34816
	ds_read_b128 v[158:161], v187 offset:35840
	ds_read_b128 v[172:175], v187 offset:36864
	ds_read_b128 v[176:179], v187 offset:37888
	ds_read_b128 v[180:183], v187 offset:38912
	ds_read_b128 v[188:191], v187 offset:39936
	global_load_lds_dwordx4 v[196:197], off
	v_lshl_add_u64 v[196:197], s[2:3], 0, v[164:165]
	s_mov_b32 m0, s39
	s_nop 0
	global_load_lds_dwordx4 v[196:197], off
	s_waitcnt vmcnt(10)
	s_waitcnt lgkmcnt(8)
	s_barrier
	s_waitcnt lgkmcnt(0)
	s_setprio 1
	s_waitcnt lgkmcnt(0)
	v_mfma_f32_16x16x32_bf16 v[150:153], v[106:109], v[138:141], v[150:153]
	v_mfma_f32_16x16x32_bf16 v[142:145], v[126:129], v[138:141], v[142:145]
	v_mfma_f32_16x16x32_bf16 v[118:121], v[106:109], v[154:157], v[118:121]
	v_mfma_f32_16x16x32_bf16 v[114:117], v[126:129], v[154:157], v[114:117]
	v_mfma_f32_16x16x32_bf16 v[94:97], v[106:109], v[172:175], v[94:97]
	v_mfma_f32_16x16x32_bf16 v[90:93], v[126:129], v[172:175], v[90:93]
	v_mfma_f32_16x16x32_bf16 v[78:81], v[106:109], v[180:183], v[78:81]
	v_mfma_f32_16x16x32_bf16 v[74:77], v[126:129], v[180:183], v[74:77]
	v_mfma_f32_16x16x32_bf16 v[150:153], v[110:113], v[146:149], v[150:153]
	v_mfma_f32_16x16x32_bf16 v[142:145], v[134:137], v[146:149], v[142:145]
	v_mfma_f32_16x16x32_bf16 v[118:121], v[110:113], v[158:161], v[118:121]
	v_mfma_f32_16x16x32_bf16 v[114:117], v[134:137], v[158:161], v[114:117]
	v_mfma_f32_16x16x32_bf16 v[94:97], v[110:113], v[176:179], v[94:97]
	v_mfma_f32_16x16x32_bf16 v[90:93], v[134:137], v[176:179], v[90:93]
	v_mfma_f32_16x16x32_bf16 v[78:81], v[110:113], v[188:191], v[78:81]
	v_mfma_f32_16x16x32_bf16 v[74:77], v[134:137], v[188:191], v[74:77]
	s_setprio 0
	s_barrier
	s_add_i32 s35, 0, 0x1c000
	s_add_i32 s2, s34, s17
	v_add_u32_e32 v195, s35, v185
	v_lshl_add_u64 v[192:193], v[192:193], 0, s[74:75]
	s_mov_b32 m0, s2
	ds_read_b128 v[196:199], v195
	ds_read_b128 v[200:203], v195 offset:1024
	ds_read_b128 v[206:209], v195 offset:2048
	ds_read_b128 v[210:213], v195 offset:3072
	global_load_lds_dwordx4 v[192:193], off
	v_lshl_add_u64 v[192:193], v[214:215], 0, s[74:75]
	s_add_i32 m0, s2, 0x2000
	s_nop 0
	global_load_lds_dwordx4 v[192:193], off
	s_mov_b32 m0, s44
	v_lshl_add_u64 v[192:193], v[216:217], 0, s[74:75]
	global_load_lds_dwordx4 v[192:193], off
	v_lshl_add_u64 v[192:193], v[218:219], 0, s[74:75]
	s_mov_b32 m0, s45
	s_nop 0
	global_load_lds_dwordx4 v[192:193], off
	s_waitcnt vmcnt(12)
	s_barrier
	s_waitcnt lgkmcnt(0)
	s_setprio 1
	s_waitcnt lgkmcnt(0)
	v_mfma_f32_16x16x32_bf16 v[130:133], v[196:199], v[138:141], v[130:133]
	v_mfma_f32_16x16x32_bf16 v[122:125], v[206:209], v[138:141], v[122:125]
	v_mfma_f32_16x16x32_bf16 v[102:105], v[196:199], v[154:157], v[102:105]
	v_mfma_f32_16x16x32_bf16 v[98:101], v[206:209], v[154:157], v[98:101]
	v_mfma_f32_16x16x32_bf16 v[86:89], v[196:199], v[172:175], v[86:89]
	v_mfma_f32_16x16x32_bf16 v[82:85], v[206:209], v[172:175], v[82:85]
	v_mfma_f32_16x16x32_bf16 v[70:73], v[196:199], v[180:183], v[70:73]
	v_mfma_f32_16x16x32_bf16 v[66:69], v[206:209], v[180:183], v[66:69]
	v_mfma_f32_16x16x32_bf16 v[130:133], v[200:203], v[146:149], v[130:133]
	v_mfma_f32_16x16x32_bf16 v[122:125], v[210:213], v[146:149], v[122:125]
	v_mfma_f32_16x16x32_bf16 v[102:105], v[200:203], v[158:161], v[102:105]
	v_mfma_f32_16x16x32_bf16 v[98:101], v[210:213], v[158:161], v[98:101]
	v_mfma_f32_16x16x32_bf16 v[86:89], v[200:203], v[176:179], v[86:89]
	v_mfma_f32_16x16x32_bf16 v[82:85], v[210:213], v[176:179], v[82:85]
	v_mfma_f32_16x16x32_bf16 v[70:73], v[200:203], v[188:191], v[70:73]
	v_mfma_f32_16x16x32_bf16 v[66:69], v[210:213], v[188:191], v[66:69]
	s_setprio 0
	s_barrier
	ds_read_b128 v[138:141], v187 offset:49152
	ds_read_b128 v[146:149], v187 offset:50176
	ds_read_b128 v[154:157], v187 offset:51200
	ds_read_b128 v[158:161], v187 offset:52224
	ds_read_b128 v[172:175], v187 offset:53248
	ds_read_b128 v[176:179], v187 offset:54272
	ds_read_b128 v[180:183], v187 offset:55296
	ds_read_b128 v[188:191], v187 offset:56320
	s_barrier
	s_waitcnt lgkmcnt(0)
	s_setprio 1
	s_waitcnt lgkmcnt(0)
	v_mfma_f32_16x16x32_bf16 v[62:65], v[106:109], v[138:141], v[62:65]
	v_mfma_f32_16x16x32_bf16 v[58:61], v[126:129], v[138:141], v[58:61]
	v_mfma_f32_16x16x32_bf16 v[46:49], v[106:109], v[154:157], v[46:49]
	v_mfma_f32_16x16x32_bf16 v[42:45], v[126:129], v[154:157], v[42:45]
	v_mfma_f32_16x16x32_bf16 v[30:33], v[106:109], v[172:175], v[30:33]
	v_mfma_f32_16x16x32_bf16 v[26:29], v[126:129], v[172:175], v[26:29]
	v_mfma_f32_16x16x32_bf16 v[14:17], v[106:109], v[180:183], v[14:17]
	v_mfma_f32_16x16x32_bf16 v[10:13], v[126:129], v[180:183], v[10:13]
	v_mfma_f32_16x16x32_bf16 v[62:65], v[110:113], v[146:149], v[62:65]
	v_mfma_f32_16x16x32_bf16 v[58:61], v[134:137], v[146:149], v[58:61]
	v_mfma_f32_16x16x32_bf16 v[46:49], v[110:113], v[158:161], v[46:49]
	v_mfma_f32_16x16x32_bf16 v[42:45], v[134:137], v[158:161], v[42:45]
	v_mfma_f32_16x16x32_bf16 v[30:33], v[110:113], v[176:179], v[30:33]
	v_mfma_f32_16x16x32_bf16 v[26:29], v[134:137], v[176:179], v[26:29]
	v_mfma_f32_16x16x32_bf16 v[14:17], v[110:113], v[188:191], v[14:17]
	v_mfma_f32_16x16x32_bf16 v[10:13], v[134:137], v[188:191], v[10:13]
	s_setprio 0
	s_barrier
	s_add_u32 s2, s14, 0x20080
	s_addc_u32 s3, s15, 0
	s_add_i32 s14, s35, s17
	v_lshl_add_u64 v[106:107], s[2:3], 0, v[0:1]
	s_mov_b32 m0, s14
	s_nop 0
	global_load_lds_dwordx4 v[106:107], off
	v_lshl_add_u64 v[106:107], s[2:3], 0, v[162:163]
	s_add_i32 m0, s14, 0x2000
	s_nop 0
	global_load_lds_dwordx4 v[106:107], off
	s_waitcnt vmcnt(10)
	s_barrier
	s_setprio 1
	v_mfma_f32_16x16x32_bf16 v[54:57], v[196:199], v[138:141], v[54:57]
	v_mfma_f32_16x16x32_bf16 v[50:53], v[206:209], v[138:141], v[50:53]
	v_mfma_f32_16x16x32_bf16 v[38:41], v[196:199], v[154:157], v[38:41]
	v_mfma_f32_16x16x32_bf16 v[34:37], v[206:209], v[154:157], v[34:37]
	v_mfma_f32_16x16x32_bf16 v[22:25], v[196:199], v[172:175], v[22:25]
	v_mfma_f32_16x16x32_bf16 v[18:21], v[206:209], v[172:175], v[18:21]
	v_mfma_f32_16x16x32_bf16 v[6:9], v[196:199], v[180:183], v[6:9]
	v_mfma_f32_16x16x32_bf16 v[2:5], v[206:209], v[180:183], v[2:5]
	v_mfma_f32_16x16x32_bf16 v[54:57], v[200:203], v[146:149], v[54:57]
	v_mfma_f32_16x16x32_bf16 v[50:53], v[210:213], v[146:149], v[50:53]
	v_mfma_f32_16x16x32_bf16 v[38:41], v[200:203], v[158:161], v[38:41]
	v_mfma_f32_16x16x32_bf16 v[34:37], v[210:213], v[158:161], v[34:37]
	v_mfma_f32_16x16x32_bf16 v[22:25], v[200:203], v[176:179], v[22:25]
	v_mfma_f32_16x16x32_bf16 v[18:21], v[210:213], v[176:179], v[18:21]
	v_mfma_f32_16x16x32_bf16 v[6:9], v[200:203], v[188:191], v[6:9]
	v_mfma_f32_16x16x32_bf16 v[2:5], v[210:213], v[188:191], v[2:5]
	s_setprio 0
	s_add_i32 s54, s54, 2
	s_add_u32 s12, s12, 0x100
	s_addc_u32 s13, s13, 0
	s_add_u32 s53, s53, 0x100
	s_addc_u32 s50, s50, 0
	s_cmp_gt_u32 s54, 5
	s_barrier
	s_cbranch_scc0 .LBB0_402
	v_lshl_or_b32 v108, s5, 8, v186
	v_lshl_add_u32 v106, s49, 8, v184
	v_ashrrev_i32_e32 v109, 31, v108
	v_readlane_b32 s2, v250, 57
	v_lshlrev_b64 v[172:173], 1, v[108:109]
	v_readlane_b32 s3, v250, 58
	v_ashrrev_i32_e32 v107, 31, v106
	v_lshlrev_b64 v[176:177], 10, v[106:107]
	v_lshl_add_u64 v[174:175], s[2:3], 0, v[172:173]
	v_lshl_add_u64 v[108:109], v[174:175], 0, v[176:177]
	global_load_dwordx4 v[158:161], v[108:109], off
	global_load_dwordx4 v[154:157], v[108:109], off offset:256
	v_or_b32_e32 v108, 16, v106
	v_ashrrev_i32_e32 v109, 31, v108
	v_lshlrev_b64 v[182:183], 10, v[108:109]
	v_lshl_add_u64 v[108:109], v[174:175], 0, v[182:183]
	global_load_dwordx4 v[146:149], v[108:109], off
	global_load_dwordx4 v[138:141], v[108:109], off offset:256
	v_mul_f32_e32 v150, 0xbfb8aa3b, v150
	v_mul_f32_e32 v151, 0xbfb8aa3b, v151
	v_exp_f32_e32 v150, v150
	v_exp_f32_e32 v151, v151
	v_mul_f32_e32 v142, 0xbfb8aa3b, v142
	v_mul_f32_e32 v143, 0xbfb8aa3b, v143
	v_add_f32_e32 v150, 1.0, v150
	v_add_f32_e32 v151, 1.0, v151
	v_rcp_f32_e32 v150, v150
	v_rcp_f32_e32 v151, v151
	v_exp_f32_e32 v142, v142
	v_exp_f32_e32 v143, v143
	v_mul_f32_e32 v130, 0xbfb8aa3b, v130
	v_mul_f32_e32 v131, 0xbfb8aa3b, v131
	v_add_f32_e32 v142, 1.0, v142
	v_add_f32_e32 v143, 1.0, v143
	v_rcp_f32_e32 v142, v142
	v_rcp_f32_e32 v143, v143
	v_exp_f32_e32 v130, v130
	v_exp_f32_e32 v131, v131
	v_mul_f32_e32 v122, 0xbfb8aa3b, v122
	v_mul_f32_e32 v123, 0xbfb8aa3b, v123
	v_add_f32_e32 v130, 1.0, v130
	v_add_f32_e32 v131, 1.0, v131
	v_rcp_f32_e32 v130, v130
	v_rcp_f32_e32 v131, v131
	v_exp_f32_e32 v122, v122
	v_exp_f32_e32 v123, v123
	v_or_b32_e32 v108, 32, v106
	v_ashrrev_i32_e32 v109, 31, v108
	v_lshlrev_b64 v[180:181], 10, v[108:109]
	v_lshl_add_u64 v[108:109], v[174:175], 0, v[180:181]
	v_add_f32_e32 v122, 1.0, v122
	v_add_f32_e32 v123, 1.0, v123
	global_load_dwordx4 v[134:137], v[108:109], off
	global_load_dwordx4 v[126:129], v[108:109], off offset:256
	v_rcp_f32_e32 v122, v122
	v_rcp_f32_e32 v123, v123
	v_mul_f32_e32 v118, 0xbfb8aa3b, v118
	v_mul_f32_e32 v119, 0xbfb8aa3b, v119
	v_exp_f32_e32 v118, v118
	v_exp_f32_e32 v119, v119
	v_mul_f32_e32 v114, 0xbfb8aa3b, v114
	v_mul_f32_e32 v115, 0xbfb8aa3b, v115
	v_add_f32_e32 v118, 1.0, v118
	v_add_f32_e32 v119, 1.0, v119
	v_rcp_f32_e32 v118, v118
	v_rcp_f32_e32 v119, v119
	v_exp_f32_e32 v114, v114
	v_exp_f32_e32 v115, v115
	v_mul_f32_e32 v102, 0xbfb8aa3b, v102
	v_mul_f32_e32 v103, 0xbfb8aa3b, v103
	v_add_f32_e32 v114, 1.0, v114
	v_add_f32_e32 v115, 1.0, v115
	v_rcp_f32_e32 v114, v114
	v_rcp_f32_e32 v115, v115
	v_exp_f32_e32 v102, v102
	v_exp_f32_e32 v103, v103
	v_mul_f32_e32 v98, 0xbfb8aa3b, v98
	v_mul_f32_e32 v99, 0xbfb8aa3b, v99
	v_add_f32_e32 v102, 1.0, v102
	v_add_f32_e32 v103, 1.0, v103
	v_rcp_f32_e32 v102, v102
	v_rcp_f32_e32 v103, v103
	v_exp_f32_e32 v98, v98
	v_exp_f32_e32 v99, v99
	v_or_b32_e32 v106, 48, v106
	v_ashrrev_i32_e32 v107, 31, v106
	v_lshlrev_b64 v[178:179], 10, v[106:107]
	v_lshl_add_u64 v[106:107], v[174:175], 0, v[178:179]
	v_add_f32_e32 v98, 1.0, v98
	v_add_f32_e32 v99, 1.0, v99
	global_load_dwordx4 v[110:113], v[106:107], off
	s_nop 0
	global_load_dwordx4 v[106:109], v[106:107], off offset:256
	v_rcp_f32_e32 v98, v98
	s_waitcnt vmcnt(0)
	v_lshlrev_b32_e32 v188, 16, v158
	v_and_b32_e32 v189, 0xffff0000, v158
	v_pk_mul_f32 v[150:151], v[150:151], v[188:189]
	v_lshlrev_b32_e32 v158, 16, v159
	v_cvt_pk_bf16_f32 v150, v150, v151
	v_mul_f32_e32 v151, 0xbfb8aa3b, v152
	v_exp_f32_e32 v151, v151
	v_and_b32_e32 v159, 0xffff0000, v159
	v_rcp_f32_e32 v99, v99
	v_mul_f32_e32 v94, 0xbfb8aa3b, v94
	v_add_f32_e32 v151, 1.0, v151
	v_rcp_f32_e32 v152, v151
	v_mul_f32_e32 v151, 0xbfb8aa3b, v153
	v_exp_f32_e32 v151, v151
	v_mul_f32_e32 v95, 0xbfb8aa3b, v95
	v_exp_f32_e32 v94, v94
	v_exp_f32_e32 v95, v95
	v_add_f32_e32 v151, 1.0, v151
	v_rcp_f32_e32 v153, v151
	v_add_f32_e32 v94, 1.0, v94
	v_add_f32_e32 v95, 1.0, v95
	v_rcp_f32_e32 v94, v94
	v_pk_mul_f32 v[152:153], v[152:153], v[158:159]
	v_rcp_f32_e32 v95, v95
	v_cvt_pk_bf16_f32 v151, v152, v153
	v_lshlrev_b32_e32 v152, 16, v160
	v_and_b32_e32 v153, 0xffff0000, v160
	v_pk_mul_f32 v[142:143], v[142:143], v[152:153]
	v_mul_f32_e32 v90, 0xbfb8aa3b, v90
	v_cvt_pk_bf16_f32 v152, v142, v143
	v_mul_f32_e32 v142, 0xbfb8aa3b, v144
	v_mul_f32_e32 v143, 0xbfb8aa3b, v145
	v_exp_f32_e32 v142, v142
	v_exp_f32_e32 v143, v143
	v_lshlrev_b32_e32 v144, 16, v161
	v_and_b32_e32 v145, 0xffff0000, v161
	v_add_f32_e32 v142, 1.0, v142
	v_add_f32_e32 v143, 1.0, v143
	v_rcp_f32_e32 v142, v142
	v_rcp_f32_e32 v143, v143
	v_mul_f32_e32 v91, 0xbfb8aa3b, v91
	v_exp_f32_e32 v90, v90
	v_exp_f32_e32 v91, v91
	v_pk_mul_f32 v[142:143], v[142:143], v[144:145]
	v_lshlrev_b32_e32 v144, 16, v154
	v_and_b32_e32 v145, 0xffff0000, v154
	v_pk_mul_f32 v[130:131], v[130:131], v[144:145]
	v_lshlrev_b32_e32 v144, 16, v155
	v_cvt_pk_bf16_f32 v130, v130, v131
	v_mul_f32_e32 v131, 0xbfb8aa3b, v132
	v_exp_f32_e32 v131, v131
	v_and_b32_e32 v145, 0xffff0000, v155
	v_add_f32_e32 v90, 1.0, v90
	v_add_f32_e32 v91, 1.0, v91
	v_add_f32_e32 v131, 1.0, v131
	v_rcp_f32_e32 v132, v131
	v_mul_f32_e32 v131, 0xbfb8aa3b, v133
	v_exp_f32_e32 v131, v131
	v_rcp_f32_e32 v90, v90
	v_rcp_f32_e32 v91, v91
	v_mul_f32_e32 v86, 0xbfb8aa3b, v86
	v_add_f32_e32 v131, 1.0, v131
	v_rcp_f32_e32 v133, v131
	v_mul_f32_e32 v87, 0xbfb8aa3b, v87
	v_exp_f32_e32 v86, v86
	v_exp_f32_e32 v87, v87
	v_pk_mul_f32 v[132:133], v[132:133], v[144:145]
	v_mul_f32_e32 v82, 0xbfb8aa3b, v82
	v_cvt_pk_bf16_f32 v131, v132, v133
	v_lshlrev_b32_e32 v132, 16, v156
	v_and_b32_e32 v133, 0xffff0000, v156
	v_pk_mul_f32 v[122:123], v[122:123], v[132:133]
	v_add_f32_e32 v86, 1.0, v86
	v_cvt_pk_bf16_f32 v132, v122, v123
	v_mul_f32_e32 v122, 0xbfb8aa3b, v124
	v_mul_f32_e32 v123, 0xbfb8aa3b, v125
	v_exp_f32_e32 v122, v122
	v_exp_f32_e32 v123, v123
	v_lshlrev_b32_e32 v124, 16, v157
	v_and_b32_e32 v125, 0xffff0000, v157
	v_add_f32_e32 v122, 1.0, v122
	v_add_f32_e32 v123, 1.0, v123
	v_rcp_f32_e32 v122, v122
	v_rcp_f32_e32 v123, v123
	v_add_f32_e32 v87, 1.0, v87
	v_rcp_f32_e32 v86, v86
	v_rcp_f32_e32 v87, v87
	v_pk_mul_f32 v[122:123], v[122:123], v[124:125]
	v_mul_f32_e32 v83, 0xbfb8aa3b, v83
	v_cvt_pk_bf16_f32 v133, v122, v123
	v_lshlrev_b32_e32 v122, 16, v146
	v_and_b32_e32 v123, 0xffff0000, v146
	v_pk_mul_f32 v[118:119], v[118:119], v[122:123]
	v_lshlrev_b32_e32 v122, 16, v147
	v_cvt_pk_bf16_f32 v118, v118, v119
	v_mul_f32_e32 v119, 0xbfb8aa3b, v120
	v_exp_f32_e32 v119, v119
	v_and_b32_e32 v123, 0xffff0000, v147
	v_exp_f32_e32 v82, v82
	v_exp_f32_e32 v83, v83
	v_add_f32_e32 v119, 1.0, v119
	v_rcp_f32_e32 v120, v119
	v_mul_f32_e32 v119, 0xbfb8aa3b, v121
	v_exp_f32_e32 v119, v119
	v_add_f32_e32 v82, 1.0, v82
	v_add_f32_e32 v83, 1.0, v83
	v_rcp_f32_e32 v82, v82
	v_add_f32_e32 v119, 1.0, v119
	v_rcp_f32_e32 v121, v119
	v_rcp_f32_e32 v83, v83
	v_mul_f32_e32 v78, 0xbfb8aa3b, v78
	v_mul_f32_e32 v79, 0xbfb8aa3b, v79
	v_pk_mul_f32 v[120:121], v[120:121], v[122:123]
	v_exp_f32_e32 v78, v78
	v_cvt_pk_bf16_f32 v119, v120, v121
	v_lshlrev_b32_e32 v120, 16, v148
	v_and_b32_e32 v121, 0xffff0000, v148
	v_pk_mul_f32 v[114:115], v[114:115], v[120:121]
	v_exp_f32_e32 v79, v79
	v_cvt_pk_bf16_f32 v120, v114, v115
	v_mul_f32_e32 v114, 0xbfb8aa3b, v116
	v_mul_f32_e32 v115, 0xbfb8aa3b, v117
	v_exp_f32_e32 v114, v114
	v_exp_f32_e32 v115, v115
	v_lshlrev_b32_e32 v116, 16, v149
	v_and_b32_e32 v117, 0xffff0000, v149
	v_add_f32_e32 v114, 1.0, v114
	v_add_f32_e32 v115, 1.0, v115
	v_rcp_f32_e32 v114, v114
	v_rcp_f32_e32 v115, v115
	v_add_f32_e32 v78, 1.0, v78
	v_add_f32_e32 v79, 1.0, v79
	v_rcp_f32_e32 v78, v78
	v_pk_mul_f32 v[114:115], v[114:115], v[116:117]
	v_lshlrev_b32_e32 v116, 16, v138
	v_and_b32_e32 v117, 0xffff0000, v138
	v_pk_mul_f32 v[102:103], v[102:103], v[116:117]
	v_lshlrev_b32_e32 v116, 16, v139
	v_cvt_pk_bf16_f32 v102, v102, v103
	v_mul_f32_e32 v103, 0xbfb8aa3b, v104
	v_exp_f32_e32 v103, v103
	v_and_b32_e32 v117, 0xffff0000, v139
	v_rcp_f32_e32 v79, v79
	v_mul_f32_e32 v74, 0xbfb8aa3b, v74
	v_add_f32_e32 v103, 1.0, v103
	v_rcp_f32_e32 v104, v103
	v_mul_f32_e32 v103, 0xbfb8aa3b, v105
	v_exp_f32_e32 v103, v103
	v_mul_f32_e32 v75, 0xbfb8aa3b, v75
	v_exp_f32_e32 v74, v74
	v_exp_f32_e32 v75, v75
	v_add_f32_e32 v103, 1.0, v103
	v_rcp_f32_e32 v105, v103
	v_add_f32_e32 v74, 1.0, v74
	v_add_f32_e32 v75, 1.0, v75
	v_rcp_f32_e32 v74, v74
	v_pk_mul_f32 v[104:105], v[104:105], v[116:117]
	v_rcp_f32_e32 v75, v75
	v_cvt_pk_bf16_f32 v103, v104, v105
	v_lshlrev_b32_e32 v104, 16, v140
	v_and_b32_e32 v105, 0xffff0000, v140
	v_pk_mul_f32 v[98:99], v[98:99], v[104:105]
	v_mul_f32_e32 v70, 0xbfb8aa3b, v70
	v_cvt_pk_bf16_f32 v104, v98, v99
	v_mul_f32_e32 v98, 0xbfb8aa3b, v100
	v_mul_f32_e32 v99, 0xbfb8aa3b, v101
	v_exp_f32_e32 v98, v98
	v_exp_f32_e32 v99, v99
	v_lshlrev_b32_e32 v100, 16, v141
	v_and_b32_e32 v101, 0xffff0000, v141
	v_add_f32_e32 v98, 1.0, v98
	v_add_f32_e32 v99, 1.0, v99
	v_rcp_f32_e32 v98, v98
	v_rcp_f32_e32 v99, v99
	v_mul_f32_e32 v71, 0xbfb8aa3b, v71
	v_exp_f32_e32 v70, v70
	v_exp_f32_e32 v71, v71
	v_pk_mul_f32 v[98:99], v[98:99], v[100:101]
	v_mul_f32_e32 v66, 0xbfb8aa3b, v66
	v_cvt_pk_bf16_f32 v105, v98, v99
	v_lshlrev_b32_e32 v98, 16, v134
	v_and_b32_e32 v99, 0xffff0000, v134
	v_pk_mul_f32 v[94:95], v[94:95], v[98:99]
	v_lshlrev_b32_e32 v98, 16, v135
	v_cvt_pk_bf16_f32 v94, v94, v95
	v_mul_f32_e32 v95, 0xbfb8aa3b, v96
	v_exp_f32_e32 v95, v95
	v_and_b32_e32 v99, 0xffff0000, v135
	v_add_f32_e32 v70, 1.0, v70
	v_add_f32_e32 v71, 1.0, v71
	v_add_f32_e32 v95, 1.0, v95
	v_rcp_f32_e32 v96, v95
	v_mul_f32_e32 v95, 0xbfb8aa3b, v97
	v_exp_f32_e32 v95, v95
	v_rcp_f32_e32 v70, v70
	v_rcp_f32_e32 v71, v71
	v_mul_f32_e32 v67, 0xbfb8aa3b, v67
	v_add_f32_e32 v95, 1.0, v95
	v_rcp_f32_e32 v97, v95
	v_exp_f32_e32 v66, v66
	v_exp_f32_e32 v67, v67
	v_readlane_b32 s2, v253, 6
	v_pk_mul_f32 v[96:97], v[96:97], v[98:99]
	v_add_f32_e32 v66, 1.0, v66
	v_cvt_pk_bf16_f32 v95, v96, v97
	v_lshlrev_b32_e32 v96, 16, v136
	v_and_b32_e32 v97, 0xffff0000, v136
	v_pk_mul_f32 v[90:91], v[90:91], v[96:97]
	v_add_f32_e32 v67, 1.0, v67
	v_cvt_pk_bf16_f32 v96, v90, v91
	v_mul_f32_e32 v90, 0xbfb8aa3b, v92
	v_mul_f32_e32 v91, 0xbfb8aa3b, v93
	v_exp_f32_e32 v90, v90
	v_exp_f32_e32 v91, v91
	v_lshlrev_b32_e32 v92, 16, v137
	v_and_b32_e32 v93, 0xffff0000, v137
	v_add_f32_e32 v90, 1.0, v90
	v_add_f32_e32 v91, 1.0, v91
	v_rcp_f32_e32 v90, v90
	v_rcp_f32_e32 v91, v91
	v_rcp_f32_e32 v66, v66
	v_rcp_f32_e32 v67, v67
	v_readlane_b32 s3, v253, 7
	v_pk_mul_f32 v[90:91], v[90:91], v[92:93]
	v_lshlrev_b32_e32 v92, 16, v126
	v_and_b32_e32 v93, 0xffff0000, v126
	v_pk_mul_f32 v[86:87], v[86:87], v[92:93]
	v_lshlrev_b32_e32 v92, 16, v127
	v_cvt_pk_bf16_f32 v86, v86, v87
	v_mul_f32_e32 v87, 0xbfb8aa3b, v88
	v_exp_f32_e32 v87, v87
	v_and_b32_e32 v93, 0xffff0000, v127
	v_cvt_pk_bf16_f32 v121, v114, v115
	v_lshl_add_u64 v[114:115], s[2:3], 0, v[182:183]
	v_add_f32_e32 v87, 1.0, v87
	v_rcp_f32_e32 v88, v87
	v_mul_f32_e32 v87, 0xbfb8aa3b, v89
	v_exp_f32_e32 v87, v87
	v_cvt_pk_bf16_f32 v153, v142, v143
	v_lshl_add_u64 v[142:143], s[2:3], 0, v[176:177]
	v_lshl_add_u64 v[114:115], v[114:115], 0, v[172:173]
	v_add_f32_e32 v87, 1.0, v87
	v_rcp_f32_e32 v89, v87
	v_cvt_pk_bf16_f32 v97, v90, v91
	v_lshl_add_u64 v[90:91], s[2:3], 0, v[180:181]
	s_mov_b64 s[12:13], 0x20000
	v_pk_mul_f32 v[88:89], v[88:89], v[92:93]
	v_lshl_add_u64 v[142:143], v[142:143], 0, v[172:173]
	v_cvt_pk_bf16_f32 v87, v88, v89
	v_lshlrev_b32_e32 v88, 16, v128
	v_and_b32_e32 v89, 0xffff0000, v128
	v_pk_mul_f32 v[82:83], v[82:83], v[88:89]
	global_store_dwordx4 v[114:115], v[102:105], off offset:256
	v_cvt_pk_bf16_f32 v88, v82, v83
	v_mul_f32_e32 v82, 0xbfb8aa3b, v84
	v_mul_f32_e32 v83, 0xbfb8aa3b, v85
	v_exp_f32_e32 v82, v82
	v_exp_f32_e32 v83, v83
	v_lshlrev_b32_e32 v84, 16, v129
	v_and_b32_e32 v85, 0xffff0000, v129
	v_add_f32_e32 v82, 1.0, v82
	v_add_f32_e32 v83, 1.0, v83
	v_rcp_f32_e32 v82, v82
	v_rcp_f32_e32 v83, v83
	v_lshl_add_u64 v[90:91], v[90:91], 0, v[172:173]
	v_lshl_add_u64 v[104:105], v[176:177], 0, s[12:13]
	global_store_dwordx4 v[142:143], v[150:153], off
	v_pk_mul_f32 v[82:83], v[82:83], v[84:85]
	global_store_dwordx4 v[142:143], v[130:133], off offset:256
	v_cvt_pk_bf16_f32 v89, v82, v83
	v_lshlrev_b32_e32 v82, 16, v110
	v_and_b32_e32 v83, 0xffff0000, v110
	v_pk_mul_f32 v[78:79], v[78:79], v[82:83]
	v_lshlrev_b32_e32 v82, 16, v111
	v_cvt_pk_bf16_f32 v78, v78, v79
	v_mul_f32_e32 v79, 0xbfb8aa3b, v80
	v_exp_f32_e32 v79, v79
	v_and_b32_e32 v83, 0xffff0000, v111
	global_store_dwordx4 v[114:115], v[118:121], off
	global_store_dwordx4 v[90:91], v[94:97], off
	v_add_f32_e32 v79, 1.0, v79
	v_rcp_f32_e32 v80, v79
	v_mul_f32_e32 v79, 0xbfb8aa3b, v81
	v_exp_f32_e32 v79, v79
	global_store_dwordx4 v[90:91], v[86:89], off offset:256
	s_mov_b64 s[12:13], 0x24000
	v_lshl_add_u64 v[102:103], v[176:177], 0, s[12:13]
	v_add_f32_e32 v79, 1.0, v79
	v_rcp_f32_e32 v81, v79
	v_mul_f32_e32 v62, 0xbfb8aa3b, v62
	v_mul_f32_e32 v63, 0xbfb8aa3b, v63
	v_exp_f32_e32 v62, v62
	v_pk_mul_f32 v[80:81], v[80:81], v[82:83]
	v_exp_f32_e32 v63, v63
	v_cvt_pk_bf16_f32 v79, v80, v81
	v_lshlrev_b32_e32 v80, 16, v112
	v_and_b32_e32 v81, 0xffff0000, v112
	v_pk_mul_f32 v[74:75], v[74:75], v[80:81]
	v_add_f32_e32 v62, 1.0, v62
	v_cvt_pk_bf16_f32 v80, v74, v75
	v_mul_f32_e32 v74, 0xbfb8aa3b, v76
	v_mul_f32_e32 v75, 0xbfb8aa3b, v77
	v_exp_f32_e32 v74, v74
	v_exp_f32_e32 v75, v75
	v_lshlrev_b32_e32 v76, 16, v113
	v_and_b32_e32 v77, 0xffff0000, v113
	v_add_f32_e32 v74, 1.0, v74
	v_add_f32_e32 v75, 1.0, v75
	v_rcp_f32_e32 v74, v74
	v_rcp_f32_e32 v75, v75
	v_add_f32_e32 v63, 1.0, v63
	v_rcp_f32_e32 v62, v62
	v_rcp_f32_e32 v63, v63
	v_pk_mul_f32 v[74:75], v[74:75], v[76:77]
	v_lshlrev_b32_e32 v76, 16, v106
	v_and_b32_e32 v77, 0xffff0000, v106
	v_pk_mul_f32 v[70:71], v[70:71], v[76:77]
	v_lshlrev_b32_e32 v76, 16, v107
	v_cvt_pk_bf16_f32 v70, v70, v71
	v_mul_f32_e32 v71, 0xbfb8aa3b, v72
	v_exp_f32_e32 v71, v71
	v_and_b32_e32 v77, 0xffff0000, v107
	v_cvt_pk_bf16_f32 v81, v74, v75
	v_lshl_add_u64 v[74:75], s[2:3], 0, v[178:179]
	v_add_f32_e32 v71, 1.0, v71
	v_rcp_f32_e32 v72, v71
	v_mul_f32_e32 v71, 0xbfb8aa3b, v73
	v_exp_f32_e32 v71, v71
	v_lshl_add_u64 v[74:75], v[74:75], 0, v[172:173]
	global_store_dwordx4 v[74:75], v[78:81], off
	v_mul_f32_e32 v58, 0xbfb8aa3b, v58
	v_add_f32_e32 v71, 1.0, v71
	v_rcp_f32_e32 v73, v71
	v_mul_f32_e32 v59, 0xbfb8aa3b, v59
	v_exp_f32_e32 v58, v58
	v_exp_f32_e32 v59, v59
	v_pk_mul_f32 v[72:73], v[72:73], v[76:77]
	v_mul_f32_e32 v54, 0xbfb8aa3b, v54
	v_cvt_pk_bf16_f32 v71, v72, v73
	v_lshlrev_b32_e32 v72, 16, v108
	v_and_b32_e32 v73, 0xffff0000, v108
	v_pk_mul_f32 v[66:67], v[66:67], v[72:73]
	v_add_f32_e32 v58, 1.0, v58
	v_cvt_pk_bf16_f32 v72, v66, v67
	v_mul_f32_e32 v66, 0xbfb8aa3b, v68
	v_mul_f32_e32 v67, 0xbfb8aa3b, v69
	v_exp_f32_e32 v66, v66
	v_exp_f32_e32 v67, v67
	v_lshlrev_b32_e32 v68, 16, v109
	v_and_b32_e32 v69, 0xffff0000, v109
	v_add_f32_e32 v66, 1.0, v66
	v_add_f32_e32 v67, 1.0, v67
	v_rcp_f32_e32 v66, v66
	v_rcp_f32_e32 v67, v67
	v_add_f32_e32 v59, 1.0, v59
	v_rcp_f32_e32 v58, v58
	v_rcp_f32_e32 v59, v59
	v_pk_mul_f32 v[66:67], v[66:67], v[68:69]
	v_mul_f32_e32 v55, 0xbfb8aa3b, v55
	v_cvt_pk_bf16_f32 v73, v66, v67
	global_store_dwordx4 v[74:75], v[70:73], off offset:256
	v_lshl_add_u64 v[66:67], v[174:175], 0, v[104:105]
	global_load_dwordx4 v[90:93], v[66:67], off
	global_load_dwordx4 v[94:97], v[66:67], off offset:256
	v_lshl_add_u64 v[66:67], v[174:175], 0, v[102:103]
	global_load_dwordx4 v[86:89], v[66:67], off
	global_load_dwordx4 v[82:85], v[66:67], off offset:256
	v_exp_f32_e32 v54, v54
	v_exp_f32_e32 v55, v55
	v_mul_f32_e32 v50, 0xbfb8aa3b, v50
	v_mul_f32_e32 v51, 0xbfb8aa3b, v51
	v_add_f32_e32 v54, 1.0, v54
	v_add_f32_e32 v55, 1.0, v55
	v_rcp_f32_e32 v54, v54
	v_rcp_f32_e32 v55, v55
	v_exp_f32_e32 v50, v50
	v_exp_f32_e32 v51, v51
	s_mov_b64 s[12:13], 0x28000
	v_lshl_add_u64 v[100:101], v[176:177], 0, s[12:13]
	v_lshl_add_u64 v[66:67], v[174:175], 0, v[100:101]
	v_add_f32_e32 v50, 1.0, v50
	v_add_f32_e32 v51, 1.0, v51
	global_load_dwordx4 v[78:81], v[66:67], off
	global_load_dwordx4 v[74:77], v[66:67], off offset:256
	v_rcp_f32_e32 v50, v50
	v_rcp_f32_e32 v51, v51
	v_mul_f32_e32 v46, 0xbfb8aa3b, v46
	v_mul_f32_e32 v47, 0xbfb8aa3b, v47
	v_exp_f32_e32 v46, v46
	v_exp_f32_e32 v47, v47
	v_mul_f32_e32 v42, 0xbfb8aa3b, v42
	v_mul_f32_e32 v43, 0xbfb8aa3b, v43
	v_add_f32_e32 v46, 1.0, v46
	v_add_f32_e32 v47, 1.0, v47
	v_rcp_f32_e32 v46, v46
	v_rcp_f32_e32 v47, v47
	v_exp_f32_e32 v42, v42
	v_exp_f32_e32 v43, v43
	v_mul_f32_e32 v38, 0xbfb8aa3b, v38
	v_mul_f32_e32 v39, 0xbfb8aa3b, v39
	v_add_f32_e32 v42, 1.0, v42
	v_add_f32_e32 v43, 1.0, v43
	v_rcp_f32_e32 v42, v42
	v_rcp_f32_e32 v43, v43
	v_exp_f32_e32 v38, v38
	v_exp_f32_e32 v39, v39
	v_mul_f32_e32 v34, 0xbfb8aa3b, v34
	v_mul_f32_e32 v35, 0xbfb8aa3b, v35
	v_add_f32_e32 v38, 1.0, v38
	v_add_f32_e32 v39, 1.0, v39
	v_rcp_f32_e32 v38, v38
	v_rcp_f32_e32 v39, v39
	v_exp_f32_e32 v34, v34
	v_exp_f32_e32 v35, v35
	s_mov_b64 s[12:13], 0x2c000
	v_lshl_add_u64 v[98:99], v[176:177], 0, s[12:13]
	v_lshl_add_u64 v[66:67], v[174:175], 0, v[98:99]
	v_add_f32_e32 v34, 1.0, v34
	v_add_f32_e32 v35, 1.0, v35
	global_load_dwordx4 v[70:73], v[66:67], off
	s_nop 0
	global_load_dwordx4 v[66:69], v[66:67], off offset:256
	v_rcp_f32_e32 v34, v34
	v_rcp_f32_e32 v35, v35
	v_mul_f32_e32 v30, 0xbfb8aa3b, v30
	v_mul_f32_e32 v31, 0xbfb8aa3b, v31
	v_exp_f32_e32 v30, v30
	v_exp_f32_e32 v31, v31
	v_mul_f32_e32 v26, 0xbfb8aa3b, v26
	v_mul_f32_e32 v27, 0xbfb8aa3b, v27
	v_add_f32_e32 v30, 1.0, v30
	v_add_f32_e32 v31, 1.0, v31
	v_rcp_f32_e32 v30, v30
	v_rcp_f32_e32 v31, v31
	v_exp_f32_e32 v26, v26
	v_exp_f32_e32 v27, v27
	v_mul_f32_e32 v22, 0xbfb8aa3b, v22
	v_mul_f32_e32 v23, 0xbfb8aa3b, v23
	v_add_f32_e32 v26, 1.0, v26
	v_add_f32_e32 v27, 1.0, v27
	v_rcp_f32_e32 v26, v26
	v_rcp_f32_e32 v27, v27
	v_exp_f32_e32 v22, v22
	v_exp_f32_e32 v23, v23
	v_mul_f32_e32 v18, 0xbfb8aa3b, v18
	v_mul_f32_e32 v19, 0xbfb8aa3b, v19
	s_waitcnt vmcnt(0)
	v_lshlrev_b32_e32 v106, 16, v90
	v_and_b32_e32 v107, 0xffff0000, v90
	v_pk_mul_f32 v[62:63], v[62:63], v[106:107]
	v_lshlrev_b32_e32 v90, 16, v91
	v_cvt_pk_bf16_f32 v62, v62, v63
	v_mul_f32_e32 v63, 0xbfb8aa3b, v64
	v_exp_f32_e32 v63, v63
	v_and_b32_e32 v91, 0xffff0000, v91
	v_add_f32_e32 v22, 1.0, v22
	v_add_f32_e32 v23, 1.0, v23
	v_add_f32_e32 v63, 1.0, v63
	v_rcp_f32_e32 v64, v63
	v_mul_f32_e32 v63, 0xbfb8aa3b, v65
	v_exp_f32_e32 v63, v63
	v_rcp_f32_e32 v22, v22
	v_rcp_f32_e32 v23, v23
	v_exp_f32_e32 v18, v18
	v_add_f32_e32 v63, 1.0, v63
	v_rcp_f32_e32 v65, v63
	v_exp_f32_e32 v19, v19
	v_add_f32_e32 v18, 1.0, v18
	v_rcp_f32_e32 v18, v18
	v_pk_mul_f32 v[64:65], v[64:65], v[90:91]
	v_add_f32_e32 v19, 1.0, v19
	v_cvt_pk_bf16_f32 v63, v64, v65
	v_lshlrev_b32_e32 v64, 16, v92
	v_and_b32_e32 v65, 0xffff0000, v92
	v_pk_mul_f32 v[58:59], v[58:59], v[64:65]
	v_rcp_f32_e32 v19, v19
	v_cvt_pk_bf16_f32 v64, v58, v59
	v_mul_f32_e32 v58, 0xbfb8aa3b, v60
	v_mul_f32_e32 v59, 0xbfb8aa3b, v61
	v_exp_f32_e32 v58, v58
	v_exp_f32_e32 v59, v59
	v_lshlrev_b32_e32 v60, 16, v93
	v_and_b32_e32 v61, 0xffff0000, v93
	v_add_f32_e32 v58, 1.0, v58
	v_add_f32_e32 v59, 1.0, v59
	v_rcp_f32_e32 v58, v58
	v_rcp_f32_e32 v59, v59
	v_mul_f32_e32 v14, 0xbfb8aa3b, v14
	v_mul_f32_e32 v15, 0xbfb8aa3b, v15
	v_exp_f32_e32 v14, v14
	v_pk_mul_f32 v[58:59], v[58:59], v[60:61]
	v_lshlrev_b32_e32 v60, 16, v94
	v_and_b32_e32 v61, 0xffff0000, v94
	v_pk_mul_f32 v[54:55], v[54:55], v[60:61]
	v_lshlrev_b32_e32 v60, 16, v95
	v_cvt_pk_bf16_f32 v54, v54, v55
	v_mul_f32_e32 v55, 0xbfb8aa3b, v56
	v_exp_f32_e32 v55, v55
	v_and_b32_e32 v61, 0xffff0000, v95
	v_exp_f32_e32 v15, v15
	v_add_f32_e32 v14, 1.0, v14
	v_add_f32_e32 v55, 1.0, v55
	v_rcp_f32_e32 v56, v55
	v_mul_f32_e32 v55, 0xbfb8aa3b, v57
	v_exp_f32_e32 v55, v55
	v_add_f32_e32 v15, 1.0, v15
	v_rcp_f32_e32 v14, v14
	v_rcp_f32_e32 v15, v15
	v_add_f32_e32 v55, 1.0, v55
	v_rcp_f32_e32 v57, v55
	v_mul_f32_e32 v10, 0xbfb8aa3b, v10
	v_mul_f32_e32 v11, 0xbfb8aa3b, v11
	v_exp_f32_e32 v10, v10
	v_pk_mul_f32 v[56:57], v[56:57], v[60:61]
	v_exp_f32_e32 v11, v11
	v_cvt_pk_bf16_f32 v55, v56, v57
	v_lshlrev_b32_e32 v56, 16, v96
	v_and_b32_e32 v57, 0xffff0000, v96
	v_pk_mul_f32 v[50:51], v[50:51], v[56:57]
	v_add_f32_e32 v10, 1.0, v10
	v_cvt_pk_bf16_f32 v56, v50, v51
	v_mul_f32_e32 v50, 0xbfb8aa3b, v52
	v_mul_f32_e32 v51, 0xbfb8aa3b, v53
	v_exp_f32_e32 v50, v50
	v_exp_f32_e32 v51, v51
	v_lshlrev_b32_e32 v52, 16, v97
	v_and_b32_e32 v53, 0xffff0000, v97
	v_add_f32_e32 v50, 1.0, v50
	v_add_f32_e32 v51, 1.0, v51
	v_rcp_f32_e32 v50, v50
	v_rcp_f32_e32 v51, v51
	v_add_f32_e32 v11, 1.0, v11
	v_rcp_f32_e32 v10, v10
	v_rcp_f32_e32 v11, v11
	v_pk_mul_f32 v[50:51], v[50:51], v[52:53]
	v_mul_f32_e32 v6, 0xbfb8aa3b, v6
	v_cvt_pk_bf16_f32 v57, v50, v51
	v_lshlrev_b32_e32 v50, 16, v86
	v_and_b32_e32 v51, 0xffff0000, v86
	v_pk_mul_f32 v[46:47], v[46:47], v[50:51]
	v_lshlrev_b32_e32 v50, 16, v87
	v_cvt_pk_bf16_f32 v46, v46, v47
	v_mul_f32_e32 v47, 0xbfb8aa3b, v48
	v_exp_f32_e32 v47, v47
	v_and_b32_e32 v51, 0xffff0000, v87
	v_mul_f32_e32 v7, 0xbfb8aa3b, v7
	v_exp_f32_e32 v6, v6
	v_add_f32_e32 v47, 1.0, v47
	v_rcp_f32_e32 v48, v47
	v_mul_f32_e32 v47, 0xbfb8aa3b, v49
	v_exp_f32_e32 v47, v47
	v_exp_f32_e32 v7, v7
	v_add_f32_e32 v6, 1.0, v6
	v_rcp_f32_e32 v6, v6
	v_add_f32_e32 v47, 1.0, v47
	v_rcp_f32_e32 v49, v47
	v_add_f32_e32 v7, 1.0, v7
	v_rcp_f32_e32 v7, v7
	v_mul_f32_e32 v2, 0xbfb8aa3b, v2
	v_pk_mul_f32 v[48:49], v[48:49], v[50:51]
	v_mul_f32_e32 v3, 0xbfb8aa3b, v3
	v_cvt_pk_bf16_f32 v47, v48, v49
	v_lshlrev_b32_e32 v48, 16, v88
	v_and_b32_e32 v49, 0xffff0000, v88
	v_pk_mul_f32 v[42:43], v[42:43], v[48:49]
	v_exp_f32_e32 v2, v2
	v_cvt_pk_bf16_f32 v48, v42, v43
	v_mul_f32_e32 v42, 0xbfb8aa3b, v44
	v_mul_f32_e32 v43, 0xbfb8aa3b, v45
	v_exp_f32_e32 v42, v42
	v_exp_f32_e32 v43, v43
	v_lshlrev_b32_e32 v44, 16, v89
	v_and_b32_e32 v45, 0xffff0000, v89
	v_add_f32_e32 v42, 1.0, v42
	v_add_f32_e32 v43, 1.0, v43
	v_rcp_f32_e32 v42, v42
	v_rcp_f32_e32 v43, v43
	v_exp_f32_e32 v3, v3
	v_add_f32_e32 v2, 1.0, v2
	v_rcp_f32_e32 v2, v2
	v_pk_mul_f32 v[42:43], v[42:43], v[44:45]
	v_lshlrev_b32_e32 v44, 16, v82
	v_and_b32_e32 v45, 0xffff0000, v82
	v_pk_mul_f32 v[38:39], v[38:39], v[44:45]
	v_lshlrev_b32_e32 v44, 16, v83
	v_cvt_pk_bf16_f32 v38, v38, v39
	v_mul_f32_e32 v39, 0xbfb8aa3b, v40
	v_exp_f32_e32 v39, v39
	v_and_b32_e32 v45, 0xffff0000, v83
	v_add_f32_e32 v3, 1.0, v3
	v_rcp_f32_e32 v3, v3
	v_add_f32_e32 v39, 1.0, v39
	v_rcp_f32_e32 v40, v39
	v_mul_f32_e32 v39, 0xbfb8aa3b, v41
	v_exp_f32_e32 v39, v39
	v_cvt_pk_bf16_f32 v65, v58, v59
	v_lshl_add_u64 v[58:59], s[2:3], 0, v[104:105]
	v_cvt_pk_bf16_f32 v49, v42, v43
	v_add_f32_e32 v39, 1.0, v39
	v_rcp_f32_e32 v41, v39
	v_lshl_add_u64 v[42:43], s[2:3], 0, v[102:103]
	v_lshl_add_u64 v[58:59], v[58:59], 0, v[172:173]
	v_lshl_add_u64 v[42:43], v[42:43], 0, v[172:173]
	v_pk_mul_f32 v[40:41], v[40:41], v[44:45]
	s_and_b64 vcc, exec, s[36:37]
	v_cvt_pk_bf16_f32 v39, v40, v41
	v_lshlrev_b32_e32 v40, 16, v84
	v_and_b32_e32 v41, 0xffff0000, v84
	v_pk_mul_f32 v[34:35], v[34:35], v[40:41]
	s_mov_b32 s5, s0
	v_cvt_pk_bf16_f32 v40, v34, v35
	v_mul_f32_e32 v34, 0xbfb8aa3b, v36
	v_mul_f32_e32 v35, 0xbfb8aa3b, v37
	v_exp_f32_e32 v34, v34
	v_exp_f32_e32 v35, v35
	v_lshlrev_b32_e32 v36, 16, v85
	v_and_b32_e32 v37, 0xffff0000, v85
	v_add_f32_e32 v34, 1.0, v34
	v_add_f32_e32 v35, 1.0, v35
	v_rcp_f32_e32 v34, v34
	v_rcp_f32_e32 v35, v35
	s_mov_b32 s49, s6
	s_mov_b64 s[12:13], s[8:9]
	global_store_dwordx4 v[58:59], v[62:65], off
	v_pk_mul_f32 v[34:35], v[34:35], v[36:37]
	global_store_dwordx4 v[58:59], v[54:57], off offset:256
	v_cvt_pk_bf16_f32 v41, v34, v35
	v_lshlrev_b32_e32 v34, 16, v78
	v_and_b32_e32 v35, 0xffff0000, v78
	v_pk_mul_f32 v[30:31], v[30:31], v[34:35]
	v_lshlrev_b32_e32 v34, 16, v79
	v_cvt_pk_bf16_f32 v30, v30, v31
	v_mul_f32_e32 v31, 0xbfb8aa3b, v32
	v_exp_f32_e32 v31, v31
	v_and_b32_e32 v35, 0xffff0000, v79
	global_store_dwordx4 v[42:43], v[46:49], off
	global_store_dwordx4 v[42:43], v[38:41], off offset:256
	v_add_f32_e32 v31, 1.0, v31
	v_rcp_f32_e32 v32, v31
	v_mul_f32_e32 v31, 0xbfb8aa3b, v33
	v_exp_f32_e32 v31, v31
	s_nop 0
	v_add_f32_e32 v31, 1.0, v31
	v_rcp_f32_e32 v33, v31
	s_nop 0
	v_pk_mul_f32 v[32:33], v[32:33], v[34:35]
	s_nop 0
	v_cvt_pk_bf16_f32 v31, v32, v33
	v_lshlrev_b32_e32 v32, 16, v80
	v_and_b32_e32 v33, 0xffff0000, v80
	v_pk_mul_f32 v[26:27], v[26:27], v[32:33]
	s_nop 0
	v_cvt_pk_bf16_f32 v32, v26, v27
	v_mul_f32_e32 v26, 0xbfb8aa3b, v28
	v_mul_f32_e32 v27, 0xbfb8aa3b, v29
	v_exp_f32_e32 v26, v26
	v_exp_f32_e32 v27, v27
	v_lshlrev_b32_e32 v28, 16, v81
	v_and_b32_e32 v29, 0xffff0000, v81
	v_add_f32_e32 v26, 1.0, v26
	v_add_f32_e32 v27, 1.0, v27
	v_rcp_f32_e32 v26, v26
	v_rcp_f32_e32 v27, v27
	s_nop 0
	v_pk_mul_f32 v[26:27], v[26:27], v[28:29]
	v_lshlrev_b32_e32 v28, 16, v74
	v_and_b32_e32 v29, 0xffff0000, v74
	v_pk_mul_f32 v[22:23], v[22:23], v[28:29]
	v_lshlrev_b32_e32 v28, 16, v75
	v_cvt_pk_bf16_f32 v22, v22, v23
	v_mul_f32_e32 v23, 0xbfb8aa3b, v24
	v_exp_f32_e32 v23, v23
	v_and_b32_e32 v29, 0xffff0000, v75
	v_cvt_pk_bf16_f32 v33, v26, v27
	v_lshl_add_u64 v[26:27], s[2:3], 0, v[100:101]
	v_add_f32_e32 v23, 1.0, v23
	v_rcp_f32_e32 v24, v23
	v_mul_f32_e32 v23, 0xbfb8aa3b, v25
	v_exp_f32_e32 v23, v23
	v_lshl_add_u64 v[26:27], v[26:27], 0, v[172:173]
	global_store_dwordx4 v[26:27], v[30:33], off
	v_add_f32_e32 v23, 1.0, v23
	v_rcp_f32_e32 v25, v23
	s_nop 0
	v_pk_mul_f32 v[24:25], v[24:25], v[28:29]
	s_nop 0
	v_cvt_pk_bf16_f32 v23, v24, v25
	v_lshlrev_b32_e32 v24, 16, v76
	v_and_b32_e32 v25, 0xffff0000, v76
	v_pk_mul_f32 v[18:19], v[18:19], v[24:25]
	s_nop 0
	v_cvt_pk_bf16_f32 v24, v18, v19
	v_mul_f32_e32 v18, 0xbfb8aa3b, v20
	v_mul_f32_e32 v19, 0xbfb8aa3b, v21
	v_exp_f32_e32 v18, v18
	v_exp_f32_e32 v19, v19
	v_lshlrev_b32_e32 v20, 16, v77
	v_and_b32_e32 v21, 0xffff0000, v77
	v_add_f32_e32 v18, 1.0, v18
	v_add_f32_e32 v19, 1.0, v19
	v_rcp_f32_e32 v18, v18
	v_rcp_f32_e32 v19, v19
	s_nop 0
	v_pk_mul_f32 v[18:19], v[18:19], v[20:21]
	s_nop 0
	v_cvt_pk_bf16_f32 v25, v18, v19
	v_lshlrev_b32_e32 v18, 16, v70
	v_and_b32_e32 v19, 0xffff0000, v70
	v_pk_mul_f32 v[14:15], v[14:15], v[18:19]
	v_lshlrev_b32_e32 v18, 16, v71
	v_cvt_pk_bf16_f32 v14, v14, v15
	v_mul_f32_e32 v15, 0xbfb8aa3b, v16
	v_exp_f32_e32 v15, v15
	v_and_b32_e32 v19, 0xffff0000, v71
	global_store_dwordx4 v[26:27], v[22:25], off offset:256
	v_add_f32_e32 v15, 1.0, v15
	v_rcp_f32_e32 v16, v15
	v_mul_f32_e32 v15, 0xbfb8aa3b, v17
	v_exp_f32_e32 v15, v15
	s_nop 0
	v_add_f32_e32 v15, 1.0, v15
	v_rcp_f32_e32 v17, v15
	s_nop 0
	v_pk_mul_f32 v[16:17], v[16:17], v[18:19]
	s_nop 0
	v_cvt_pk_bf16_f32 v15, v16, v17
	v_lshlrev_b32_e32 v16, 16, v72
	v_and_b32_e32 v17, 0xffff0000, v72
	v_pk_mul_f32 v[10:11], v[10:11], v[16:17]
	s_nop 0
	v_cvt_pk_bf16_f32 v16, v10, v11
	v_mul_f32_e32 v10, 0xbfb8aa3b, v12
	v_mul_f32_e32 v11, 0xbfb8aa3b, v13
	v_exp_f32_e32 v10, v10
	v_exp_f32_e32 v11, v11
	v_lshlrev_b32_e32 v12, 16, v73
	v_and_b32_e32 v13, 0xffff0000, v73
	v_add_f32_e32 v10, 1.0, v10
	v_add_f32_e32 v11, 1.0, v11
	v_rcp_f32_e32 v10, v10
	v_rcp_f32_e32 v11, v11
	s_nop 0
	v_pk_mul_f32 v[10:11], v[10:11], v[12:13]
	v_lshlrev_b32_e32 v12, 16, v66
	v_and_b32_e32 v13, 0xffff0000, v66
	v_pk_mul_f32 v[6:7], v[6:7], v[12:13]
	v_lshlrev_b32_e32 v12, 16, v67
	v_cvt_pk_bf16_f32 v6, v6, v7
	v_mul_f32_e32 v7, 0xbfb8aa3b, v8
	v_exp_f32_e32 v7, v7
	v_and_b32_e32 v13, 0xffff0000, v67
	v_cvt_pk_bf16_f32 v17, v10, v11
	v_lshl_add_u64 v[10:11], s[2:3], 0, v[98:99]
	v_add_f32_e32 v7, 1.0, v7
	v_rcp_f32_e32 v8, v7
	v_mul_f32_e32 v7, 0xbfb8aa3b, v9
	v_exp_f32_e32 v7, v7
	v_lshl_add_u64 v[10:11], v[10:11], 0, v[172:173]
	s_mov_b64 s[2:3], s[10:11]
	global_store_dwordx4 v[10:11], v[14:17], off
	v_add_f32_e32 v7, 1.0, v7
	v_rcp_f32_e32 v9, v7
	s_nop 0
	v_pk_mul_f32 v[8:9], v[8:9], v[12:13]
	s_nop 0
	v_cvt_pk_bf16_f32 v7, v8, v9
	v_lshlrev_b32_e32 v8, 16, v68
	v_and_b32_e32 v9, 0xffff0000, v68
	v_pk_mul_f32 v[2:3], v[2:3], v[8:9]
	s_nop 0
	v_cvt_pk_bf16_f32 v8, v2, v3
	v_mul_f32_e32 v2, 0xbfb8aa3b, v4
	v_mul_f32_e32 v3, 0xbfb8aa3b, v5
	v_exp_f32_e32 v2, v2
	v_exp_f32_e32 v3, v3
	v_lshlrev_b32_e32 v4, 16, v69
	v_and_b32_e32 v5, 0xffff0000, v69
	v_add_f32_e32 v2, 1.0, v2
	v_add_f32_e32 v3, 1.0, v3
	v_rcp_f32_e32 v2, v2
	v_rcp_f32_e32 v3, v3
	s_nop 0
	v_pk_mul_f32 v[2:3], v[2:3], v[4:5]
	s_nop 0
	v_cvt_pk_bf16_f32 v9, v2, v3
	global_store_dwordx4 v[10:11], v[6:9], off offset:256
	s_cbranch_vccz .LBB0_399
	s_waitcnt vmcnt(0)
	s_cmpk_gt_u32 s16, 0xff
	v_readlane_b32 s50, v255, 53
	v_readlane_b32 s51, v255, 54
	s_cbranch_scc1 .LBB0_406
	s_barrier

.LBB0_442:
	s_add_u32 s2, s36, 0xfff00080
	s_addc_u32 s3, s37, -1
	s_add_i32 s34, 0, 0x10000
	v_add_u32_e32 v156, s34, v141
	ds_read_b128 v[144:147], v156
	ds_read_b128 v[148:151], v156 offset:1024
	ds_read_b128 v[152:155], v156 offset:2048
	ds_read_b128 v[156:159], v156 offset:3072
	s_cmp_eq_u32 s60, 28
	s_cselect_b32 s3, s11, s3
	s_cselect_b32 s2, vcc_lo, s2
	s_cselect_b32 s39, s7, s50
	s_cselect_b32 s38, s9, vcc_hi
	v_lshl_add_u64 v[192:193], s[36:37], 0, v[136:137]
	s_add_i32 m0, s59, 0xc000
	ds_read_b128 v[160:163], v143
	ds_read_b128 v[164:167], v143 offset:1024
	ds_read_b128 v[168:171], v143 offset:2048
	ds_read_b128 v[172:175], v143 offset:3072
	ds_read_b128 v[176:179], v143 offset:4096
	ds_read_b128 v[180:183], v143 offset:5120
	ds_read_b128 v[184:187], v143 offset:6144
	ds_read_b128 v[188:191], v143 offset:7168
	global_load_lds_dwordx4 v[192:193], off
	v_lshl_add_u64 v[192:193], s[36:37], 0, v[138:139]
	s_add_i32 m0, s59, 0xe000
	s_nop 0
	global_load_lds_dwordx4 v[192:193], off
	s_waitcnt vmcnt(10)
	s_waitcnt lgkmcnt(8)
	s_barrier
	s_waitcnt lgkmcnt(0)
	s_setprio 1
	s_waitcnt lgkmcnt(0)
	v_mfma_f32_16x16x32_bf16 v[126:129], v[144:147], v[160:163], v[126:129]
	v_mfma_f32_16x16x32_bf16 v[122:125], v[152:155], v[160:163], v[122:125]
	v_mfma_f32_16x16x32_bf16 v[118:121], v[144:147], v[168:171], v[118:121]
	v_mfma_f32_16x16x32_bf16 v[114:117], v[152:155], v[168:171], v[114:117]
	v_mfma_f32_16x16x32_bf16 v[102:105], v[144:147], v[176:179], v[102:105]
	v_mfma_f32_16x16x32_bf16 v[98:101], v[152:155], v[176:179], v[98:101]
	v_mfma_f32_16x16x32_bf16 v[86:89], v[144:147], v[184:187], v[86:89]
	v_mfma_f32_16x16x32_bf16 v[82:85], v[152:155], v[184:187], v[82:85]
	v_mfma_f32_16x16x32_bf16 v[126:129], v[148:151], v[164:167], v[126:129]
	v_mfma_f32_16x16x32_bf16 v[122:125], v[156:159], v[164:167], v[122:125]
	v_mfma_f32_16x16x32_bf16 v[118:121], v[148:151], v[172:175], v[118:121]
	v_mfma_f32_16x16x32_bf16 v[114:117], v[156:159], v[172:175], v[114:117]
	v_mfma_f32_16x16x32_bf16 v[102:105], v[148:151], v[180:183], v[102:105]
	v_mfma_f32_16x16x32_bf16 v[98:101], v[156:159], v[180:183], v[98:101]
	v_mfma_f32_16x16x32_bf16 v[86:89], v[148:151], v[188:191], v[86:89]
	v_mfma_f32_16x16x32_bf16 v[82:85], v[156:159], v[188:191], v[82:85]
	s_setprio 0
	s_barrier
	s_add_i32 s40, 0, 0x14000
	v_add_u32_e32 v192, s40, v141
	s_add_i32 s34, s34, s53
	ds_read_b128 v[200:203], v192
	ds_read_b128 v[206:209], v192 offset:1024
	ds_read_b128 v[210:213], v192 offset:2048
	ds_read_b128 v[214:217], v192 offset:3072
	v_lshl_add_u64 v[192:193], s[38:39], 0, v[0:1]
	s_mov_b32 m0, s34
	v_lshl_add_u64 v[196:197], s[38:39], 0, v[130:131]
	global_load_lds_dwordx4 v[192:193], off
	s_add_i32 m0, s34, 0x2000
	s_nop 0
	global_load_lds_dwordx4 v[196:197], off
	s_mov_b32 m0, s59
	v_lshl_add_u64 v[198:199], s[2:3], 0, v[134:135]
	global_load_lds_dwordx4 v[198:199], off
	v_lshl_add_u64 v[218:219], s[2:3], 0, v[132:133]
	s_mov_b32 m0, s67
	s_nop 0
	global_load_lds_dwordx4 v[218:219], off
	s_waitcnt vmcnt(12)
	s_barrier
	s_waitcnt lgkmcnt(0)
	s_setprio 1
	s_waitcnt lgkmcnt(0)
	v_mfma_f32_16x16x32_bf16 v[110:113], v[200:203], v[160:163], v[110:113]
	v_mfma_f32_16x16x32_bf16 v[106:109], v[210:213], v[160:163], v[106:109]
	v_mfma_f32_16x16x32_bf16 v[94:97], v[200:203], v[168:171], v[94:97]
	v_mfma_f32_16x16x32_bf16 v[90:93], v[210:213], v[168:171], v[90:93]
	v_mfma_f32_16x16x32_bf16 v[78:81], v[200:203], v[176:179], v[78:81]
	v_mfma_f32_16x16x32_bf16 v[74:77], v[210:213], v[176:179], v[74:77]
	v_mfma_f32_16x16x32_bf16 v[70:73], v[200:203], v[184:187], v[70:73]
	v_mfma_f32_16x16x32_bf16 v[66:69], v[210:213], v[184:187], v[66:69]
	v_mfma_f32_16x16x32_bf16 v[110:113], v[206:209], v[164:167], v[110:113]
	v_mfma_f32_16x16x32_bf16 v[106:109], v[214:217], v[164:167], v[106:109]
	v_mfma_f32_16x16x32_bf16 v[94:97], v[206:209], v[172:175], v[94:97]
	v_mfma_f32_16x16x32_bf16 v[90:93], v[214:217], v[172:175], v[90:93]
	v_mfma_f32_16x16x32_bf16 v[78:81], v[206:209], v[180:183], v[78:81]
	v_mfma_f32_16x16x32_bf16 v[74:77], v[214:217], v[180:183], v[74:77]
	v_mfma_f32_16x16x32_bf16 v[70:73], v[206:209], v[188:191], v[70:73]
	v_mfma_f32_16x16x32_bf16 v[66:69], v[214:217], v[188:191], v[66:69]
	s_setprio 0
	s_barrier
	ds_read_b128 v[160:163], v143 offset:16384
	ds_read_b128 v[164:167], v143 offset:17408
	ds_read_b128 v[168:171], v143 offset:18432
	ds_read_b128 v[172:175], v143 offset:19456
	ds_read_b128 v[176:179], v143 offset:20480
	ds_read_b128 v[180:183], v143 offset:21504
	ds_read_b128 v[184:187], v143 offset:22528
	ds_read_b128 v[188:191], v143 offset:23552
	s_barrier
	s_waitcnt lgkmcnt(0)
	s_setprio 1
	s_waitcnt lgkmcnt(0)
	v_mfma_f32_16x16x32_bf16 v[62:65], v[144:147], v[160:163], v[62:65]
	v_mfma_f32_16x16x32_bf16 v[58:61], v[152:155], v[160:163], v[58:61]
	v_mfma_f32_16x16x32_bf16 v[54:57], v[144:147], v[168:171], v[54:57]
	v_mfma_f32_16x16x32_bf16 v[50:53], v[152:155], v[168:171], v[50:53]
	v_mfma_f32_16x16x32_bf16 v[38:41], v[144:147], v[176:179], v[38:41]
	v_mfma_f32_16x16x32_bf16 v[34:37], v[152:155], v[176:179], v[34:37]
	v_mfma_f32_16x16x32_bf16 v[22:25], v[144:147], v[184:187], v[22:25]
	v_mfma_f32_16x16x32_bf16 v[18:21], v[152:155], v[184:187], v[18:21]
	v_mfma_f32_16x16x32_bf16 v[62:65], v[148:151], v[164:167], v[62:65]
	v_mfma_f32_16x16x32_bf16 v[58:61], v[156:159], v[164:167], v[58:61]
	v_mfma_f32_16x16x32_bf16 v[54:57], v[148:151], v[172:175], v[54:57]
	v_mfma_f32_16x16x32_bf16 v[50:53], v[156:159], v[172:175], v[50:53]
	v_mfma_f32_16x16x32_bf16 v[38:41], v[148:151], v[180:183], v[38:41]
	v_mfma_f32_16x16x32_bf16 v[34:37], v[156:159], v[180:183], v[34:37]
	v_mfma_f32_16x16x32_bf16 v[22:25], v[148:151], v[188:191], v[22:25]
	v_mfma_f32_16x16x32_bf16 v[18:21], v[156:159], v[188:191], v[18:21]
	s_setprio 0
	s_barrier
	s_add_u32 s34, s38, 0x200000
	s_addc_u32 s35, s39, 0
	s_add_i32 s40, s40, s53
	v_lshl_add_u64 v[144:145], s[34:35], 0, v[0:1]
	s_mov_b32 m0, s40
	s_nop 0
	global_load_lds_dwordx4 v[144:145], off
	v_lshl_add_u64 v[144:145], s[34:35], 0, v[130:131]
	s_add_i32 m0, s40, 0x2000
	s_nop 0
	global_load_lds_dwordx4 v[144:145], off
	s_waitcnt vmcnt(10)
	s_barrier
	s_setprio 1
	v_mfma_f32_16x16x32_bf16 v[46:49], v[200:203], v[160:163], v[46:49]
	v_mfma_f32_16x16x32_bf16 v[42:45], v[210:213], v[160:163], v[42:45]
	v_mfma_f32_16x16x32_bf16 v[30:33], v[200:203], v[168:171], v[30:33]
	v_mfma_f32_16x16x32_bf16 v[26:29], v[210:213], v[168:171], v[26:29]
	v_mfma_f32_16x16x32_bf16 v[14:17], v[200:203], v[176:179], v[14:17]
	v_mfma_f32_16x16x32_bf16 v[10:13], v[210:213], v[176:179], v[10:13]
	v_mfma_f32_16x16x32_bf16 v[6:9], v[200:203], v[184:187], v[6:9]
	v_mfma_f32_16x16x32_bf16 v[2:5], v[210:213], v[184:187], v[2:5]
	v_mfma_f32_16x16x32_bf16 v[46:49], v[206:209], v[164:167], v[46:49]
	v_mfma_f32_16x16x32_bf16 v[42:45], v[214:217], v[164:167], v[42:45]
	v_mfma_f32_16x16x32_bf16 v[30:33], v[206:209], v[172:175], v[30:33]
	v_mfma_f32_16x16x32_bf16 v[26:29], v[214:217], v[172:175], v[26:29]
	v_mfma_f32_16x16x32_bf16 v[14:17], v[206:209], v[180:183], v[14:17]
	v_mfma_f32_16x16x32_bf16 v[10:13], v[214:217], v[180:183], v[10:13]
	v_mfma_f32_16x16x32_bf16 v[6:9], v[206:209], v[188:191], v[6:9]
	v_mfma_f32_16x16x32_bf16 v[2:5], v[214:217], v[188:191], v[2:5]
	s_setprio 0
	s_add_i32 s34, 0, 0x18000
	v_add_u32_e32 v156, s34, v141
	s_barrier
	ds_read_b128 v[144:147], v156
	ds_read_b128 v[148:151], v156 offset:1024
	ds_read_b128 v[152:155], v156 offset:2048
	ds_read_b128 v[156:159], v156 offset:3072
	s_add_u32 s2, s2, 0x100000
	s_addc_u32 s3, s3, 0
	s_mov_b32 m0, s72
	v_lshl_add_u64 v[200:201], s[2:3], 0, v[134:135]
	ds_read_b128 v[160:163], v143 offset:32768
	ds_read_b128 v[164:167], v143 offset:33792
	ds_read_b128 v[168:171], v143 offset:34816
	ds_read_b128 v[172:175], v143 offset:35840
	ds_read_b128 v[176:179], v143 offset:36864
	ds_read_b128 v[180:183], v143 offset:37888
	ds_read_b128 v[184:187], v143 offset:38912
	ds_read_b128 v[188:191], v143 offset:39936
	global_load_lds_dwordx4 v[200:201], off
	v_lshl_add_u64 v[200:201], s[2:3], 0, v[132:133]
	s_mov_b32 m0, s73
	s_nop 0
	global_load_lds_dwordx4 v[200:201], off
	s_waitcnt vmcnt(10)
	s_waitcnt lgkmcnt(8)
	s_barrier
	s_waitcnt lgkmcnt(0)
	s_setprio 1
	s_waitcnt lgkmcnt(0)
	v_mfma_f32_16x16x32_bf16 v[126:129], v[144:147], v[160:163], v[126:129]
	v_mfma_f32_16x16x32_bf16 v[122:125], v[152:155], v[160:163], v[122:125]
	v_mfma_f32_16x16x32_bf16 v[118:121], v[144:147], v[168:171], v[118:121]
	v_mfma_f32_16x16x32_bf16 v[114:117], v[152:155], v[168:171], v[114:117]
	v_mfma_f32_16x16x32_bf16 v[102:105], v[144:147], v[176:179], v[102:105]
	v_mfma_f32_16x16x32_bf16 v[98:101], v[152:155], v[176:179], v[98:101]
	v_mfma_f32_16x16x32_bf16 v[86:89], v[144:147], v[184:187], v[86:89]
	v_mfma_f32_16x16x32_bf16 v[82:85], v[152:155], v[184:187], v[82:85]
	v_mfma_f32_16x16x32_bf16 v[126:129], v[148:151], v[164:167], v[126:129]
	v_mfma_f32_16x16x32_bf16 v[122:125], v[156:159], v[164:167], v[122:125]
	v_mfma_f32_16x16x32_bf16 v[118:121], v[148:151], v[172:175], v[118:121]
	v_mfma_f32_16x16x32_bf16 v[114:117], v[156:159], v[172:175], v[114:117]
	v_mfma_f32_16x16x32_bf16 v[102:105], v[148:151], v[180:183], v[102:105]
	v_mfma_f32_16x16x32_bf16 v[98:101], v[156:159], v[180:183], v[98:101]
	v_mfma_f32_16x16x32_bf16 v[86:89], v[148:151], v[188:191], v[86:89]
	v_mfma_f32_16x16x32_bf16 v[82:85], v[156:159], v[188:191], v[82:85]
	s_setprio 0
	s_barrier
	s_add_i32 s35, 0, 0x1c000
	s_add_i32 s2, s34, s53
	v_add_u32_e32 v195, s35, v141
	v_lshl_add_u64 v[192:193], v[192:193], 0, s[74:75]
	s_mov_b32 m0, s2
	ds_read_b128 v[200:203], v195
	ds_read_b128 v[206:209], v195 offset:1024
	ds_read_b128 v[210:213], v195 offset:2048
	ds_read_b128 v[214:217], v195 offset:3072
	global_load_lds_dwordx4 v[192:193], off
	v_lshl_add_u64 v[192:193], v[196:197], 0, s[74:75]
	s_add_i32 m0, s2, 0x2000
	s_nop 0
	global_load_lds_dwordx4 v[192:193], off
	s_mov_b32 m0, s56
	v_lshl_add_u64 v[192:193], v[198:199], 0, s[74:75]
	global_load_lds_dwordx4 v[192:193], off
	v_lshl_add_u64 v[192:193], v[218:219], 0, s[74:75]
	s_mov_b32 m0, s57
	s_nop 0
	global_load_lds_dwordx4 v[192:193], off
	s_waitcnt vmcnt(12)
	s_barrier
	s_waitcnt lgkmcnt(0)
	s_setprio 1
	s_waitcnt lgkmcnt(0)
	v_mfma_f32_16x16x32_bf16 v[110:113], v[200:203], v[160:163], v[110:113]
	v_mfma_f32_16x16x32_bf16 v[106:109], v[210:213], v[160:163], v[106:109]
	v_mfma_f32_16x16x32_bf16 v[94:97], v[200:203], v[168:171], v[94:97]
	v_mfma_f32_16x16x32_bf16 v[90:93], v[210:213], v[168:171], v[90:93]
	v_mfma_f32_16x16x32_bf16 v[78:81], v[200:203], v[176:179], v[78:81]
	v_mfma_f32_16x16x32_bf16 v[74:77], v[210:213], v[176:179], v[74:77]
	v_mfma_f32_16x16x32_bf16 v[70:73], v[200:203], v[184:187], v[70:73]
	v_mfma_f32_16x16x32_bf16 v[66:69], v[210:213], v[184:187], v[66:69]
	v_mfma_f32_16x16x32_bf16 v[110:113], v[206:209], v[164:167], v[110:113]
	v_mfma_f32_16x16x32_bf16 v[106:109], v[214:217], v[164:167], v[106:109]
	v_mfma_f32_16x16x32_bf16 v[94:97], v[206:209], v[172:175], v[94:97]
	v_mfma_f32_16x16x32_bf16 v[90:93], v[214:217], v[172:175], v[90:93]
	v_mfma_f32_16x16x32_bf16 v[78:81], v[206:209], v[180:183], v[78:81]
	v_mfma_f32_16x16x32_bf16 v[74:77], v[214:217], v[180:183], v[74:77]
	v_mfma_f32_16x16x32_bf16 v[70:73], v[206:209], v[188:191], v[70:73]
	v_mfma_f32_16x16x32_bf16 v[66:69], v[214:217], v[188:191], v[66:69]
	s_setprio 0
	s_barrier
	ds_read_b128 v[160:163], v143 offset:49152
	ds_read_b128 v[164:167], v143 offset:50176
	ds_read_b128 v[168:171], v143 offset:51200
	ds_read_b128 v[172:175], v143 offset:52224
	ds_read_b128 v[176:179], v143 offset:53248
	ds_read_b128 v[180:183], v143 offset:54272
	ds_read_b128 v[184:187], v143 offset:55296
	ds_read_b128 v[188:191], v143 offset:56320
	s_barrier
	s_waitcnt lgkmcnt(0)
	s_setprio 1
	s_waitcnt lgkmcnt(0)
	v_mfma_f32_16x16x32_bf16 v[62:65], v[144:147], v[160:163], v[62:65]
	v_mfma_f32_16x16x32_bf16 v[58:61], v[152:155], v[160:163], v[58:61]
	v_mfma_f32_16x16x32_bf16 v[54:57], v[144:147], v[168:171], v[54:57]
	v_mfma_f32_16x16x32_bf16 v[50:53], v[152:155], v[168:171], v[50:53]
	v_mfma_f32_16x16x32_bf16 v[38:41], v[144:147], v[176:179], v[38:41]
	v_mfma_f32_16x16x32_bf16 v[34:37], v[152:155], v[176:179], v[34:37]
	v_mfma_f32_16x16x32_bf16 v[22:25], v[144:147], v[184:187], v[22:25]
	v_mfma_f32_16x16x32_bf16 v[18:21], v[152:155], v[184:187], v[18:21]
	v_mfma_f32_16x16x32_bf16 v[62:65], v[148:151], v[164:167], v[62:65]
	v_mfma_f32_16x16x32_bf16 v[58:61], v[156:159], v[164:167], v[58:61]
	v_mfma_f32_16x16x32_bf16 v[54:57], v[148:151], v[172:175], v[54:57]
	v_mfma_f32_16x16x32_bf16 v[50:53], v[156:159], v[172:175], v[50:53]
	v_mfma_f32_16x16x32_bf16 v[38:41], v[148:151], v[180:183], v[38:41]
	v_mfma_f32_16x16x32_bf16 v[34:37], v[156:159], v[180:183], v[34:37]
	v_mfma_f32_16x16x32_bf16 v[22:25], v[148:151], v[188:191], v[22:25]
	v_mfma_f32_16x16x32_bf16 v[18:21], v[156:159], v[188:191], v[18:21]
	s_setprio 0
	s_barrier
	s_add_u32 s2, s38, 0x200080
	s_addc_u32 s3, s39, 0
	s_add_i32 s34, s35, s53
	v_lshl_add_u64 v[144:145], s[2:3], 0, v[0:1]
	s_mov_b32 m0, s34
	s_nop 0
	global_load_lds_dwordx4 v[144:145], off
	v_lshl_add_u64 v[144:145], s[2:3], 0, v[130:131]
	s_add_i32 m0, s34, 0x2000
	s_nop 0
	global_load_lds_dwordx4 v[144:145], off
	s_waitcnt vmcnt(10)
	s_barrier
	s_setprio 1
	v_mfma_f32_16x16x32_bf16 v[46:49], v[200:203], v[160:163], v[46:49]
	v_mfma_f32_16x16x32_bf16 v[42:45], v[210:213], v[160:163], v[42:45]
	v_mfma_f32_16x16x32_bf16 v[30:33], v[200:203], v[168:171], v[30:33]
	v_mfma_f32_16x16x32_bf16 v[26:29], v[210:213], v[168:171], v[26:29]
	v_mfma_f32_16x16x32_bf16 v[14:17], v[200:203], v[176:179], v[14:17]
	v_mfma_f32_16x16x32_bf16 v[10:13], v[210:213], v[176:179], v[10:13]
	v_mfma_f32_16x16x32_bf16 v[6:9], v[200:203], v[184:187], v[6:9]
	v_mfma_f32_16x16x32_bf16 v[2:5], v[210:213], v[184:187], v[2:5]
	v_mfma_f32_16x16x32_bf16 v[46:49], v[206:209], v[164:167], v[46:49]
	v_mfma_f32_16x16x32_bf16 v[42:45], v[214:217], v[164:167], v[42:45]
	v_mfma_f32_16x16x32_bf16 v[30:33], v[206:209], v[172:175], v[30:33]
	v_mfma_f32_16x16x32_bf16 v[26:29], v[214:217], v[172:175], v[26:29]
	v_mfma_f32_16x16x32_bf16 v[14:17], v[206:209], v[180:183], v[14:17]
	v_mfma_f32_16x16x32_bf16 v[10:13], v[214:217], v[180:183], v[10:13]
	v_mfma_f32_16x16x32_bf16 v[6:9], v[206:209], v[188:191], v[6:9]
	v_mfma_f32_16x16x32_bf16 v[2:5], v[214:217], v[188:191], v[2:5]
	s_setprio 0
	s_add_i32 s60, s60, 2
	s_add_u32 s36, s36, 0x100
	s_addc_u32 s37, s37, 0
	s_add_u32 vcc_hi, vcc_hi, 0x100
	s_addc_u32 s50, s50, 0
	s_cmp_gt_u32 s60, 29
	s_barrier
	s_cbranch_scc0 .LBB0_442
	v_lshl_or_b32 v146, s19, 8, v142
	s_ashr_i32 s19, s18, 31
	v_lshl_add_u32 v144, s58, 8, v140
	s_lshl_b64 s[2:3], s[18:19], 21
	v_ashrrev_i32_e32 v145, 31, v144
	s_add_u32 s2, s49, s2
	v_cvt_pk_bf16_f32 v110, v110, v111
	v_cvt_pk_bf16_f32 v111, v112, v113
	v_cvt_pk_bf16_f32 v112, v106, v107
	v_or_b32_e32 v106, 16, v144
	v_cvt_pk_bf16_f32 v94, v94, v95
	v_cvt_pk_bf16_f32 v95, v96, v97
	v_cvt_pk_bf16_f32 v96, v90, v91
	v_or_b32_e32 v90, 32, v144
	v_cvt_pk_bf16_f32 v78, v78, v79
	v_cvt_pk_bf16_f32 v79, v80, v81
	v_cvt_pk_bf16_f32 v80, v74, v75
	v_or_b32_e32 v74, 48, v144
	s_addc_u32 s3, s55, s3
	v_lshlrev_b64 v[148:149], 10, v[144:145]
	v_ashrrev_i32_e32 v147, 31, v146
	v_ashrrev_i32_e32 v107, 31, v106
	v_ashrrev_i32_e32 v91, 31, v90
	v_ashrrev_i32_e32 v75, 31, v74
	v_lshl_add_u64 v[148:149], s[2:3], 0, v[148:149]
	v_lshlrev_b64 v[146:147], 1, v[146:147]
	v_lshlrev_b64 v[106:107], 10, v[106:107]
	v_lshlrev_b64 v[90:91], 10, v[90:91]
	v_lshlrev_b64 v[74:75], 10, v[74:75]
	v_lshl_add_u64 v[148:149], v[148:149], 0, v[146:147]
	v_lshl_add_u64 v[106:107], s[2:3], 0, v[106:107]
	v_lshl_add_u64 v[90:91], s[2:3], 0, v[90:91]
	v_lshl_add_u64 v[74:75], s[2:3], 0, v[74:75]
	s_mov_b64 s[2:3], 0x20000
	v_cvt_pk_bf16_f32 v70, v70, v71
	v_cvt_pk_bf16_f32 v71, v72, v73
	v_cvt_pk_bf16_f32 v72, v66, v67
	v_lshl_add_u64 v[66:67], v[148:149], 0, s[2:3]
	s_mov_b32 s2, 0x20000
	v_cvt_pk_bf16_f32 v62, v62, v63
	v_cvt_pk_bf16_f32 v63, v64, v65
	v_cvt_pk_bf16_f32 v64, v58, v59
	v_add_co_u32_e32 v58, vcc, s2, v148
	v_cvt_pk_bf16_f32 v46, v46, v47
	s_nop 0
	v_addc_co_u32_e32 v59, vcc, 0, v149, vcc
	v_cvt_pk_bf16_f32 v47, v48, v49
	v_cvt_pk_bf16_f32 v48, v42, v43
	v_cvt_pk_bf16_f32 v49, v44, v45
	s_mov_b64 s[2:3], 0x24000
	global_store_dwordx4 v[66:67], v[46:49], off offset:256
	v_cvt_pk_bf16_f32 v30, v30, v31
	v_cvt_pk_bf16_f32 v31, v32, v33
	v_lshl_add_u64 v[46:47], v[148:149], 0, s[2:3]
	v_add_co_u32_e32 v48, vcc, s63, v148
	v_cvt_pk_bf16_f32 v32, v26, v27
	v_cvt_pk_bf16_f32 v33, v28, v29
	s_mov_b64 s[2:3], 0x28000
	v_addc_co_u32_e32 v49, vcc, 0, v149, vcc
	global_store_dwordx4 v[46:47], v[30:33], off offset:256
	v_cvt_pk_bf16_f32 v14, v14, v15
	v_cvt_pk_bf16_f32 v15, v16, v17
	v_lshl_add_u64 v[30:31], v[148:149], 0, s[2:3]
	s_mov_b32 s2, 0x28000
	v_add_co_u32_e32 v32, vcc, s2, v148
	v_cvt_pk_bf16_f32 v16, v10, v11
	v_cvt_pk_bf16_f32 v17, v12, v13
	s_mov_b64 s[2:3], 0x2c000
	v_cvt_pk_bf16_f32 v113, v108, v109
	v_addc_co_u32_e32 v33, vcc, 0, v149, vcc
	global_store_dwordx4 v[30:31], v[14:17], off offset:256
	global_store_dwordx4 v[148:149], v[110:113], off offset:256
	v_cvt_pk_bf16_f32 v97, v92, v93
	v_lshl_add_u64 v[14:15], v[148:149], 0, s[2:3]
	s_mov_b32 s2, 0x2c000
	v_lshl_add_u64 v[110:111], v[106:107], 0, v[146:147]
	v_add_co_u32_e32 v16, vcc, s2, v148
	global_store_dwordx4 v[110:111], v[94:97], off offset:256
	v_cvt_pk_bf16_f32 v81, v76, v77
	v_addc_co_u32_e32 v17, vcc, 0, v149, vcc
	v_lshl_add_u64 v[94:95], v[90:91], 0, v[146:147]
	v_cvt_pk_bf16_f32 v126, v126, v127
	v_cvt_pk_bf16_f32 v127, v128, v129
	v_cvt_pk_bf16_f32 v128, v122, v123
	v_cvt_pk_bf16_f32 v129, v124, v125
	v_cvt_pk_bf16_f32 v106, v118, v119
	v_cvt_pk_bf16_f32 v107, v120, v121
	v_cvt_pk_bf16_f32 v108, v114, v115
	v_cvt_pk_bf16_f32 v109, v116, v117
	v_cvt_pk_bf16_f32 v90, v102, v103
	v_cvt_pk_bf16_f32 v91, v104, v105
	v_cvt_pk_bf16_f32 v92, v98, v99
	v_cvt_pk_bf16_f32 v93, v100, v101
	global_store_dwordx4 v[94:95], v[78:81], off offset:256
	v_cvt_pk_bf16_f32 v76, v82, v83
	v_cvt_pk_bf16_f32 v77, v84, v85
	v_lshl_add_u64 v[78:79], v[74:75], 0, v[146:147]
	v_cvt_pk_bf16_f32 v74, v86, v87
	v_cvt_pk_bf16_f32 v75, v88, v89
	v_cvt_pk_bf16_f32 v73, v68, v69
	v_cvt_pk_bf16_f32 v65, v60, v61
	v_cvt_pk_bf16_f32 v42, v54, v55
	v_cvt_pk_bf16_f32 v43, v56, v57
	v_cvt_pk_bf16_f32 v44, v50, v51
	v_cvt_pk_bf16_f32 v45, v52, v53
	v_cvt_pk_bf16_f32 v26, v38, v39
	v_cvt_pk_bf16_f32 v27, v40, v41
	v_cvt_pk_bf16_f32 v28, v34, v35
	v_cvt_pk_bf16_f32 v29, v36, v37
	v_cvt_pk_bf16_f32 v10, v22, v23
	v_cvt_pk_bf16_f32 v11, v24, v25
	v_cvt_pk_bf16_f32 v12, v18, v19
	v_cvt_pk_bf16_f32 v13, v20, v21
	v_cvt_pk_bf16_f32 v6, v6, v7
	v_cvt_pk_bf16_f32 v7, v8, v9
	v_cvt_pk_bf16_f32 v8, v2, v3
	v_cvt_pk_bf16_f32 v9, v4, v5
	s_and_b64 vcc, exec, s[12:13]
	s_mov_b32 s34, 0xc2ce8ed0
	global_store_dwordx4 v[148:149], v[126:129], off
	global_store_dwordx4 v[110:111], v[106:109], off
	global_store_dwordx4 v[94:95], v[90:93], off
	global_store_dwordx4 v[78:79], v[74:77], off
	global_store_dwordx4 v[78:79], v[70:73], off offset:256
	global_store_dwordx4 v[58:59], v[62:65], off
	global_store_dwordx4 v[48:49], v[42:45], off
	global_store_dwordx4 v[32:33], v[26:29], off
	global_store_dwordx4 v[16:17], v[10:13], off
	global_store_dwordx4 v[14:15], v[6:9], off offset:256
	s_cbranch_vccnz .LBB0_445
	s_mov_b32 s18, s6
	s_mov_b32 s19, s8
	s_mov_b32 s58, s10
	s_mov_b64 s[38:39], s[16:17]
	s_mov_b64 s[36:37], s[14:15]
	s_branch .LBB0_439

.LBB0_459:
	s_add_u32 s12, s10, 0x100
	s_addc_u32 s13, s11, 0
	s_add_i32 s34, 0, 0x10000
	v_add_u32_e32 v156, s34, v141
	ds_read_b128 v[144:147], v156
	ds_read_b128 v[148:151], v156 offset:1024
	ds_read_b128 v[152:155], v156 offset:2048
	ds_read_b128 v[156:159], v156 offset:3072
	s_cmp_eq_u32 s38, 2
	s_cselect_b32 s3, s7, s13
	s_cselect_b32 s2, s6, s12
	s_cselect_b32 s15, s9, s37
	s_cselect_b32 s14, s8, s36
	v_lshl_add_u64 v[192:193], s[10:11], 0, v[136:137]
	s_add_i32 m0, s17, 0xc000
	ds_read_b128 v[160:163], v143
	ds_read_b128 v[164:167], v143 offset:1024
	ds_read_b128 v[168:171], v143 offset:2048
	ds_read_b128 v[172:175], v143 offset:3072
	ds_read_b128 v[176:179], v143 offset:4096
	ds_read_b128 v[180:183], v143 offset:5120
	ds_read_b128 v[184:187], v143 offset:6144
	ds_read_b128 v[188:191], v143 offset:7168
	global_load_lds_dwordx4 v[192:193], off
	v_lshl_add_u64 v[192:193], s[10:11], 0, v[138:139]
	s_add_i32 m0, s17, 0xe000
	s_nop 0
	global_load_lds_dwordx4 v[192:193], off
	s_waitcnt vmcnt(10)
	s_waitcnt lgkmcnt(8)
	s_barrier
	s_waitcnt lgkmcnt(0)
	s_setprio 1
	s_waitcnt lgkmcnt(0)
	v_mfma_f32_16x16x32_bf16 v[126:129], v[144:147], v[160:163], v[126:129]
	v_mfma_f32_16x16x32_bf16 v[122:125], v[152:155], v[160:163], v[122:125]
	v_mfma_f32_16x16x32_bf16 v[118:121], v[144:147], v[168:171], v[118:121]
	v_mfma_f32_16x16x32_bf16 v[114:117], v[152:155], v[168:171], v[114:117]
	v_mfma_f32_16x16x32_bf16 v[102:105], v[144:147], v[176:179], v[102:105]
	v_mfma_f32_16x16x32_bf16 v[98:101], v[152:155], v[176:179], v[98:101]
	v_mfma_f32_16x16x32_bf16 v[86:89], v[144:147], v[184:187], v[86:89]
	v_mfma_f32_16x16x32_bf16 v[82:85], v[152:155], v[184:187], v[82:85]
	v_mfma_f32_16x16x32_bf16 v[126:129], v[148:151], v[164:167], v[126:129]
	v_mfma_f32_16x16x32_bf16 v[122:125], v[156:159], v[164:167], v[122:125]
	v_mfma_f32_16x16x32_bf16 v[118:121], v[148:151], v[172:175], v[118:121]
	v_mfma_f32_16x16x32_bf16 v[114:117], v[156:159], v[172:175], v[114:117]
	v_mfma_f32_16x16x32_bf16 v[102:105], v[148:151], v[180:183], v[102:105]
	v_mfma_f32_16x16x32_bf16 v[98:101], v[156:159], v[180:183], v[98:101]
	v_mfma_f32_16x16x32_bf16 v[86:89], v[148:151], v[188:191], v[86:89]
	v_mfma_f32_16x16x32_bf16 v[82:85], v[156:159], v[188:191], v[82:85]
	s_setprio 0
	s_barrier
	s_add_i32 s35, 0, 0x14000
	v_add_u32_e32 v192, s35, v141
	s_add_i32 s10, s34, s16
	ds_read_b128 v[200:203], v192
	ds_read_b128 v[206:209], v192 offset:1024
	ds_read_b128 v[210:213], v192 offset:2048
	ds_read_b128 v[214:217], v192 offset:3072
	v_lshl_add_u64 v[192:193], s[14:15], 0, v[0:1]
	s_mov_b32 m0, s10
	v_lshl_add_u64 v[196:197], s[14:15], 0, v[130:131]
	global_load_lds_dwordx4 v[192:193], off
	s_add_i32 m0, s10, 0x2000
	s_nop 0
	global_load_lds_dwordx4 v[196:197], off
	s_mov_b32 m0, s17
	v_lshl_add_u64 v[198:199], s[2:3], 0, v[134:135]
	global_load_lds_dwordx4 v[198:199], off
	v_lshl_add_u64 v[218:219], s[2:3], 0, v[132:133]
	s_mov_b32 m0, s18
	s_nop 0
	global_load_lds_dwordx4 v[218:219], off
	s_waitcnt vmcnt(12)
	s_barrier
	s_waitcnt lgkmcnt(0)
	s_setprio 1
	s_waitcnt lgkmcnt(0)
	v_mfma_f32_16x16x32_bf16 v[110:113], v[200:203], v[160:163], v[110:113]
	v_mfma_f32_16x16x32_bf16 v[106:109], v[210:213], v[160:163], v[106:109]
	v_mfma_f32_16x16x32_bf16 v[94:97], v[200:203], v[168:171], v[94:97]
	v_mfma_f32_16x16x32_bf16 v[90:93], v[210:213], v[168:171], v[90:93]
	v_mfma_f32_16x16x32_bf16 v[78:81], v[200:203], v[176:179], v[78:81]
	v_mfma_f32_16x16x32_bf16 v[74:77], v[210:213], v[176:179], v[74:77]
	v_mfma_f32_16x16x32_bf16 v[70:73], v[200:203], v[184:187], v[70:73]
	v_mfma_f32_16x16x32_bf16 v[66:69], v[210:213], v[184:187], v[66:69]
	v_mfma_f32_16x16x32_bf16 v[110:113], v[206:209], v[164:167], v[110:113]
	v_mfma_f32_16x16x32_bf16 v[106:109], v[214:217], v[164:167], v[106:109]
	v_mfma_f32_16x16x32_bf16 v[94:97], v[206:209], v[172:175], v[94:97]
	v_mfma_f32_16x16x32_bf16 v[90:93], v[214:217], v[172:175], v[90:93]
	v_mfma_f32_16x16x32_bf16 v[78:81], v[206:209], v[180:183], v[78:81]
	v_mfma_f32_16x16x32_bf16 v[74:77], v[214:217], v[180:183], v[74:77]
	v_mfma_f32_16x16x32_bf16 v[70:73], v[206:209], v[188:191], v[70:73]
	v_mfma_f32_16x16x32_bf16 v[66:69], v[214:217], v[188:191], v[66:69]
	s_setprio 0
	s_barrier
	ds_read_b128 v[160:163], v143 offset:16384
	ds_read_b128 v[164:167], v143 offset:17408
	ds_read_b128 v[168:171], v143 offset:18432
	ds_read_b128 v[172:175], v143 offset:19456
	ds_read_b128 v[176:179], v143 offset:20480
	ds_read_b128 v[180:183], v143 offset:21504
	ds_read_b128 v[184:187], v143 offset:22528
	ds_read_b128 v[188:191], v143 offset:23552
	s_barrier
	s_waitcnt lgkmcnt(0)
	s_setprio 1
	s_waitcnt lgkmcnt(0)
	v_mfma_f32_16x16x32_bf16 v[62:65], v[144:147], v[160:163], v[62:65]
	v_mfma_f32_16x16x32_bf16 v[58:61], v[152:155], v[160:163], v[58:61]
	v_mfma_f32_16x16x32_bf16 v[54:57], v[144:147], v[168:171], v[54:57]
	v_mfma_f32_16x16x32_bf16 v[50:53], v[152:155], v[168:171], v[50:53]
	v_mfma_f32_16x16x32_bf16 v[38:41], v[144:147], v[176:179], v[38:41]
	v_mfma_f32_16x16x32_bf16 v[34:37], v[152:155], v[176:179], v[34:37]
	v_mfma_f32_16x16x32_bf16 v[22:25], v[144:147], v[184:187], v[22:25]
	v_mfma_f32_16x16x32_bf16 v[18:21], v[152:155], v[184:187], v[18:21]
	v_mfma_f32_16x16x32_bf16 v[62:65], v[148:151], v[164:167], v[62:65]
	v_mfma_f32_16x16x32_bf16 v[58:61], v[156:159], v[164:167], v[58:61]
	v_mfma_f32_16x16x32_bf16 v[54:57], v[148:151], v[172:175], v[54:57]
	v_mfma_f32_16x16x32_bf16 v[50:53], v[156:159], v[172:175], v[50:53]
	v_mfma_f32_16x16x32_bf16 v[38:41], v[148:151], v[180:183], v[38:41]
	v_mfma_f32_16x16x32_bf16 v[34:37], v[156:159], v[180:183], v[34:37]
	v_mfma_f32_16x16x32_bf16 v[22:25], v[148:151], v[188:191], v[22:25]
	v_mfma_f32_16x16x32_bf16 v[18:21], v[156:159], v[188:191], v[18:21]
	s_setprio 0
	s_barrier
	s_add_u32 s10, s14, 0x18000
	s_addc_u32 s11, s15, 0
	s_add_i32 s34, s35, s16
	v_lshl_add_u64 v[144:145], s[10:11], 0, v[0:1]
	s_mov_b32 m0, s34
	s_nop 0
	global_load_lds_dwordx4 v[144:145], off
	v_lshl_add_u64 v[144:145], s[10:11], 0, v[130:131]
	s_add_i32 m0, s34, 0x2000
	s_nop 0
	global_load_lds_dwordx4 v[144:145], off
	s_waitcnt vmcnt(10)
	s_barrier
	s_setprio 1
	v_mfma_f32_16x16x32_bf16 v[46:49], v[200:203], v[160:163], v[46:49]
	v_mfma_f32_16x16x32_bf16 v[42:45], v[210:213], v[160:163], v[42:45]
	v_mfma_f32_16x16x32_bf16 v[30:33], v[200:203], v[168:171], v[30:33]
	v_mfma_f32_16x16x32_bf16 v[26:29], v[210:213], v[168:171], v[26:29]
	v_mfma_f32_16x16x32_bf16 v[14:17], v[200:203], v[176:179], v[14:17]
	v_mfma_f32_16x16x32_bf16 v[10:13], v[210:213], v[176:179], v[10:13]
	v_mfma_f32_16x16x32_bf16 v[6:9], v[200:203], v[184:187], v[6:9]
	v_mfma_f32_16x16x32_bf16 v[2:5], v[210:213], v[184:187], v[2:5]
	v_mfma_f32_16x16x32_bf16 v[46:49], v[206:209], v[164:167], v[46:49]
	v_mfma_f32_16x16x32_bf16 v[42:45], v[214:217], v[164:167], v[42:45]
	v_mfma_f32_16x16x32_bf16 v[30:33], v[206:209], v[172:175], v[30:33]
	v_mfma_f32_16x16x32_bf16 v[26:29], v[214:217], v[172:175], v[26:29]
	v_mfma_f32_16x16x32_bf16 v[14:17], v[206:209], v[180:183], v[14:17]
	v_mfma_f32_16x16x32_bf16 v[10:13], v[214:217], v[180:183], v[10:13]
	v_mfma_f32_16x16x32_bf16 v[6:9], v[206:209], v[188:191], v[6:9]
	v_mfma_f32_16x16x32_bf16 v[2:5], v[214:217], v[188:191], v[2:5]
	s_setprio 0
	s_add_i32 s10, 0, 0x18000
	v_add_u32_e32 v156, s10, v141
	s_barrier
	ds_read_b128 v[144:147], v156
	ds_read_b128 v[148:151], v156 offset:1024
	ds_read_b128 v[152:155], v156 offset:2048
	ds_read_b128 v[156:159], v156 offset:3072
	s_add_u32 s2, s2, 0x18000
	s_addc_u32 s3, s3, 0
	s_mov_b32 m0, s19
	v_lshl_add_u64 v[200:201], s[2:3], 0, v[134:135]
	ds_read_b128 v[160:163], v143 offset:32768
	ds_read_b128 v[164:167], v143 offset:33792
	ds_read_b128 v[168:171], v143 offset:34816
	ds_read_b128 v[172:175], v143 offset:35840
	ds_read_b128 v[176:179], v143 offset:36864
	ds_read_b128 v[180:183], v143 offset:37888
	ds_read_b128 v[184:187], v143 offset:38912
	ds_read_b128 v[188:191], v143 offset:39936
	global_load_lds_dwordx4 v[200:201], off
	v_lshl_add_u64 v[200:201], s[2:3], 0, v[132:133]
	s_mov_b32 m0, s44
	s_nop 0
	global_load_lds_dwordx4 v[200:201], off
	s_waitcnt vmcnt(10)
	s_waitcnt lgkmcnt(8)
	s_barrier
	s_waitcnt lgkmcnt(0)
	s_setprio 1
	s_waitcnt lgkmcnt(0)
	v_mfma_f32_16x16x32_bf16 v[126:129], v[144:147], v[160:163], v[126:129]
	v_mfma_f32_16x16x32_bf16 v[122:125], v[152:155], v[160:163], v[122:125]
	v_mfma_f32_16x16x32_bf16 v[118:121], v[144:147], v[168:171], v[118:121]
	v_mfma_f32_16x16x32_bf16 v[114:117], v[152:155], v[168:171], v[114:117]
	v_mfma_f32_16x16x32_bf16 v[102:105], v[144:147], v[176:179], v[102:105]
	v_mfma_f32_16x16x32_bf16 v[98:101], v[152:155], v[176:179], v[98:101]
	v_mfma_f32_16x16x32_bf16 v[86:89], v[144:147], v[184:187], v[86:89]
	v_mfma_f32_16x16x32_bf16 v[82:85], v[152:155], v[184:187], v[82:85]
	v_mfma_f32_16x16x32_bf16 v[126:129], v[148:151], v[164:167], v[126:129]
	v_mfma_f32_16x16x32_bf16 v[122:125], v[156:159], v[164:167], v[122:125]
	v_mfma_f32_16x16x32_bf16 v[118:121], v[148:151], v[172:175], v[118:121]
	v_mfma_f32_16x16x32_bf16 v[114:117], v[156:159], v[172:175], v[114:117]
	v_mfma_f32_16x16x32_bf16 v[102:105], v[148:151], v[180:183], v[102:105]
	v_mfma_f32_16x16x32_bf16 v[98:101], v[156:159], v[180:183], v[98:101]
	v_mfma_f32_16x16x32_bf16 v[86:89], v[148:151], v[188:191], v[86:89]
	v_mfma_f32_16x16x32_bf16 v[82:85], v[156:159], v[188:191], v[82:85]
	s_setprio 0
	s_barrier
	s_add_i32 s11, 0, 0x1c000
	s_add_i32 s2, s10, s16
	v_add_u32_e32 v195, s11, v141
	v_lshl_add_u64 v[192:193], v[192:193], 0, s[74:75]
	s_mov_b32 m0, s2
	ds_read_b128 v[200:203], v195
	ds_read_b128 v[206:209], v195 offset:1024
	ds_read_b128 v[210:213], v195 offset:2048
	ds_read_b128 v[214:217], v195 offset:3072
	global_load_lds_dwordx4 v[192:193], off
	v_lshl_add_u64 v[192:193], v[196:197], 0, s[74:75]
	s_add_i32 m0, s2, 0x2000
	s_nop 0
	global_load_lds_dwordx4 v[192:193], off
	s_mov_b32 m0, s45
	v_lshl_add_u64 v[192:193], v[198:199], 0, s[74:75]
	global_load_lds_dwordx4 v[192:193], off
	v_lshl_add_u64 v[192:193], v[218:219], 0, s[74:75]
	s_mov_b32 m0, s49
	s_nop 0
	global_load_lds_dwordx4 v[192:193], off
	s_waitcnt vmcnt(12)
	s_barrier
	s_waitcnt lgkmcnt(0)
	s_setprio 1
	s_waitcnt lgkmcnt(0)
	v_mfma_f32_16x16x32_bf16 v[110:113], v[200:203], v[160:163], v[110:113]
	v_mfma_f32_16x16x32_bf16 v[106:109], v[210:213], v[160:163], v[106:109]
	v_mfma_f32_16x16x32_bf16 v[94:97], v[200:203], v[168:171], v[94:97]
	v_mfma_f32_16x16x32_bf16 v[90:93], v[210:213], v[168:171], v[90:93]
	v_mfma_f32_16x16x32_bf16 v[78:81], v[200:203], v[176:179], v[78:81]
	v_mfma_f32_16x16x32_bf16 v[74:77], v[210:213], v[176:179], v[74:77]
	v_mfma_f32_16x16x32_bf16 v[70:73], v[200:203], v[184:187], v[70:73]
	v_mfma_f32_16x16x32_bf16 v[66:69], v[210:213], v[184:187], v[66:69]
	v_mfma_f32_16x16x32_bf16 v[110:113], v[206:209], v[164:167], v[110:113]
	v_mfma_f32_16x16x32_bf16 v[106:109], v[214:217], v[164:167], v[106:109]
	v_mfma_f32_16x16x32_bf16 v[94:97], v[206:209], v[172:175], v[94:97]
	v_mfma_f32_16x16x32_bf16 v[90:93], v[214:217], v[172:175], v[90:93]
	v_mfma_f32_16x16x32_bf16 v[78:81], v[206:209], v[180:183], v[78:81]
	v_mfma_f32_16x16x32_bf16 v[74:77], v[214:217], v[180:183], v[74:77]
	v_mfma_f32_16x16x32_bf16 v[70:73], v[206:209], v[188:191], v[70:73]
	v_mfma_f32_16x16x32_bf16 v[66:69], v[214:217], v[188:191], v[66:69]
	s_setprio 0
	s_barrier
	ds_read_b128 v[160:163], v143 offset:49152
	ds_read_b128 v[164:167], v143 offset:50176
	ds_read_b128 v[168:171], v143 offset:51200
	ds_read_b128 v[172:175], v143 offset:52224
	ds_read_b128 v[176:179], v143 offset:53248
	ds_read_b128 v[180:183], v143 offset:54272
	ds_read_b128 v[184:187], v143 offset:55296
	ds_read_b128 v[188:191], v143 offset:56320
	s_barrier
	s_waitcnt lgkmcnt(0)
	s_setprio 1
	s_waitcnt lgkmcnt(0)
	v_mfma_f32_16x16x32_bf16 v[62:65], v[144:147], v[160:163], v[62:65]
	v_mfma_f32_16x16x32_bf16 v[58:61], v[152:155], v[160:163], v[58:61]
	v_mfma_f32_16x16x32_bf16 v[54:57], v[144:147], v[168:171], v[54:57]
	v_mfma_f32_16x16x32_bf16 v[50:53], v[152:155], v[168:171], v[50:53]
	v_mfma_f32_16x16x32_bf16 v[38:41], v[144:147], v[176:179], v[38:41]
	v_mfma_f32_16x16x32_bf16 v[34:37], v[152:155], v[176:179], v[34:37]
	v_mfma_f32_16x16x32_bf16 v[22:25], v[144:147], v[184:187], v[22:25]
	v_mfma_f32_16x16x32_bf16 v[18:21], v[152:155], v[184:187], v[18:21]
	v_mfma_f32_16x16x32_bf16 v[62:65], v[148:151], v[164:167], v[62:65]
	v_mfma_f32_16x16x32_bf16 v[58:61], v[156:159], v[164:167], v[58:61]
	v_mfma_f32_16x16x32_bf16 v[54:57], v[148:151], v[172:175], v[54:57]
	v_mfma_f32_16x16x32_bf16 v[50:53], v[156:159], v[172:175], v[50:53]
	v_mfma_f32_16x16x32_bf16 v[38:41], v[148:151], v[180:183], v[38:41]
	v_mfma_f32_16x16x32_bf16 v[34:37], v[156:159], v[180:183], v[34:37]
	v_mfma_f32_16x16x32_bf16 v[22:25], v[148:151], v[188:191], v[22:25]
	v_mfma_f32_16x16x32_bf16 v[18:21], v[156:159], v[188:191], v[18:21]
	s_setprio 0
	s_barrier
	s_add_u32 s2, s14, 0x18080
	s_addc_u32 s3, s15, 0
	s_add_i32 s10, s11, s16
	v_lshl_add_u64 v[144:145], s[2:3], 0, v[0:1]
	s_mov_b32 m0, s10
	s_nop 0
	global_load_lds_dwordx4 v[144:145], off
	v_lshl_add_u64 v[144:145], s[2:3], 0, v[130:131]
	s_add_i32 m0, s10, 0x2000
	s_nop 0
	global_load_lds_dwordx4 v[144:145], off
	s_waitcnt vmcnt(10)
	s_barrier
	s_setprio 1
	v_mfma_f32_16x16x32_bf16 v[46:49], v[200:203], v[160:163], v[46:49]
	v_mfma_f32_16x16x32_bf16 v[42:45], v[210:213], v[160:163], v[42:45]
	v_mfma_f32_16x16x32_bf16 v[30:33], v[200:203], v[168:171], v[30:33]
	v_mfma_f32_16x16x32_bf16 v[26:29], v[210:213], v[168:171], v[26:29]
	v_mfma_f32_16x16x32_bf16 v[14:17], v[200:203], v[176:179], v[14:17]
	v_mfma_f32_16x16x32_bf16 v[10:13], v[210:213], v[176:179], v[10:13]
	v_mfma_f32_16x16x32_bf16 v[6:9], v[200:203], v[184:187], v[6:9]
	v_mfma_f32_16x16x32_bf16 v[2:5], v[210:213], v[184:187], v[2:5]
	v_mfma_f32_16x16x32_bf16 v[46:49], v[206:209], v[164:167], v[46:49]
	v_mfma_f32_16x16x32_bf16 v[42:45], v[214:217], v[164:167], v[42:45]
	v_mfma_f32_16x16x32_bf16 v[30:33], v[206:209], v[172:175], v[30:33]
	v_mfma_f32_16x16x32_bf16 v[26:29], v[214:217], v[172:175], v[26:29]
	v_mfma_f32_16x16x32_bf16 v[14:17], v[206:209], v[180:183], v[14:17]
	v_mfma_f32_16x16x32_bf16 v[10:13], v[214:217], v[180:183], v[10:13]
	v_mfma_f32_16x16x32_bf16 v[6:9], v[206:209], v[188:191], v[6:9]
	v_mfma_f32_16x16x32_bf16 v[2:5], v[214:217], v[188:191], v[2:5]
	s_setprio 0
	s_add_i32 s38, s38, 2
	s_add_u32 s36, s36, 0x100
	s_addc_u32 s37, s37, 0
	s_cmp_gt_u32 s38, 3
	s_mov_b64 s[10:11], s[12:13]
	s_barrier
	s_cbranch_scc0 .LBB0_459
	v_readlane_b32 s2, v250, 0
	v_lshl_add_u32 v150, s55, 8, v140
	v_lshl_or_b32 v144, s54, 8, v142
	v_readlane_b32 s3, v250, 1
	v_ashrrev_i32_e32 v145, 31, v144
	v_cvt_pk_bf16_f32 v70, v70, v71
	v_mov_b64_e32 v[146:147], s[2:3]
	v_cvt_pk_bf16_f32 v71, v72, v73
	v_cvt_pk_bf16_f32 v72, v66, v67
	v_add_u32_e32 v66, 0x80, v150
	v_mad_i64_i32 v[148:149], s[2:3], v150, s48, v[146:147]
	v_lshlrev_b64 v[144:145], 1, v[144:145]
	v_cvt_pk_bf16_f32 v110, v110, v111
	v_cvt_pk_bf16_f32 v111, v112, v113
	v_cvt_pk_bf16_f32 v112, v106, v107
	v_or_b32_e32 v106, 16, v150
	v_mad_i64_i32 v[66:67], s[2:3], v66, s48, v[146:147]
	v_cvt_pk_bf16_f32 v46, v46, v47
	v_cvt_pk_bf16_f32 v47, v48, v49
	v_cvt_pk_bf16_f32 v48, v42, v43
	v_add_u32_e32 v42, 0x90, v150
	v_lshl_add_u64 v[148:149], v[148:149], 0, v[144:145]
	v_cvt_pk_bf16_f32 v113, v108, v109
	v_mad_i64_i32 v[106:107], s[2:3], v106, s48, v[146:147]
	v_cvt_pk_bf16_f32 v94, v94, v95
	v_cvt_pk_bf16_f32 v95, v96, v97
	v_cvt_pk_bf16_f32 v96, v90, v91
	v_or_b32_e32 v90, 32, v150
	v_lshl_add_u64 v[66:67], v[66:67], 0, v[144:145]
	v_cvt_pk_bf16_f32 v49, v44, v45
	v_mad_i64_i32 v[42:43], s[2:3], v42, s48, v[146:147]
	v_cvt_pk_bf16_f32 v30, v30, v31
	v_cvt_pk_bf16_f32 v31, v32, v33
	v_cvt_pk_bf16_f32 v32, v26, v27
	v_add_u32_e32 v26, 0xa0, v150
	global_store_dwordx4 v[148:149], v[110:113], off offset:256
	v_cvt_pk_bf16_f32 v97, v92, v93
	v_mad_i64_i32 v[90:91], s[2:3], v90, s48, v[146:147]
	v_lshl_add_u64 v[110:111], v[106:107], 0, v[144:145]
	v_cvt_pk_bf16_f32 v78, v78, v79
	v_cvt_pk_bf16_f32 v79, v80, v81
	v_cvt_pk_bf16_f32 v80, v74, v75
	v_or_b32_e32 v74, 48, v150
	global_store_dwordx4 v[66:67], v[46:49], off offset:256
	v_cvt_pk_bf16_f32 v33, v28, v29
	v_mad_i64_i32 v[26:27], s[2:3], v26, s48, v[146:147]
	v_lshl_add_u64 v[46:47], v[42:43], 0, v[144:145]
	v_cvt_pk_bf16_f32 v14, v14, v15
	v_cvt_pk_bf16_f32 v15, v16, v17
	v_cvt_pk_bf16_f32 v16, v10, v11
	v_add_u32_e32 v10, 0xb0, v150
	global_store_dwordx4 v[110:111], v[94:97], off offset:256
	v_cvt_pk_bf16_f32 v81, v76, v77
	v_mad_i64_i32 v[74:75], s[2:3], v74, s48, v[146:147]
	v_lshl_add_u64 v[94:95], v[90:91], 0, v[144:145]
	global_store_dwordx4 v[46:47], v[30:33], off offset:256
	v_cvt_pk_bf16_f32 v17, v12, v13
	v_mad_i64_i32 v[10:11], s[2:3], v10, s48, v[146:147]
	v_lshl_add_u64 v[30:31], v[26:27], 0, v[144:145]
	v_cvt_pk_bf16_f32 v126, v126, v127
	v_cvt_pk_bf16_f32 v127, v128, v129
	v_cvt_pk_bf16_f32 v128, v122, v123
	v_cvt_pk_bf16_f32 v129, v124, v125
	v_cvt_pk_bf16_f32 v106, v118, v119
	v_cvt_pk_bf16_f32 v107, v120, v121
	v_cvt_pk_bf16_f32 v108, v114, v115
	v_cvt_pk_bf16_f32 v109, v116, v117
	v_cvt_pk_bf16_f32 v90, v102, v103
	v_cvt_pk_bf16_f32 v91, v104, v105
	v_cvt_pk_bf16_f32 v92, v98, v99
	v_cvt_pk_bf16_f32 v93, v100, v101
	global_store_dwordx4 v[94:95], v[78:81], off offset:256
	v_cvt_pk_bf16_f32 v76, v82, v83
	v_cvt_pk_bf16_f32 v77, v84, v85
	v_lshl_add_u64 v[78:79], v[74:75], 0, v[144:145]
	v_cvt_pk_bf16_f32 v74, v86, v87
	v_cvt_pk_bf16_f32 v75, v88, v89
	v_cvt_pk_bf16_f32 v73, v68, v69
	v_cvt_pk_bf16_f32 v62, v62, v63
	v_cvt_pk_bf16_f32 v63, v64, v65
	v_cvt_pk_bf16_f32 v64, v58, v59
	v_cvt_pk_bf16_f32 v65, v60, v61
	v_cvt_pk_bf16_f32 v42, v54, v55
	v_cvt_pk_bf16_f32 v43, v56, v57
	v_cvt_pk_bf16_f32 v44, v50, v51
	v_cvt_pk_bf16_f32 v45, v52, v53
	v_cvt_pk_bf16_f32 v26, v38, v39
	v_cvt_pk_bf16_f32 v27, v40, v41
	v_cvt_pk_bf16_f32 v28, v34, v35
	v_cvt_pk_bf16_f32 v29, v36, v37
	global_store_dwordx4 v[30:31], v[14:17], off offset:256
	v_cvt_pk_bf16_f32 v12, v18, v19
	v_cvt_pk_bf16_f32 v13, v20, v21
	v_lshl_add_u64 v[14:15], v[10:11], 0, v[144:145]
	v_cvt_pk_bf16_f32 v10, v22, v23
	v_cvt_pk_bf16_f32 v11, v24, v25
	v_cvt_pk_bf16_f32 v6, v6, v7
	v_cvt_pk_bf16_f32 v7, v8, v9
	v_cvt_pk_bf16_f32 v8, v2, v3
	v_cvt_pk_bf16_f32 v9, v4, v5
	s_and_b64 vcc, exec, s[0:1]
	s_mov_b32 s54, s52
	s_mov_b32 s55, s53
	s_mov_b64 s[2:3], s[8:9]
	s_mov_b64 s[10:11], s[6:7]
	s_mov_b32 s35, 0x3fb8aa3b
	s_mov_b32 s34, 0xc2ce8ed0
	global_store_dwordx4 v[148:149], v[126:129], off
	global_store_dwordx4 v[110:111], v[106:109], off
	global_store_dwordx4 v[94:95], v[90:93], off
	global_store_dwordx4 v[78:79], v[74:77], off
	global_store_dwordx4 v[78:79], v[70:73], off offset:256
	global_store_dwordx4 v[66:67], v[62:65], off
	global_store_dwordx4 v[46:47], v[42:45], off
	global_store_dwordx4 v[30:31], v[26:29], off
	global_store_dwordx4 v[14:15], v[10:13], off
	global_store_dwordx4 v[14:15], v[6:9], off offset:256
	s_cbranch_vccz .LBB0_452
	s_waitcnt vmcnt(0)
	s_cmpk_gt_u32 s5, 0xff
	s_cbranch_scc1 .LBB0_463
	s_barrier

.LBB0_471:
	s_add_u32 s38, s16, s2
	s_addc_u32 s39, s17, 0
	s_add_u32 s3, s38, 0x100
	s_addc_u32 s40, s39, 0
	s_and_b64 s[34:35], s[36:37], exec
	s_cselect_b32 vcc_hi, s9, s40
	s_cselect_b32 vcc_lo, s58, s3
	s_add_u32 s2, s14, s2
	s_addc_u32 s3, s15, 0
	s_add_u32 s34, s2, 0x100
	s_addc_u32 s35, s3, 0
	s_add_i32 s71, 0, 0x10000
	s_and_b64 s[2:3], s[36:37], exec
	s_cselect_b32 s73, s7, s35
	s_cselect_b32 s72, s5, s34
	s_add_u32 s2, s38, 0x10080
	s_addc_u32 s3, s39, 0
	s_add_i32 s41, s71, s51
	s_add_i32 m0, s42, 0xc000
	s_add_i32 s49, s42, 0xe000
	s_add_i32 s65, 0, 0x14000
	s_add_i32 s35, s41, 0x2000
	s_add_u32 s44, s72, 0x10000
	v_add_u32_e32 v152, s71, v137
	s_addc_u32 s45, s73, 0
	s_add_i32 s64, s65, s51
	ds_read_b128 v[140:143], v152
	ds_read_b128 v[144:147], v152 offset:1024
	ds_read_b128 v[148:151], v152 offset:2048
	ds_read_b128 v[152:155], v152 offset:3072
	s_add_i32 s40, s64, 0x2000
	s_add_i32 s97, 0, 0x18000
	s_add_u32 s38, vcc_lo, 0x10000
	s_addc_u32 s39, vcc_hi, 0
	s_add_i32 s50, s97, s51
	s_add_i32 s60, 0, 0x1c000
	s_add_i32 s96, s50, 0x2000
	s_add_u32 s36, s72, 0x10080
	s_addc_u32 s37, s73, 0
	s_add_i32 s71, s60, s51
	s_add_i32 s34, s71, 0x2000
	v_lshl_add_u64 v[188:189], s[2:3], 0, v[134:135]
	ds_read_b128 v[156:159], v139
	ds_read_b128 v[160:163], v139 offset:1024
	ds_read_b128 v[164:167], v139 offset:2048
	ds_read_b128 v[168:171], v139 offset:3072
	ds_read_b128 v[172:175], v139 offset:4096
	ds_read_b128 v[176:179], v139 offset:5120
	ds_read_b128 v[180:183], v139 offset:6144
	ds_read_b128 v[184:187], v139 offset:7168
	global_load_lds_dwordx4 v[188:189], off
	v_lshl_add_u64 v[188:189], s[2:3], 0, v[132:133]
	s_mov_b32 m0, s49
	s_nop 0
	global_load_lds_dwordx4 v[188:189], off
	s_waitcnt vmcnt(10)
	s_waitcnt lgkmcnt(8)
	s_barrier
	s_waitcnt lgkmcnt(0)
	s_setprio 1
	s_waitcnt lgkmcnt(0)
	v_mfma_f32_16x16x32_bf16 v[126:129], v[140:143], v[156:159], v[126:129]
	v_mfma_f32_16x16x32_bf16 v[122:125], v[148:151], v[156:159], v[122:125]
	v_mfma_f32_16x16x32_bf16 v[118:121], v[140:143], v[164:167], v[118:121]
	v_mfma_f32_16x16x32_bf16 v[114:117], v[148:151], v[164:167], v[114:117]
	v_mfma_f32_16x16x32_bf16 v[102:105], v[140:143], v[172:175], v[102:105]
	v_mfma_f32_16x16x32_bf16 v[98:101], v[148:151], v[172:175], v[98:101]
	v_mfma_f32_16x16x32_bf16 v[86:89], v[140:143], v[180:183], v[86:89]
	v_mfma_f32_16x16x32_bf16 v[82:85], v[148:151], v[180:183], v[82:85]
	v_mfma_f32_16x16x32_bf16 v[126:129], v[144:147], v[160:163], v[126:129]
	v_mfma_f32_16x16x32_bf16 v[122:125], v[152:155], v[160:163], v[122:125]
	v_mfma_f32_16x16x32_bf16 v[118:121], v[144:147], v[168:171], v[118:121]
	v_mfma_f32_16x16x32_bf16 v[114:117], v[152:155], v[168:171], v[114:117]
	v_mfma_f32_16x16x32_bf16 v[102:105], v[144:147], v[176:179], v[102:105]
	v_mfma_f32_16x16x32_bf16 v[98:101], v[152:155], v[176:179], v[98:101]
	v_mfma_f32_16x16x32_bf16 v[86:89], v[144:147], v[184:187], v[86:89]
	v_mfma_f32_16x16x32_bf16 v[82:85], v[152:155], v[184:187], v[82:85]
	s_setprio 0
	s_barrier
	v_add_u32_e32 v192, s65, v137
	s_mov_b32 m0, s41
	ds_read_b128 v[188:191], v192
	ds_read_b128 v[200:203], v192 offset:1024
	ds_read_b128 v[206:209], v192 offset:2048
	ds_read_b128 v[210:213], v192 offset:3072
	v_lshl_add_u64 v[192:193], s[72:73], 0, v[0:1]
	global_load_lds_dwordx4 v[192:193], off
	v_lshl_add_u64 v[196:197], s[72:73], 0, v[130:131]
	s_mov_b32 m0, s35
	s_nop 0
	global_load_lds_dwordx4 v[196:197], off
	s_mov_b32 m0, s42
	v_lshl_add_u64 v[198:199], vcc, 0, v[134:135]
	global_load_lds_dwordx4 v[198:199], off
	v_lshl_add_u64 v[214:215], vcc, 0, v[132:133]
	s_mov_b32 m0, s52
	s_nop 0
	global_load_lds_dwordx4 v[214:215], off
	s_waitcnt vmcnt(12)
	s_barrier
	s_waitcnt lgkmcnt(0)
	s_setprio 1
	s_waitcnt lgkmcnt(0)
	v_mfma_f32_16x16x32_bf16 v[110:113], v[188:191], v[156:159], v[110:113]
	v_mfma_f32_16x16x32_bf16 v[106:109], v[206:209], v[156:159], v[106:109]
	v_mfma_f32_16x16x32_bf16 v[94:97], v[188:191], v[164:167], v[94:97]
	v_mfma_f32_16x16x32_bf16 v[90:93], v[206:209], v[164:167], v[90:93]
	v_mfma_f32_16x16x32_bf16 v[78:81], v[188:191], v[172:175], v[78:81]
	v_mfma_f32_16x16x32_bf16 v[74:77], v[206:209], v[172:175], v[74:77]
	v_mfma_f32_16x16x32_bf16 v[70:73], v[188:191], v[180:183], v[70:73]
	v_mfma_f32_16x16x32_bf16 v[66:69], v[206:209], v[180:183], v[66:69]
	v_mfma_f32_16x16x32_bf16 v[110:113], v[200:203], v[160:163], v[110:113]
	v_mfma_f32_16x16x32_bf16 v[106:109], v[210:213], v[160:163], v[106:109]
	v_mfma_f32_16x16x32_bf16 v[94:97], v[200:203], v[168:171], v[94:97]
	v_mfma_f32_16x16x32_bf16 v[90:93], v[210:213], v[168:171], v[90:93]
	v_mfma_f32_16x16x32_bf16 v[78:81], v[200:203], v[176:179], v[78:81]
	v_mfma_f32_16x16x32_bf16 v[74:77], v[210:213], v[176:179], v[74:77]
	v_mfma_f32_16x16x32_bf16 v[70:73], v[200:203], v[184:187], v[70:73]
	v_mfma_f32_16x16x32_bf16 v[66:69], v[210:213], v[184:187], v[66:69]
	s_setprio 0
	s_barrier
	ds_read_b128 v[156:159], v139 offset:16384
	ds_read_b128 v[160:163], v139 offset:17408
	ds_read_b128 v[164:167], v139 offset:18432
	ds_read_b128 v[168:171], v139 offset:19456
	ds_read_b128 v[172:175], v139 offset:20480
	ds_read_b128 v[176:179], v139 offset:21504
	ds_read_b128 v[180:183], v139 offset:22528
	ds_read_b128 v[184:187], v139 offset:23552
	s_barrier
	s_waitcnt lgkmcnt(0)
	s_setprio 1
	s_waitcnt lgkmcnt(0)
	v_mfma_f32_16x16x32_bf16 v[62:65], v[140:143], v[156:159], v[62:65]
	v_mfma_f32_16x16x32_bf16 v[58:61], v[148:151], v[156:159], v[58:61]
	v_mfma_f32_16x16x32_bf16 v[54:57], v[140:143], v[164:167], v[54:57]
	v_mfma_f32_16x16x32_bf16 v[50:53], v[148:151], v[164:167], v[50:53]
	v_mfma_f32_16x16x32_bf16 v[38:41], v[140:143], v[172:175], v[38:41]
	v_mfma_f32_16x16x32_bf16 v[34:37], v[148:151], v[172:175], v[34:37]
	v_mfma_f32_16x16x32_bf16 v[22:25], v[140:143], v[180:183], v[22:25]
	v_mfma_f32_16x16x32_bf16 v[18:21], v[148:151], v[180:183], v[18:21]
	v_mfma_f32_16x16x32_bf16 v[62:65], v[144:147], v[160:163], v[62:65]
	v_mfma_f32_16x16x32_bf16 v[58:61], v[152:155], v[160:163], v[58:61]
	v_mfma_f32_16x16x32_bf16 v[54:57], v[144:147], v[168:171], v[54:57]
	v_mfma_f32_16x16x32_bf16 v[50:53], v[152:155], v[168:171], v[50:53]
	v_mfma_f32_16x16x32_bf16 v[38:41], v[144:147], v[176:179], v[38:41]
	v_mfma_f32_16x16x32_bf16 v[34:37], v[152:155], v[176:179], v[34:37]
	v_mfma_f32_16x16x32_bf16 v[22:25], v[144:147], v[184:187], v[22:25]
	v_mfma_f32_16x16x32_bf16 v[18:21], v[152:155], v[184:187], v[18:21]
	s_setprio 0
	s_barrier
	s_mov_b32 m0, s64
	v_lshl_add_u64 v[140:141], s[44:45], 0, v[0:1]
	global_load_lds_dwordx4 v[140:141], off
	v_lshl_add_u64 v[140:141], s[44:45], 0, v[130:131]
	s_mov_b32 m0, s40
	s_nop 0
	global_load_lds_dwordx4 v[140:141], off
	s_waitcnt vmcnt(10)
	s_barrier
	s_setprio 1
	v_mfma_f32_16x16x32_bf16 v[46:49], v[188:191], v[156:159], v[46:49]
	v_mfma_f32_16x16x32_bf16 v[42:45], v[206:209], v[156:159], v[42:45]
	v_mfma_f32_16x16x32_bf16 v[30:33], v[188:191], v[164:167], v[30:33]
	v_mfma_f32_16x16x32_bf16 v[26:29], v[206:209], v[164:167], v[26:29]
	v_mfma_f32_16x16x32_bf16 v[14:17], v[188:191], v[172:175], v[14:17]
	v_mfma_f32_16x16x32_bf16 v[10:13], v[206:209], v[172:175], v[10:13]
	v_mfma_f32_16x16x32_bf16 v[6:9], v[188:191], v[180:183], v[6:9]
	v_mfma_f32_16x16x32_bf16 v[2:5], v[206:209], v[180:183], v[2:5]
	v_mfma_f32_16x16x32_bf16 v[46:49], v[200:203], v[160:163], v[46:49]
	v_mfma_f32_16x16x32_bf16 v[42:45], v[210:213], v[160:163], v[42:45]
	v_mfma_f32_16x16x32_bf16 v[30:33], v[200:203], v[168:171], v[30:33]
	v_mfma_f32_16x16x32_bf16 v[26:29], v[210:213], v[168:171], v[26:29]
	v_mfma_f32_16x16x32_bf16 v[14:17], v[200:203], v[176:179], v[14:17]
	v_mfma_f32_16x16x32_bf16 v[10:13], v[210:213], v[176:179], v[10:13]
	v_mfma_f32_16x16x32_bf16 v[6:9], v[200:203], v[184:187], v[6:9]
	v_mfma_f32_16x16x32_bf16 v[2:5], v[210:213], v[184:187], v[2:5]
	s_setprio 0
	v_add_u32_e32 v152, s97, v137
	s_barrier
	ds_read_b128 v[140:143], v152
	ds_read_b128 v[144:147], v152 offset:1024
	ds_read_b128 v[148:151], v152 offset:2048
	ds_read_b128 v[152:155], v152 offset:3072
	s_mov_b32 m0, s53
	v_lshl_add_u64 v[188:189], s[38:39], 0, v[134:135]
	ds_read_b128 v[156:159], v139 offset:32768
	ds_read_b128 v[160:163], v139 offset:33792
	ds_read_b128 v[164:167], v139 offset:34816
	ds_read_b128 v[168:171], v139 offset:35840
	ds_read_b128 v[172:175], v139 offset:36864
	ds_read_b128 v[176:179], v139 offset:37888
	ds_read_b128 v[180:183], v139 offset:38912
	ds_read_b128 v[184:187], v139 offset:39936
	global_load_lds_dwordx4 v[188:189], off
	v_lshl_add_u64 v[188:189], s[38:39], 0, v[132:133]
	s_mov_b32 m0, s54
	s_nop 0
	global_load_lds_dwordx4 v[188:189], off
	s_waitcnt vmcnt(10)
	s_waitcnt lgkmcnt(8)
	s_barrier
	s_waitcnt lgkmcnt(0)
	s_setprio 1
	s_waitcnt lgkmcnt(0)
	v_mfma_f32_16x16x32_bf16 v[126:129], v[140:143], v[156:159], v[126:129]
	v_mfma_f32_16x16x32_bf16 v[122:125], v[148:151], v[156:159], v[122:125]
	v_mfma_f32_16x16x32_bf16 v[118:121], v[140:143], v[164:167], v[118:121]
	v_mfma_f32_16x16x32_bf16 v[114:117], v[148:151], v[164:167], v[114:117]
	v_mfma_f32_16x16x32_bf16 v[102:105], v[140:143], v[172:175], v[102:105]
	v_mfma_f32_16x16x32_bf16 v[98:101], v[148:151], v[172:175], v[98:101]
	v_mfma_f32_16x16x32_bf16 v[86:89], v[140:143], v[180:183], v[86:89]
	v_mfma_f32_16x16x32_bf16 v[82:85], v[148:151], v[180:183], v[82:85]
	v_mfma_f32_16x16x32_bf16 v[126:129], v[144:147], v[160:163], v[126:129]
	v_mfma_f32_16x16x32_bf16 v[122:125], v[152:155], v[160:163], v[122:125]
	v_mfma_f32_16x16x32_bf16 v[118:121], v[144:147], v[168:171], v[118:121]
	v_mfma_f32_16x16x32_bf16 v[114:117], v[152:155], v[168:171], v[114:117]
	v_mfma_f32_16x16x32_bf16 v[102:105], v[144:147], v[176:179], v[102:105]
	v_mfma_f32_16x16x32_bf16 v[98:101], v[152:155], v[176:179], v[98:101]
	v_mfma_f32_16x16x32_bf16 v[86:89], v[144:147], v[184:187], v[86:89]
	v_mfma_f32_16x16x32_bf16 v[82:85], v[152:155], v[184:187], v[82:85]
	s_setprio 0
	s_barrier
	s_mov_b32 m0, s50
	v_add_u32_e32 v195, s60, v137
	v_lshl_add_u64 v[192:193], v[192:193], 0, s[74:75]
	ds_read_b128 v[188:191], v195
	ds_read_b128 v[200:203], v195 offset:1024
	ds_read_b128 v[206:209], v195 offset:2048
	ds_read_b128 v[210:213], v195 offset:3072
	global_load_lds_dwordx4 v[192:193], off
	v_lshl_add_u64 v[192:193], v[196:197], 0, s[74:75]
	s_mov_b32 m0, s96
	s_nop 0
	global_load_lds_dwordx4 v[192:193], off
	s_mov_b32 m0, s55
	v_lshl_add_u64 v[192:193], v[198:199], 0, s[74:75]
	global_load_lds_dwordx4 v[192:193], off
	v_lshl_add_u64 v[192:193], v[214:215], 0, s[74:75]
	s_mov_b32 m0, s56
	s_nop 0
	global_load_lds_dwordx4 v[192:193], off
	s_waitcnt vmcnt(12)
	s_barrier
	s_waitcnt lgkmcnt(0)
	s_setprio 1
	s_waitcnt lgkmcnt(0)
	v_mfma_f32_16x16x32_bf16 v[110:113], v[188:191], v[156:159], v[110:113]
	v_mfma_f32_16x16x32_bf16 v[106:109], v[206:209], v[156:159], v[106:109]
	v_mfma_f32_16x16x32_bf16 v[94:97], v[188:191], v[164:167], v[94:97]
	v_mfma_f32_16x16x32_bf16 v[90:93], v[206:209], v[164:167], v[90:93]
	v_mfma_f32_16x16x32_bf16 v[78:81], v[188:191], v[172:175], v[78:81]
	v_mfma_f32_16x16x32_bf16 v[74:77], v[206:209], v[172:175], v[74:77]
	v_mfma_f32_16x16x32_bf16 v[70:73], v[188:191], v[180:183], v[70:73]
	v_mfma_f32_16x16x32_bf16 v[66:69], v[206:209], v[180:183], v[66:69]
	v_mfma_f32_16x16x32_bf16 v[110:113], v[200:203], v[160:163], v[110:113]
	v_mfma_f32_16x16x32_bf16 v[106:109], v[210:213], v[160:163], v[106:109]
	v_mfma_f32_16x16x32_bf16 v[94:97], v[200:203], v[168:171], v[94:97]
	v_mfma_f32_16x16x32_bf16 v[90:93], v[210:213], v[168:171], v[90:93]
	v_mfma_f32_16x16x32_bf16 v[78:81], v[200:203], v[176:179], v[78:81]
	v_mfma_f32_16x16x32_bf16 v[74:77], v[210:213], v[176:179], v[74:77]
	v_mfma_f32_16x16x32_bf16 v[70:73], v[200:203], v[184:187], v[70:73]
	v_mfma_f32_16x16x32_bf16 v[66:69], v[210:213], v[184:187], v[66:69]
	s_setprio 0
	s_barrier
	ds_read_b128 v[156:159], v139 offset:49152
	ds_read_b128 v[160:163], v139 offset:50176
	ds_read_b128 v[164:167], v139 offset:51200
	ds_read_b128 v[168:171], v139 offset:52224
	ds_read_b128 v[172:175], v139 offset:53248
	ds_read_b128 v[176:179], v139 offset:54272
	ds_read_b128 v[180:183], v139 offset:55296
	ds_read_b128 v[184:187], v139 offset:56320
	s_barrier
	s_waitcnt lgkmcnt(0)
	s_setprio 1
	s_waitcnt lgkmcnt(0)
	v_mfma_f32_16x16x32_bf16 v[62:65], v[140:143], v[156:159], v[62:65]
	v_mfma_f32_16x16x32_bf16 v[58:61], v[148:151], v[156:159], v[58:61]
	v_mfma_f32_16x16x32_bf16 v[54:57], v[140:143], v[164:167], v[54:57]
	v_mfma_f32_16x16x32_bf16 v[50:53], v[148:151], v[164:167], v[50:53]
	v_mfma_f32_16x16x32_bf16 v[38:41], v[140:143], v[172:175], v[38:41]
	v_mfma_f32_16x16x32_bf16 v[34:37], v[148:151], v[172:175], v[34:37]
	v_mfma_f32_16x16x32_bf16 v[22:25], v[140:143], v[180:183], v[22:25]
	v_mfma_f32_16x16x32_bf16 v[18:21], v[148:151], v[180:183], v[18:21]
	v_mfma_f32_16x16x32_bf16 v[62:65], v[144:147], v[160:163], v[62:65]
	v_mfma_f32_16x16x32_bf16 v[58:61], v[152:155], v[160:163], v[58:61]
	v_mfma_f32_16x16x32_bf16 v[54:57], v[144:147], v[168:171], v[54:57]
	v_mfma_f32_16x16x32_bf16 v[50:53], v[152:155], v[168:171], v[50:53]
	v_mfma_f32_16x16x32_bf16 v[38:41], v[144:147], v[176:179], v[38:41]
	v_mfma_f32_16x16x32_bf16 v[34:37], v[152:155], v[176:179], v[34:37]
	v_mfma_f32_16x16x32_bf16 v[22:25], v[144:147], v[184:187], v[22:25]
	v_mfma_f32_16x16x32_bf16 v[18:21], v[152:155], v[184:187], v[18:21]
	s_setprio 0
	s_barrier
	s_mov_b32 m0, s71
	v_lshl_add_u64 v[140:141], s[36:37], 0, v[0:1]
	global_load_lds_dwordx4 v[140:141], off
	v_lshl_add_u64 v[140:141], s[36:37], 0, v[130:131]
	s_mov_b32 m0, s34
	s_nop 0
	global_load_lds_dwordx4 v[140:141], off
	s_waitcnt vmcnt(10)
	s_barrier
	s_setprio 1
	v_mfma_f32_16x16x32_bf16 v[46:49], v[188:191], v[156:159], v[46:49]
	v_mfma_f32_16x16x32_bf16 v[42:45], v[206:209], v[156:159], v[42:45]
	v_mfma_f32_16x16x32_bf16 v[30:33], v[188:191], v[164:167], v[30:33]
	v_mfma_f32_16x16x32_bf16 v[26:29], v[206:209], v[164:167], v[26:29]
	v_mfma_f32_16x16x32_bf16 v[14:17], v[188:191], v[172:175], v[14:17]
	v_mfma_f32_16x16x32_bf16 v[10:13], v[206:209], v[172:175], v[10:13]
	v_mfma_f32_16x16x32_bf16 v[6:9], v[188:191], v[180:183], v[6:9]
	v_mfma_f32_16x16x32_bf16 v[2:5], v[206:209], v[180:183], v[2:5]
	v_mfma_f32_16x16x32_bf16 v[46:49], v[200:203], v[160:163], v[46:49]
	v_mfma_f32_16x16x32_bf16 v[42:45], v[210:213], v[160:163], v[42:45]
	v_mfma_f32_16x16x32_bf16 v[30:33], v[200:203], v[168:171], v[30:33]
	v_mfma_f32_16x16x32_bf16 v[26:29], v[210:213], v[168:171], v[26:29]
	v_mfma_f32_16x16x32_bf16 v[14:17], v[200:203], v[176:179], v[14:17]
	v_mfma_f32_16x16x32_bf16 v[10:13], v[210:213], v[176:179], v[10:13]
	v_mfma_f32_16x16x32_bf16 v[6:9], v[200:203], v[184:187], v[6:9]
	v_mfma_f32_16x16x32_bf16 v[2:5], v[210:213], v[184:187], v[2:5]
	s_setprio 0
	s_movk_i32 s2, 0x100
	s_andn2_b64 vcc, exec, s[18:19]
	s_mov_b64 s[36:37], -1
	s_mov_b64 s[18:19], 0
	s_barrier
	s_cbranch_vccz .LBB0_471
	v_lshl_add_u32 v140, s67, 8, v136
	v_lshl_or_b32 v142, s59, 8, v138
	v_ashrrev_i32_e32 v141, 31, v140
	v_readlane_b32 s2, v250, 24
	v_cvt_pk_bf16_f32 v110, v110, v111
	v_cvt_pk_bf16_f32 v111, v112, v113
	v_cvt_pk_bf16_f32 v112, v106, v107
	v_or_b32_e32 v106, 16, v140
	v_cvt_pk_bf16_f32 v94, v94, v95
	v_cvt_pk_bf16_f32 v95, v96, v97
	v_cvt_pk_bf16_f32 v96, v90, v91
	v_or_b32_e32 v90, 32, v140
	v_cvt_pk_bf16_f32 v78, v78, v79
	v_cvt_pk_bf16_f32 v79, v80, v81
	v_cvt_pk_bf16_f32 v80, v74, v75
	v_or_b32_e32 v74, 48, v140
	v_lshlrev_b64 v[144:145], 10, v[140:141]
	v_readlane_b32 s3, v250, 25
	v_ashrrev_i32_e32 v143, 31, v142
	v_ashrrev_i32_e32 v107, 31, v106
	v_ashrrev_i32_e32 v91, 31, v90
	v_ashrrev_i32_e32 v75, 31, v74
	v_lshl_add_u64 v[144:145], s[2:3], 0, v[144:145]
	v_lshlrev_b64 v[142:143], 1, v[142:143]
	v_lshlrev_b64 v[106:107], 10, v[106:107]
	v_lshlrev_b64 v[90:91], 10, v[90:91]
	v_lshlrev_b64 v[74:75], 10, v[74:75]
	v_lshl_add_u64 v[144:145], v[144:145], 0, v[142:143]
	v_lshl_add_u64 v[106:107], s[2:3], 0, v[106:107]
	v_lshl_add_u64 v[90:91], s[2:3], 0, v[90:91]
	v_lshl_add_u64 v[74:75], s[2:3], 0, v[74:75]
	s_mov_b64 s[2:3], 0x20000
	v_cvt_pk_bf16_f32 v70, v70, v71
	v_cvt_pk_bf16_f32 v71, v72, v73
	v_cvt_pk_bf16_f32 v72, v66, v67
	v_lshl_add_u64 v[66:67], v[144:145], 0, s[2:3]
	s_mov_b32 s2, 0x20000
	v_cvt_pk_bf16_f32 v62, v62, v63
	v_cvt_pk_bf16_f32 v63, v64, v65
	v_cvt_pk_bf16_f32 v64, v58, v59
	v_add_co_u32_e32 v58, vcc, s2, v144
	v_cvt_pk_bf16_f32 v46, v46, v47
	s_nop 0
	v_addc_co_u32_e32 v59, vcc, 0, v145, vcc
	v_cvt_pk_bf16_f32 v47, v48, v49
	v_cvt_pk_bf16_f32 v48, v42, v43
	v_cvt_pk_bf16_f32 v49, v44, v45
	s_mov_b64 s[2:3], 0x24000
	global_store_dwordx4 v[66:67], v[46:49], off offset:256
	v_cvt_pk_bf16_f32 v30, v30, v31
	v_cvt_pk_bf16_f32 v31, v32, v33
	v_lshl_add_u64 v[46:47], v[144:145], 0, s[2:3]
	v_add_co_u32_e32 v48, vcc, s63, v144
	v_cvt_pk_bf16_f32 v32, v26, v27
	v_cvt_pk_bf16_f32 v33, v28, v29
	s_mov_b64 s[2:3], 0x28000
	v_addc_co_u32_e32 v49, vcc, 0, v145, vcc
	global_store_dwordx4 v[46:47], v[30:33], off offset:256
	v_cvt_pk_bf16_f32 v14, v14, v15
	v_cvt_pk_bf16_f32 v15, v16, v17
	v_lshl_add_u64 v[30:31], v[144:145], 0, s[2:3]
	s_mov_b32 s2, 0x28000
	v_add_co_u32_e32 v32, vcc, s2, v144
	v_cvt_pk_bf16_f32 v16, v10, v11
	v_cvt_pk_bf16_f32 v17, v12, v13
	s_mov_b64 s[2:3], 0x2c000
	v_cvt_pk_bf16_f32 v113, v108, v109
	v_addc_co_u32_e32 v33, vcc, 0, v145, vcc
	global_store_dwordx4 v[30:31], v[14:17], off offset:256
	global_store_dwordx4 v[144:145], v[110:113], off offset:256
	v_cvt_pk_bf16_f32 v97, v92, v93
	v_lshl_add_u64 v[14:15], v[144:145], 0, s[2:3]
	s_mov_b32 s2, 0x2c000
	v_lshl_add_u64 v[110:111], v[106:107], 0, v[142:143]
	v_add_co_u32_e32 v16, vcc, s2, v144
	global_store_dwordx4 v[110:111], v[94:97], off offset:256
	v_cvt_pk_bf16_f32 v81, v76, v77
	v_addc_co_u32_e32 v17, vcc, 0, v145, vcc
	v_lshl_add_u64 v[94:95], v[90:91], 0, v[142:143]
	v_cvt_pk_bf16_f32 v126, v126, v127
	v_cvt_pk_bf16_f32 v127, v128, v129
	v_cvt_pk_bf16_f32 v128, v122, v123
	v_cvt_pk_bf16_f32 v129, v124, v125
	v_cvt_pk_bf16_f32 v106, v118, v119
	v_cvt_pk_bf16_f32 v107, v120, v121
	v_cvt_pk_bf16_f32 v108, v114, v115
	v_cvt_pk_bf16_f32 v109, v116, v117
	v_cvt_pk_bf16_f32 v90, v102, v103
	v_cvt_pk_bf16_f32 v91, v104, v105
	v_cvt_pk_bf16_f32 v92, v98, v99
	v_cvt_pk_bf16_f32 v93, v100, v101
	global_store_dwordx4 v[94:95], v[78:81], off offset:256
	v_cvt_pk_bf16_f32 v76, v82, v83
	v_cvt_pk_bf16_f32 v77, v84, v85
	v_lshl_add_u64 v[78:79], v[74:75], 0, v[142:143]
	v_cvt_pk_bf16_f32 v74, v86, v87
	v_cvt_pk_bf16_f32 v75, v88, v89
	v_cvt_pk_bf16_f32 v73, v68, v69
	v_cvt_pk_bf16_f32 v65, v60, v61
	v_cvt_pk_bf16_f32 v42, v54, v55
	v_cvt_pk_bf16_f32 v43, v56, v57
	v_cvt_pk_bf16_f32 v44, v50, v51
	v_cvt_pk_bf16_f32 v45, v52, v53
	v_cvt_pk_bf16_f32 v26, v38, v39
	v_cvt_pk_bf16_f32 v27, v40, v41
	v_cvt_pk_bf16_f32 v28, v34, v35
	v_cvt_pk_bf16_f32 v29, v36, v37
	v_cvt_pk_bf16_f32 v10, v22, v23
	v_cvt_pk_bf16_f32 v11, v24, v25
	v_cvt_pk_bf16_f32 v12, v18, v19
	v_cvt_pk_bf16_f32 v13, v20, v21
	v_cvt_pk_bf16_f32 v6, v6, v7
	v_cvt_pk_bf16_f32 v7, v8, v9
	v_cvt_pk_bf16_f32 v8, v2, v3
	v_cvt_pk_bf16_f32 v9, v4, v5
	s_and_b64 vcc, exec, s[0:1]
	s_mov_b32 s59, s6
	s_mov_b32 s67, s8
	s_mov_b64 s[14:15], s[12:13]
	s_mov_b64 s[16:17], s[10:11]
	global_store_dwordx4 v[144:145], v[126:129], off
	global_store_dwordx4 v[110:111], v[106:109], off
	global_store_dwordx4 v[94:95], v[90:93], off
	global_store_dwordx4 v[78:79], v[74:77], off
	global_store_dwordx4 v[78:79], v[70:73], off offset:256
	global_store_dwordx4 v[58:59], v[62:65], off
	global_store_dwordx4 v[48:49], v[42:45], off
	global_store_dwordx4 v[32:33], v[26:29], off
	global_store_dwordx4 v[16:17], v[10:13], off
	global_store_dwordx4 v[14:15], v[6:9], off offset:256
	s_cbranch_vccz .LBB0_468
	s_waitcnt vmcnt(0)
	s_cmpk_gt_u32 s22, 0xff
	v_readlane_b32 s57, v255, 48
	s_cbranch_scc1 .LBB0_475
	s_barrier

.LBB0_483:
	s_add_u32 s38, s16, s2
	s_addc_u32 s39, s17, 0
	s_add_u32 s3, s38, 0x100
	s_addc_u32 s40, s39, 0
	s_and_b64 s[34:35], s[36:37], exec
	s_cselect_b32 vcc_hi, s9, s40
	s_cselect_b32 vcc_lo, s58, s3
	s_add_u32 s2, s14, s2
	s_addc_u32 s3, s15, 0
	s_add_u32 s34, s2, 0x100
	s_addc_u32 s35, s3, 0
	s_add_i32 s42, 0, 0x10000
	s_and_b64 s[2:3], s[36:37], exec
	s_cselect_b32 s73, s7, s35
	s_cselect_b32 s72, s5, s34
	s_add_u32 s2, s38, 0x10080
	s_addc_u32 s3, s39, 0
	s_add_i32 s41, s42, s51
	s_add_i32 m0, s49, 0xc000
	s_add_i32 s43, s49, 0xe000
	s_add_i32 s40, 0, 0x14000
	s_add_i32 s35, s41, 0x2000
	s_add_u32 s44, s72, 0x10000
	v_add_u32_e32 v152, s42, v137
	s_addc_u32 s45, s73, 0
	s_add_i32 s65, s40, s51
	ds_read_b128 v[140:143], v152
	ds_read_b128 v[144:147], v152 offset:1024
	ds_read_b128 v[148:151], v152 offset:2048
	ds_read_b128 v[152:155], v152 offset:3072
	s_add_i32 s64, s65, 0x2000
	s_add_i32 s97, 0, 0x18000
	s_add_u32 s38, vcc_lo, 0x10000
	s_addc_u32 s39, vcc_hi, 0
	s_add_i32 s96, s97, s51
	s_add_i32 s60, 0, 0x1c000
	s_add_i32 s50, s96, 0x2000
	s_add_u32 s36, s72, 0x10080
	s_addc_u32 s37, s73, 0
	s_add_i32 s34, s60, s51
	s_add_i32 s71, s34, 0x2000
	v_lshl_add_u64 v[188:189], s[2:3], 0, v[134:135]
	ds_read_b128 v[156:159], v139
	ds_read_b128 v[160:163], v139 offset:1024
	ds_read_b128 v[164:167], v139 offset:2048
	ds_read_b128 v[168:171], v139 offset:3072
	ds_read_b128 v[172:175], v139 offset:4096
	ds_read_b128 v[176:179], v139 offset:5120
	ds_read_b128 v[180:183], v139 offset:6144
	ds_read_b128 v[184:187], v139 offset:7168
	global_load_lds_dwordx4 v[188:189], off
	v_lshl_add_u64 v[188:189], s[2:3], 0, v[132:133]
	s_mov_b32 m0, s43
	s_nop 0
	global_load_lds_dwordx4 v[188:189], off
	s_waitcnt vmcnt(10)
	s_waitcnt lgkmcnt(8)
	s_barrier
	s_waitcnt lgkmcnt(0)
	s_setprio 1
	s_waitcnt lgkmcnt(0)
	v_mfma_f32_16x16x32_bf16 v[126:129], v[140:143], v[156:159], v[126:129]
	v_mfma_f32_16x16x32_bf16 v[122:125], v[148:151], v[156:159], v[122:125]
	v_mfma_f32_16x16x32_bf16 v[118:121], v[140:143], v[164:167], v[118:121]
	v_mfma_f32_16x16x32_bf16 v[114:117], v[148:151], v[164:167], v[114:117]
	v_mfma_f32_16x16x32_bf16 v[102:105], v[140:143], v[172:175], v[102:105]
	v_mfma_f32_16x16x32_bf16 v[98:101], v[148:151], v[172:175], v[98:101]
	v_mfma_f32_16x16x32_bf16 v[86:89], v[140:143], v[180:183], v[86:89]
	v_mfma_f32_16x16x32_bf16 v[82:85], v[148:151], v[180:183], v[82:85]
	v_mfma_f32_16x16x32_bf16 v[126:129], v[144:147], v[160:163], v[126:129]
	v_mfma_f32_16x16x32_bf16 v[122:125], v[152:155], v[160:163], v[122:125]
	v_mfma_f32_16x16x32_bf16 v[118:121], v[144:147], v[168:171], v[118:121]
	v_mfma_f32_16x16x32_bf16 v[114:117], v[152:155], v[168:171], v[114:117]
	v_mfma_f32_16x16x32_bf16 v[102:105], v[144:147], v[176:179], v[102:105]
	v_mfma_f32_16x16x32_bf16 v[98:101], v[152:155], v[176:179], v[98:101]
	v_mfma_f32_16x16x32_bf16 v[86:89], v[144:147], v[184:187], v[86:89]
	v_mfma_f32_16x16x32_bf16 v[82:85], v[152:155], v[184:187], v[82:85]
	s_setprio 0
	s_barrier
	v_add_u32_e32 v192, s40, v137
	s_mov_b32 m0, s41
	ds_read_b128 v[188:191], v192
	ds_read_b128 v[200:203], v192 offset:1024
	ds_read_b128 v[206:209], v192 offset:2048
	ds_read_b128 v[210:213], v192 offset:3072
	v_lshl_add_u64 v[192:193], s[72:73], 0, v[0:1]
	global_load_lds_dwordx4 v[192:193], off
	v_lshl_add_u64 v[196:197], s[72:73], 0, v[130:131]
	s_mov_b32 m0, s35
	s_nop 0
	global_load_lds_dwordx4 v[196:197], off
	s_mov_b32 m0, s49
	v_lshl_add_u64 v[198:199], vcc, 0, v[134:135]
	global_load_lds_dwordx4 v[198:199], off
	v_lshl_add_u64 v[214:215], vcc, 0, v[132:133]
	s_mov_b32 m0, s52
	s_nop 0
	global_load_lds_dwordx4 v[214:215], off
	s_waitcnt vmcnt(12)
	s_barrier
	s_waitcnt lgkmcnt(0)
	s_setprio 1
	s_waitcnt lgkmcnt(0)
	v_mfma_f32_16x16x32_bf16 v[110:113], v[188:191], v[156:159], v[110:113]
	v_mfma_f32_16x16x32_bf16 v[106:109], v[206:209], v[156:159], v[106:109]
	v_mfma_f32_16x16x32_bf16 v[94:97], v[188:191], v[164:167], v[94:97]
	v_mfma_f32_16x16x32_bf16 v[90:93], v[206:209], v[164:167], v[90:93]
	v_mfma_f32_16x16x32_bf16 v[78:81], v[188:191], v[172:175], v[78:81]
	v_mfma_f32_16x16x32_bf16 v[74:77], v[206:209], v[172:175], v[74:77]
	v_mfma_f32_16x16x32_bf16 v[70:73], v[188:191], v[180:183], v[70:73]
	v_mfma_f32_16x16x32_bf16 v[66:69], v[206:209], v[180:183], v[66:69]
	v_mfma_f32_16x16x32_bf16 v[110:113], v[200:203], v[160:163], v[110:113]
	v_mfma_f32_16x16x32_bf16 v[106:109], v[210:213], v[160:163], v[106:109]
	v_mfma_f32_16x16x32_bf16 v[94:97], v[200:203], v[168:171], v[94:97]
	v_mfma_f32_16x16x32_bf16 v[90:93], v[210:213], v[168:171], v[90:93]
	v_mfma_f32_16x16x32_bf16 v[78:81], v[200:203], v[176:179], v[78:81]
	v_mfma_f32_16x16x32_bf16 v[74:77], v[210:213], v[176:179], v[74:77]
	v_mfma_f32_16x16x32_bf16 v[70:73], v[200:203], v[184:187], v[70:73]
	v_mfma_f32_16x16x32_bf16 v[66:69], v[210:213], v[184:187], v[66:69]
	s_setprio 0
	s_barrier
	ds_read_b128 v[156:159], v139 offset:16384
	ds_read_b128 v[160:163], v139 offset:17408
	ds_read_b128 v[164:167], v139 offset:18432
	ds_read_b128 v[168:171], v139 offset:19456
	ds_read_b128 v[172:175], v139 offset:20480
	ds_read_b128 v[176:179], v139 offset:21504
	ds_read_b128 v[180:183], v139 offset:22528
	ds_read_b128 v[184:187], v139 offset:23552
	s_barrier
	s_waitcnt lgkmcnt(0)
	s_setprio 1
	s_waitcnt lgkmcnt(0)
	v_mfma_f32_16x16x32_bf16 v[62:65], v[140:143], v[156:159], v[62:65]
	v_mfma_f32_16x16x32_bf16 v[58:61], v[148:151], v[156:159], v[58:61]
	v_mfma_f32_16x16x32_bf16 v[54:57], v[140:143], v[164:167], v[54:57]
	v_mfma_f32_16x16x32_bf16 v[50:53], v[148:151], v[164:167], v[50:53]
	v_mfma_f32_16x16x32_bf16 v[38:41], v[140:143], v[172:175], v[38:41]
	v_mfma_f32_16x16x32_bf16 v[34:37], v[148:151], v[172:175], v[34:37]
	v_mfma_f32_16x16x32_bf16 v[22:25], v[140:143], v[180:183], v[22:25]
	v_mfma_f32_16x16x32_bf16 v[18:21], v[148:151], v[180:183], v[18:21]
	v_mfma_f32_16x16x32_bf16 v[62:65], v[144:147], v[160:163], v[62:65]
	v_mfma_f32_16x16x32_bf16 v[58:61], v[152:155], v[160:163], v[58:61]
	v_mfma_f32_16x16x32_bf16 v[54:57], v[144:147], v[168:171], v[54:57]
	v_mfma_f32_16x16x32_bf16 v[50:53], v[152:155], v[168:171], v[50:53]
	v_mfma_f32_16x16x32_bf16 v[38:41], v[144:147], v[176:179], v[38:41]
	v_mfma_f32_16x16x32_bf16 v[34:37], v[152:155], v[176:179], v[34:37]
	v_mfma_f32_16x16x32_bf16 v[22:25], v[144:147], v[184:187], v[22:25]
	v_mfma_f32_16x16x32_bf16 v[18:21], v[152:155], v[184:187], v[18:21]
	s_setprio 0
	s_barrier
	s_mov_b32 m0, s65
	v_lshl_add_u64 v[140:141], s[44:45], 0, v[0:1]
	global_load_lds_dwordx4 v[140:141], off
	v_lshl_add_u64 v[140:141], s[44:45], 0, v[130:131]
	s_mov_b32 m0, s64
	s_nop 0
	global_load_lds_dwordx4 v[140:141], off
	s_waitcnt vmcnt(10)
	s_barrier
	s_setprio 1
	v_mfma_f32_16x16x32_bf16 v[46:49], v[188:191], v[156:159], v[46:49]
	v_mfma_f32_16x16x32_bf16 v[42:45], v[206:209], v[156:159], v[42:45]
	v_mfma_f32_16x16x32_bf16 v[30:33], v[188:191], v[164:167], v[30:33]
	v_mfma_f32_16x16x32_bf16 v[26:29], v[206:209], v[164:167], v[26:29]
	v_mfma_f32_16x16x32_bf16 v[14:17], v[188:191], v[172:175], v[14:17]
	v_mfma_f32_16x16x32_bf16 v[10:13], v[206:209], v[172:175], v[10:13]
	v_mfma_f32_16x16x32_bf16 v[6:9], v[188:191], v[180:183], v[6:9]
	v_mfma_f32_16x16x32_bf16 v[2:5], v[206:209], v[180:183], v[2:5]
	v_mfma_f32_16x16x32_bf16 v[46:49], v[200:203], v[160:163], v[46:49]
	v_mfma_f32_16x16x32_bf16 v[42:45], v[210:213], v[160:163], v[42:45]
	v_mfma_f32_16x16x32_bf16 v[30:33], v[200:203], v[168:171], v[30:33]
	v_mfma_f32_16x16x32_bf16 v[26:29], v[210:213], v[168:171], v[26:29]
	v_mfma_f32_16x16x32_bf16 v[14:17], v[200:203], v[176:179], v[14:17]
	v_mfma_f32_16x16x32_bf16 v[10:13], v[210:213], v[176:179], v[10:13]
	v_mfma_f32_16x16x32_bf16 v[6:9], v[200:203], v[184:187], v[6:9]
	v_mfma_f32_16x16x32_bf16 v[2:5], v[210:213], v[184:187], v[2:5]
	s_setprio 0
	v_add_u32_e32 v152, s97, v137
	s_barrier
	ds_read_b128 v[140:143], v152
	ds_read_b128 v[144:147], v152 offset:1024
	ds_read_b128 v[148:151], v152 offset:2048
	ds_read_b128 v[152:155], v152 offset:3072
	s_mov_b32 m0, s53
	v_lshl_add_u64 v[188:189], s[38:39], 0, v[134:135]
	ds_read_b128 v[156:159], v139 offset:32768
	ds_read_b128 v[160:163], v139 offset:33792
	ds_read_b128 v[164:167], v139 offset:34816
	ds_read_b128 v[168:171], v139 offset:35840
	ds_read_b128 v[172:175], v139 offset:36864
	ds_read_b128 v[176:179], v139 offset:37888
	ds_read_b128 v[180:183], v139 offset:38912
	ds_read_b128 v[184:187], v139 offset:39936
	global_load_lds_dwordx4 v[188:189], off
	v_lshl_add_u64 v[188:189], s[38:39], 0, v[132:133]
	s_mov_b32 m0, s54
	s_nop 0
	global_load_lds_dwordx4 v[188:189], off
	s_waitcnt vmcnt(10)
	s_waitcnt lgkmcnt(8)
	s_barrier
	s_waitcnt lgkmcnt(0)
	s_setprio 1
	s_waitcnt lgkmcnt(0)
	v_mfma_f32_16x16x32_bf16 v[126:129], v[140:143], v[156:159], v[126:129]
	v_mfma_f32_16x16x32_bf16 v[122:125], v[148:151], v[156:159], v[122:125]
	v_mfma_f32_16x16x32_bf16 v[118:121], v[140:143], v[164:167], v[118:121]
	v_mfma_f32_16x16x32_bf16 v[114:117], v[148:151], v[164:167], v[114:117]
	v_mfma_f32_16x16x32_bf16 v[102:105], v[140:143], v[172:175], v[102:105]
	v_mfma_f32_16x16x32_bf16 v[98:101], v[148:151], v[172:175], v[98:101]
	v_mfma_f32_16x16x32_bf16 v[86:89], v[140:143], v[180:183], v[86:89]
	v_mfma_f32_16x16x32_bf16 v[82:85], v[148:151], v[180:183], v[82:85]
	v_mfma_f32_16x16x32_bf16 v[126:129], v[144:147], v[160:163], v[126:129]
	v_mfma_f32_16x16x32_bf16 v[122:125], v[152:155], v[160:163], v[122:125]
	v_mfma_f32_16x16x32_bf16 v[118:121], v[144:147], v[168:171], v[118:121]
	v_mfma_f32_16x16x32_bf16 v[114:117], v[152:155], v[168:171], v[114:117]
	v_mfma_f32_16x16x32_bf16 v[102:105], v[144:147], v[176:179], v[102:105]
	v_mfma_f32_16x16x32_bf16 v[98:101], v[152:155], v[176:179], v[98:101]
	v_mfma_f32_16x16x32_bf16 v[86:89], v[144:147], v[184:187], v[86:89]
	v_mfma_f32_16x16x32_bf16 v[82:85], v[152:155], v[184:187], v[82:85]
	s_setprio 0
	s_barrier
	s_mov_b32 m0, s96
	v_add_u32_e32 v195, s60, v137
	v_lshl_add_u64 v[192:193], v[192:193], 0, s[74:75]
	ds_read_b128 v[188:191], v195
	ds_read_b128 v[200:203], v195 offset:1024
	ds_read_b128 v[206:209], v195 offset:2048
	ds_read_b128 v[210:213], v195 offset:3072
	global_load_lds_dwordx4 v[192:193], off
	v_lshl_add_u64 v[192:193], v[196:197], 0, s[74:75]
	s_mov_b32 m0, s50
	s_nop 0
	global_load_lds_dwordx4 v[192:193], off
	s_mov_b32 m0, s55
	v_lshl_add_u64 v[192:193], v[198:199], 0, s[74:75]
	global_load_lds_dwordx4 v[192:193], off
	v_lshl_add_u64 v[192:193], v[214:215], 0, s[74:75]
	s_mov_b32 m0, s56
	s_nop 0
	global_load_lds_dwordx4 v[192:193], off
	s_waitcnt vmcnt(12)
	s_barrier
	s_waitcnt lgkmcnt(0)
	s_setprio 1
	s_waitcnt lgkmcnt(0)
	v_mfma_f32_16x16x32_bf16 v[110:113], v[188:191], v[156:159], v[110:113]
	v_mfma_f32_16x16x32_bf16 v[106:109], v[206:209], v[156:159], v[106:109]
	v_mfma_f32_16x16x32_bf16 v[94:97], v[188:191], v[164:167], v[94:97]
	v_mfma_f32_16x16x32_bf16 v[90:93], v[206:209], v[164:167], v[90:93]
	v_mfma_f32_16x16x32_bf16 v[78:81], v[188:191], v[172:175], v[78:81]
	v_mfma_f32_16x16x32_bf16 v[74:77], v[206:209], v[172:175], v[74:77]
	v_mfma_f32_16x16x32_bf16 v[70:73], v[188:191], v[180:183], v[70:73]
	v_mfma_f32_16x16x32_bf16 v[66:69], v[206:209], v[180:183], v[66:69]
	v_mfma_f32_16x16x32_bf16 v[110:113], v[200:203], v[160:163], v[110:113]
	v_mfma_f32_16x16x32_bf16 v[106:109], v[210:213], v[160:163], v[106:109]
	v_mfma_f32_16x16x32_bf16 v[94:97], v[200:203], v[168:171], v[94:97]
	v_mfma_f32_16x16x32_bf16 v[90:93], v[210:213], v[168:171], v[90:93]
	v_mfma_f32_16x16x32_bf16 v[78:81], v[200:203], v[176:179], v[78:81]
	v_mfma_f32_16x16x32_bf16 v[74:77], v[210:213], v[176:179], v[74:77]
	v_mfma_f32_16x16x32_bf16 v[70:73], v[200:203], v[184:187], v[70:73]
	v_mfma_f32_16x16x32_bf16 v[66:69], v[210:213], v[184:187], v[66:69]
	s_setprio 0
	s_barrier
	ds_read_b128 v[156:159], v139 offset:49152
	ds_read_b128 v[160:163], v139 offset:50176
	ds_read_b128 v[164:167], v139 offset:51200
	ds_read_b128 v[168:171], v139 offset:52224
	ds_read_b128 v[172:175], v139 offset:53248
	ds_read_b128 v[176:179], v139 offset:54272
	ds_read_b128 v[180:183], v139 offset:55296
	ds_read_b128 v[184:187], v139 offset:56320
	s_barrier
	s_waitcnt lgkmcnt(0)
	s_setprio 1
	s_waitcnt lgkmcnt(0)
	v_mfma_f32_16x16x32_bf16 v[62:65], v[140:143], v[156:159], v[62:65]
	v_mfma_f32_16x16x32_bf16 v[58:61], v[148:151], v[156:159], v[58:61]
	v_mfma_f32_16x16x32_bf16 v[54:57], v[140:143], v[164:167], v[54:57]
	v_mfma_f32_16x16x32_bf16 v[50:53], v[148:151], v[164:167], v[50:53]
	v_mfma_f32_16x16x32_bf16 v[38:41], v[140:143], v[172:175], v[38:41]
	v_mfma_f32_16x16x32_bf16 v[34:37], v[148:151], v[172:175], v[34:37]
	v_mfma_f32_16x16x32_bf16 v[22:25], v[140:143], v[180:183], v[22:25]
	v_mfma_f32_16x16x32_bf16 v[18:21], v[148:151], v[180:183], v[18:21]
	v_mfma_f32_16x16x32_bf16 v[62:65], v[144:147], v[160:163], v[62:65]
	v_mfma_f32_16x16x32_bf16 v[58:61], v[152:155], v[160:163], v[58:61]
	v_mfma_f32_16x16x32_bf16 v[54:57], v[144:147], v[168:171], v[54:57]
	v_mfma_f32_16x16x32_bf16 v[50:53], v[152:155], v[168:171], v[50:53]
	v_mfma_f32_16x16x32_bf16 v[38:41], v[144:147], v[176:179], v[38:41]
	v_mfma_f32_16x16x32_bf16 v[34:37], v[152:155], v[176:179], v[34:37]
	v_mfma_f32_16x16x32_bf16 v[22:25], v[144:147], v[184:187], v[22:25]
	v_mfma_f32_16x16x32_bf16 v[18:21], v[152:155], v[184:187], v[18:21]
	s_setprio 0
	s_barrier
	s_mov_b32 m0, s34
	v_lshl_add_u64 v[140:141], s[36:37], 0, v[0:1]
	global_load_lds_dwordx4 v[140:141], off
	v_lshl_add_u64 v[140:141], s[36:37], 0, v[130:131]
	s_mov_b32 m0, s71
	s_nop 0
	global_load_lds_dwordx4 v[140:141], off
	s_waitcnt vmcnt(10)
	s_barrier
	s_setprio 1
	v_mfma_f32_16x16x32_bf16 v[46:49], v[188:191], v[156:159], v[46:49]
	v_mfma_f32_16x16x32_bf16 v[42:45], v[206:209], v[156:159], v[42:45]
	v_mfma_f32_16x16x32_bf16 v[30:33], v[188:191], v[164:167], v[30:33]
	v_mfma_f32_16x16x32_bf16 v[26:29], v[206:209], v[164:167], v[26:29]
	v_mfma_f32_16x16x32_bf16 v[14:17], v[188:191], v[172:175], v[14:17]
	v_mfma_f32_16x16x32_bf16 v[10:13], v[206:209], v[172:175], v[10:13]
	v_mfma_f32_16x16x32_bf16 v[6:9], v[188:191], v[180:183], v[6:9]
	v_mfma_f32_16x16x32_bf16 v[2:5], v[206:209], v[180:183], v[2:5]
	v_mfma_f32_16x16x32_bf16 v[46:49], v[200:203], v[160:163], v[46:49]
	v_mfma_f32_16x16x32_bf16 v[42:45], v[210:213], v[160:163], v[42:45]
	v_mfma_f32_16x16x32_bf16 v[30:33], v[200:203], v[168:171], v[30:33]
	v_mfma_f32_16x16x32_bf16 v[26:29], v[210:213], v[168:171], v[26:29]
	v_mfma_f32_16x16x32_bf16 v[14:17], v[200:203], v[176:179], v[14:17]
	v_mfma_f32_16x16x32_bf16 v[10:13], v[210:213], v[176:179], v[10:13]
	v_mfma_f32_16x16x32_bf16 v[6:9], v[200:203], v[184:187], v[6:9]
	v_mfma_f32_16x16x32_bf16 v[2:5], v[210:213], v[184:187], v[2:5]
	s_setprio 0
	s_movk_i32 s2, 0x100
	s_andn2_b64 vcc, exec, s[18:19]
	s_mov_b64 s[36:37], -1
	s_mov_b64 s[18:19], 0
	s_barrier
	s_cbranch_vccz .LBB0_483
	v_readlane_b32 s2, v250, 6
	v_lshl_add_u32 v146, s67, 8, v136
	v_lshl_or_b32 v140, s59, 8, v138
	v_readlane_b32 s3, v250, 7
	s_movk_i32 s5, 0x6800
	v_ashrrev_i32_e32 v141, 31, v140
	v_mov_b64_e32 v[142:143], s[2:3]
	v_cvt_pk_bf16_f32 v70, v70, v71
	v_cvt_pk_bf16_f32 v71, v72, v73
	v_cvt_pk_bf16_f32 v72, v66, v67
	v_add_u32_e32 v66, 0x80, v146
	v_mad_i64_i32 v[144:145], s[2:3], v146, s5, v[142:143]
	v_lshlrev_b64 v[140:141], 1, v[140:141]
	v_cvt_pk_bf16_f32 v110, v110, v111
	v_cvt_pk_bf16_f32 v111, v112, v113
	v_cvt_pk_bf16_f32 v112, v106, v107
	v_or_b32_e32 v106, 16, v146
	v_mad_i64_i32 v[66:67], s[2:3], v66, s5, v[142:143]
	v_cvt_pk_bf16_f32 v46, v46, v47
	v_cvt_pk_bf16_f32 v47, v48, v49
	v_cvt_pk_bf16_f32 v48, v42, v43
	v_add_u32_e32 v42, 0x90, v146
	v_lshl_add_u64 v[144:145], v[144:145], 0, v[140:141]
	v_cvt_pk_bf16_f32 v113, v108, v109
	v_mad_i64_i32 v[106:107], s[2:3], v106, s5, v[142:143]
	v_cvt_pk_bf16_f32 v94, v94, v95
	v_cvt_pk_bf16_f32 v95, v96, v97
	v_cvt_pk_bf16_f32 v96, v90, v91
	v_or_b32_e32 v90, 32, v146
	v_lshl_add_u64 v[66:67], v[66:67], 0, v[140:141]
	v_cvt_pk_bf16_f32 v49, v44, v45
	v_mad_i64_i32 v[42:43], s[2:3], v42, s5, v[142:143]
	v_cvt_pk_bf16_f32 v30, v30, v31
	v_cvt_pk_bf16_f32 v31, v32, v33
	v_cvt_pk_bf16_f32 v32, v26, v27
	v_add_u32_e32 v26, 0xa0, v146
	global_store_dwordx4 v[144:145], v[110:113], off offset:256
	v_cvt_pk_bf16_f32 v97, v92, v93
	v_mad_i64_i32 v[90:91], s[2:3], v90, s5, v[142:143]
	v_lshl_add_u64 v[110:111], v[106:107], 0, v[140:141]
	v_cvt_pk_bf16_f32 v78, v78, v79
	v_cvt_pk_bf16_f32 v79, v80, v81
	v_cvt_pk_bf16_f32 v80, v74, v75
	v_or_b32_e32 v74, 48, v146
	global_store_dwordx4 v[66:67], v[46:49], off offset:256
	v_cvt_pk_bf16_f32 v33, v28, v29
	v_mad_i64_i32 v[26:27], s[2:3], v26, s5, v[142:143]
	v_lshl_add_u64 v[46:47], v[42:43], 0, v[140:141]
	v_cvt_pk_bf16_f32 v14, v14, v15
	v_cvt_pk_bf16_f32 v15, v16, v17
	v_cvt_pk_bf16_f32 v16, v10, v11
	v_add_u32_e32 v10, 0xb0, v146
	global_store_dwordx4 v[110:111], v[94:97], off offset:256
	v_cvt_pk_bf16_f32 v81, v76, v77
	v_mad_i64_i32 v[74:75], s[2:3], v74, s5, v[142:143]
	v_lshl_add_u64 v[94:95], v[90:91], 0, v[140:141]
	global_store_dwordx4 v[46:47], v[30:33], off offset:256
	v_cvt_pk_bf16_f32 v17, v12, v13
	v_mad_i64_i32 v[10:11], s[2:3], v10, s5, v[142:143]
	v_lshl_add_u64 v[30:31], v[26:27], 0, v[140:141]
	v_cvt_pk_bf16_f32 v126, v126, v127
	v_cvt_pk_bf16_f32 v127, v128, v129
	v_cvt_pk_bf16_f32 v128, v122, v123
	v_cvt_pk_bf16_f32 v129, v124, v125
	v_cvt_pk_bf16_f32 v106, v118, v119
	v_cvt_pk_bf16_f32 v107, v120, v121
	v_cvt_pk_bf16_f32 v108, v114, v115
	v_cvt_pk_bf16_f32 v109, v116, v117
	v_cvt_pk_bf16_f32 v90, v102, v103
	v_cvt_pk_bf16_f32 v91, v104, v105
	v_cvt_pk_bf16_f32 v92, v98, v99
	v_cvt_pk_bf16_f32 v93, v100, v101
	global_store_dwordx4 v[94:95], v[78:81], off offset:256
	v_cvt_pk_bf16_f32 v76, v82, v83
	v_cvt_pk_bf16_f32 v77, v84, v85
	v_lshl_add_u64 v[78:79], v[74:75], 0, v[140:141]
	v_cvt_pk_bf16_f32 v74, v86, v87
	v_cvt_pk_bf16_f32 v75, v88, v89
	v_cvt_pk_bf16_f32 v73, v68, v69
	v_cvt_pk_bf16_f32 v62, v62, v63
	v_cvt_pk_bf16_f32 v63, v64, v65
	v_cvt_pk_bf16_f32 v64, v58, v59
	v_cvt_pk_bf16_f32 v65, v60, v61
	v_cvt_pk_bf16_f32 v42, v54, v55
	v_cvt_pk_bf16_f32 v43, v56, v57
	v_cvt_pk_bf16_f32 v44, v50, v51
	v_cvt_pk_bf16_f32 v45, v52, v53
	v_cvt_pk_bf16_f32 v26, v38, v39
	v_cvt_pk_bf16_f32 v27, v40, v41
	v_cvt_pk_bf16_f32 v28, v34, v35
	v_cvt_pk_bf16_f32 v29, v36, v37
	global_store_dwordx4 v[30:31], v[14:17], off offset:256
	v_cvt_pk_bf16_f32 v12, v18, v19
	v_cvt_pk_bf16_f32 v13, v20, v21
	v_lshl_add_u64 v[14:15], v[10:11], 0, v[140:141]
	v_cvt_pk_bf16_f32 v10, v22, v23
	v_cvt_pk_bf16_f32 v11, v24, v25
	v_cvt_pk_bf16_f32 v6, v6, v7
	v_cvt_pk_bf16_f32 v7, v8, v9
	v_cvt_pk_bf16_f32 v8, v2, v3
	v_cvt_pk_bf16_f32 v9, v4, v5
	s_and_b64 vcc, exec, s[0:1]
	s_mov_b32 s59, s6
	s_mov_b32 s67, s8
	s_mov_b64 s[14:15], s[12:13]
	s_mov_b64 s[16:17], s[10:11]
	global_store_dwordx4 v[144:145], v[126:129], off
	global_store_dwordx4 v[110:111], v[106:109], off
	global_store_dwordx4 v[94:95], v[90:93], off
	global_store_dwordx4 v[78:79], v[74:77], off
	global_store_dwordx4 v[78:79], v[70:73], off offset:256
	global_store_dwordx4 v[66:67], v[62:65], off
	global_store_dwordx4 v[46:47], v[42:45], off
	global_store_dwordx4 v[30:31], v[26:29], off
	global_store_dwordx4 v[14:15], v[10:13], off
	global_store_dwordx4 v[14:15], v[6:9], off offset:256
	s_cbranch_vccz .LBB0_480
	s_waitcnt vmcnt(0)
	s_cmpk_gt_u32 s22, 0xff
	v_readlane_b32 s57, v255, 48
	s_cbranch_scc1 .LBB0_487
	s_barrier

.LBB0_495:
	s_add_u32 s16, s14, 0x100
	s_addc_u32 s17, s15, 0
	s_add_u32 s2, s50, s14
	s_addc_u32 s3, s52, s15
	s_cmp_eq_u32 s53, 4
	s_cselect_b32 s35, 0, s16
	s_cselect_b32 s34, 0, s17
	s_cselect_b32 s18, s7, s2
	s_cselect_b32 s19, s1, s3
	s_add_u32 s2, s46, s35
	s_addc_u32 s3, s47, s34
	s_add_i32 s34, 0, 0x10000
	v_add_u32_e32 v159, s34, v156
	ds_read_b128 v[160:163], v159
	ds_read_b128 v[164:167], v159 offset:1024
	ds_read_b128 v[168:171], v159 offset:2048
	ds_read_b128 v[172:175], v159 offset:3072
	v_lshl_add_u64 v[192:193], v[152:153], 0, s[14:15]
	s_add_i32 m0, s37, 0xc000
	ds_read_b128 v[176:179], v158
	ds_read_b128 v[180:183], v158 offset:1024
	ds_read_b128 v[184:187], v158 offset:2048
	ds_read_b128 v[188:191], v158 offset:3072
	ds_read_b128 v[200:203], v158 offset:4096
	ds_read_b128 v[206:209], v158 offset:5120
	ds_read_b128 v[210:213], v158 offset:6144
	ds_read_b128 v[214:217], v158 offset:7168
	global_load_lds_dwordx4 v[192:193], off
	v_lshl_add_u64 v[192:193], v[154:155], 0, s[14:15]
	s_add_i32 m0, s37, 0xe000
	s_nop 0
	global_load_lds_dwordx4 v[192:193], off
	s_waitcnt vmcnt(10)
	s_waitcnt lgkmcnt(8)
	s_barrier
	s_waitcnt lgkmcnt(0)
	s_setprio 1
	s_waitcnt lgkmcnt(0)
	v_mfma_f32_16x16x32_bf16 v[126:129], v[160:163], v[176:179], v[126:129]
	v_mfma_f32_16x16x32_bf16 v[122:125], v[168:171], v[176:179], v[122:125]
	v_mfma_f32_16x16x32_bf16 v[118:121], v[160:163], v[184:187], v[118:121]
	v_mfma_f32_16x16x32_bf16 v[114:117], v[168:171], v[184:187], v[114:117]
	v_mfma_f32_16x16x32_bf16 v[102:105], v[160:163], v[200:203], v[102:105]
	v_mfma_f32_16x16x32_bf16 v[98:101], v[168:171], v[200:203], v[98:101]
	v_mfma_f32_16x16x32_bf16 v[86:89], v[160:163], v[210:213], v[86:89]
	v_mfma_f32_16x16x32_bf16 v[82:85], v[168:171], v[210:213], v[82:85]
	v_mfma_f32_16x16x32_bf16 v[126:129], v[164:167], v[180:183], v[126:129]
	v_mfma_f32_16x16x32_bf16 v[122:125], v[172:175], v[180:183], v[122:125]
	v_mfma_f32_16x16x32_bf16 v[118:121], v[164:167], v[188:191], v[118:121]
	v_mfma_f32_16x16x32_bf16 v[114:117], v[172:175], v[188:191], v[114:117]
	v_mfma_f32_16x16x32_bf16 v[102:105], v[164:167], v[206:209], v[102:105]
	v_mfma_f32_16x16x32_bf16 v[98:101], v[172:175], v[206:209], v[98:101]
	v_mfma_f32_16x16x32_bf16 v[86:89], v[164:167], v[214:217], v[86:89]
	v_mfma_f32_16x16x32_bf16 v[82:85], v[172:175], v[214:217], v[82:85]
	s_setprio 0
	s_barrier
	s_add_i32 s35, 0, 0x14000
	s_add_i32 s14, s34, s36
	v_add_u32_e32 v159, s35, v156
	v_lshl_add_u64 v[192:193], s[18:19], 0, v[0:1]
	s_mov_b32 m0, s14
	ds_read_b128 v[218:221], v159
	ds_read_b128 v[228:231], v159 offset:1024
	ds_read_b128 v[196:199], v159 offset:2048
	ds_read_b128 v[222:225], v159 offset:3072
	global_load_lds_dwordx4 v[192:193], off
	v_lshl_add_u64 v[242:243], s[18:19], 0, v[130:131]
	s_add_i32 m0, s14, 0x2000
	s_nop 0
	global_load_lds_dwordx4 v[242:243], off
	s_mov_b32 m0, s37
	v_lshl_add_u64 v[234:235], s[2:3], 0, v[134:135]
	global_load_lds_dwordx4 v[234:235], off
	v_lshl_add_u64 v[236:237], s[2:3], 0, v[132:133]
	s_mov_b32 m0, s38
	s_nop 0
	global_load_lds_dwordx4 v[236:237], off
	s_waitcnt vmcnt(12)
	s_barrier
	s_waitcnt lgkmcnt(0)
	s_setprio 1
	s_waitcnt lgkmcnt(0)
	v_mfma_f32_16x16x32_bf16 v[110:113], v[218:221], v[176:179], v[110:113]
	v_mfma_f32_16x16x32_bf16 v[106:109], v[196:199], v[176:179], v[106:109]
	v_mfma_f32_16x16x32_bf16 v[94:97], v[218:221], v[184:187], v[94:97]
	v_mfma_f32_16x16x32_bf16 v[90:93], v[196:199], v[184:187], v[90:93]
	v_mfma_f32_16x16x32_bf16 v[78:81], v[218:221], v[200:203], v[78:81]
	v_mfma_f32_16x16x32_bf16 v[74:77], v[196:199], v[200:203], v[74:77]
	v_mfma_f32_16x16x32_bf16 v[70:73], v[218:221], v[210:213], v[70:73]
	v_mfma_f32_16x16x32_bf16 v[66:69], v[196:199], v[210:213], v[66:69]
	v_mfma_f32_16x16x32_bf16 v[110:113], v[228:231], v[180:183], v[110:113]
	v_mfma_f32_16x16x32_bf16 v[106:109], v[222:225], v[180:183], v[106:109]
	v_mfma_f32_16x16x32_bf16 v[94:97], v[228:231], v[188:191], v[94:97]
	v_mfma_f32_16x16x32_bf16 v[90:93], v[222:225], v[188:191], v[90:93]
	v_mfma_f32_16x16x32_bf16 v[78:81], v[228:231], v[206:209], v[78:81]
	v_mfma_f32_16x16x32_bf16 v[74:77], v[222:225], v[206:209], v[74:77]
	v_mfma_f32_16x16x32_bf16 v[70:73], v[228:231], v[214:217], v[70:73]
	v_mfma_f32_16x16x32_bf16 v[66:69], v[222:225], v[214:217], v[66:69]
	s_setprio 0
	s_barrier
	ds_read_b128 v[176:179], v158 offset:16384
	ds_read_b128 v[180:183], v158 offset:17408
	ds_read_b128 v[184:187], v158 offset:18432
	ds_read_b128 v[188:191], v158 offset:19456
	ds_read_b128 v[200:203], v158 offset:20480
	ds_read_b128 v[206:209], v158 offset:21504
	ds_read_b128 v[210:213], v158 offset:22528
	ds_read_b128 v[214:217], v158 offset:23552
	s_barrier
	s_waitcnt lgkmcnt(0)
	s_setprio 1
	s_waitcnt lgkmcnt(0)
	v_mfma_f32_16x16x32_bf16 v[62:65], v[160:163], v[176:179], v[62:65]
	v_mfma_f32_16x16x32_bf16 v[58:61], v[168:171], v[176:179], v[58:61]
	v_mfma_f32_16x16x32_bf16 v[54:57], v[160:163], v[184:187], v[54:57]
	v_mfma_f32_16x16x32_bf16 v[50:53], v[168:171], v[184:187], v[50:53]
	v_mfma_f32_16x16x32_bf16 v[38:41], v[160:163], v[200:203], v[38:41]
	v_mfma_f32_16x16x32_bf16 v[34:37], v[168:171], v[200:203], v[34:37]
	v_mfma_f32_16x16x32_bf16 v[22:25], v[160:163], v[210:213], v[22:25]
	v_mfma_f32_16x16x32_bf16 v[18:21], v[168:171], v[210:213], v[18:21]
	v_mfma_f32_16x16x32_bf16 v[62:65], v[164:167], v[180:183], v[62:65]
	v_mfma_f32_16x16x32_bf16 v[58:61], v[172:175], v[180:183], v[58:61]
	v_mfma_f32_16x16x32_bf16 v[54:57], v[164:167], v[188:191], v[54:57]
	v_mfma_f32_16x16x32_bf16 v[50:53], v[172:175], v[188:191], v[50:53]
	v_mfma_f32_16x16x32_bf16 v[38:41], v[164:167], v[206:209], v[38:41]
	v_mfma_f32_16x16x32_bf16 v[34:37], v[172:175], v[206:209], v[34:37]
	v_mfma_f32_16x16x32_bf16 v[22:25], v[164:167], v[214:217], v[22:25]
	v_mfma_f32_16x16x32_bf16 v[18:21], v[172:175], v[214:217], v[18:21]
	s_setprio 0
	s_barrier
	s_add_u32 s14, s18, 0x400000
	s_addc_u32 s15, s19, 0
	s_add_i32 s34, s35, s36
	v_lshl_add_u64 v[160:161], s[14:15], 0, v[0:1]
	s_mov_b32 m0, s34
	s_nop 0
	global_load_lds_dwordx4 v[160:161], off
	v_lshl_add_u64 v[160:161], s[14:15], 0, v[130:131]
	s_add_i32 m0, s34, 0x2000
	s_nop 0
	global_load_lds_dwordx4 v[160:161], off
	s_waitcnt vmcnt(10)
	s_barrier
	s_setprio 1
	v_mfma_f32_16x16x32_bf16 v[46:49], v[218:221], v[176:179], v[46:49]
	v_mfma_f32_16x16x32_bf16 v[42:45], v[196:199], v[176:179], v[42:45]
	v_mfma_f32_16x16x32_bf16 v[30:33], v[218:221], v[184:187], v[30:33]
	v_mfma_f32_16x16x32_bf16 v[26:29], v[196:199], v[184:187], v[26:29]
	v_mfma_f32_16x16x32_bf16 v[14:17], v[218:221], v[200:203], v[14:17]
	v_mfma_f32_16x16x32_bf16 v[10:13], v[196:199], v[200:203], v[10:13]
	v_mfma_f32_16x16x32_bf16 v[6:9], v[218:221], v[210:213], v[6:9]
	v_mfma_f32_16x16x32_bf16 v[2:5], v[196:199], v[210:213], v[2:5]
	v_mfma_f32_16x16x32_bf16 v[46:49], v[228:231], v[180:183], v[46:49]
	v_mfma_f32_16x16x32_bf16 v[42:45], v[222:225], v[180:183], v[42:45]
	v_mfma_f32_16x16x32_bf16 v[30:33], v[228:231], v[188:191], v[30:33]
	v_mfma_f32_16x16x32_bf16 v[26:29], v[222:225], v[188:191], v[26:29]
	v_mfma_f32_16x16x32_bf16 v[14:17], v[228:231], v[206:209], v[14:17]
	v_mfma_f32_16x16x32_bf16 v[10:13], v[222:225], v[206:209], v[10:13]
	v_mfma_f32_16x16x32_bf16 v[6:9], v[228:231], v[214:217], v[6:9]
	v_mfma_f32_16x16x32_bf16 v[2:5], v[222:225], v[214:217], v[2:5]
	s_setprio 0
	s_add_i32 s14, 0, 0x18000
	v_add_u32_e32 v159, s14, v156
	s_barrier
	ds_read_b128 v[160:163], v159
	ds_read_b128 v[164:167], v159 offset:1024
	ds_read_b128 v[168:171], v159 offset:2048
	ds_read_b128 v[172:175], v159 offset:3072
	s_add_u32 s2, s2, 0x20000
	s_addc_u32 s3, s3, 0
	s_mov_b32 m0, s39
	v_lshl_add_u64 v[214:215], s[2:3], 0, v[134:135]
	ds_read_b128 v[176:179], v158 offset:32768
	ds_read_b128 v[180:183], v158 offset:33792
	ds_read_b128 v[184:187], v158 offset:34816
	ds_read_b128 v[188:191], v158 offset:35840
	ds_read_b128 v[196:199], v158 offset:36864
	ds_read_b128 v[200:203], v158 offset:37888
	ds_read_b128 v[206:209], v158 offset:38912
	ds_read_b128 v[210:213], v158 offset:39936
	global_load_lds_dwordx4 v[214:215], off
	v_lshl_add_u64 v[214:215], s[2:3], 0, v[132:133]
	s_mov_b32 m0, s44
	s_nop 0
	global_load_lds_dwordx4 v[214:215], off
	s_waitcnt vmcnt(10)
	s_waitcnt lgkmcnt(8)
	s_barrier
	s_waitcnt lgkmcnt(0)
	s_setprio 1
	s_waitcnt lgkmcnt(0)
	v_mfma_f32_16x16x32_bf16 v[126:129], v[160:163], v[176:179], v[126:129]
	v_mfma_f32_16x16x32_bf16 v[122:125], v[168:171], v[176:179], v[122:125]
	v_mfma_f32_16x16x32_bf16 v[118:121], v[160:163], v[184:187], v[118:121]
	v_mfma_f32_16x16x32_bf16 v[114:117], v[168:171], v[184:187], v[114:117]
	v_mfma_f32_16x16x32_bf16 v[102:105], v[160:163], v[196:199], v[102:105]
	v_mfma_f32_16x16x32_bf16 v[98:101], v[168:171], v[196:199], v[98:101]
	v_mfma_f32_16x16x32_bf16 v[86:89], v[160:163], v[206:209], v[86:89]
	v_mfma_f32_16x16x32_bf16 v[82:85], v[168:171], v[206:209], v[82:85]
	v_mfma_f32_16x16x32_bf16 v[126:129], v[164:167], v[180:183], v[126:129]
	v_mfma_f32_16x16x32_bf16 v[122:125], v[172:175], v[180:183], v[122:125]
	v_mfma_f32_16x16x32_bf16 v[118:121], v[164:167], v[188:191], v[118:121]
	v_mfma_f32_16x16x32_bf16 v[114:117], v[172:175], v[188:191], v[114:117]
	v_mfma_f32_16x16x32_bf16 v[102:105], v[164:167], v[200:203], v[102:105]
	v_mfma_f32_16x16x32_bf16 v[98:101], v[172:175], v[200:203], v[98:101]
	v_mfma_f32_16x16x32_bf16 v[86:89], v[164:167], v[210:213], v[86:89]
	v_mfma_f32_16x16x32_bf16 v[82:85], v[172:175], v[210:213], v[82:85]
	s_setprio 0
	s_barrier
	s_add_i32 s15, 0, 0x1c000
	s_add_i32 s2, s14, s36
	v_add_u32_e32 v159, s15, v156
	v_lshl_add_u64 v[192:193], v[192:193], 0, s[74:75]
	s_mov_b32 m0, s2
	ds_read_b128 v[214:217], v159
	ds_read_b128 v[218:221], v159 offset:1024
	ds_read_b128 v[222:225], v159 offset:2048
	ds_read_b128 v[228:231], v159 offset:3072
	global_load_lds_dwordx4 v[192:193], off
	v_lshl_add_u64 v[192:193], v[242:243], 0, s[74:75]
	s_add_i32 m0, s2, 0x2000
	s_nop 0
	global_load_lds_dwordx4 v[192:193], off
	s_mov_b32 m0, s45
	v_lshl_add_u64 v[192:193], v[234:235], 0, s[74:75]
	global_load_lds_dwordx4 v[192:193], off
	v_lshl_add_u64 v[192:193], v[236:237], 0, s[74:75]
	s_mov_b32 m0, s49
	s_nop 0
	global_load_lds_dwordx4 v[192:193], off
	s_waitcnt vmcnt(12)
	s_barrier
	s_waitcnt lgkmcnt(0)
	s_setprio 1
	s_waitcnt lgkmcnt(0)
	v_mfma_f32_16x16x32_bf16 v[110:113], v[214:217], v[176:179], v[110:113]
	v_mfma_f32_16x16x32_bf16 v[106:109], v[222:225], v[176:179], v[106:109]
	v_mfma_f32_16x16x32_bf16 v[94:97], v[214:217], v[184:187], v[94:97]
	v_mfma_f32_16x16x32_bf16 v[90:93], v[222:225], v[184:187], v[90:93]
	v_mfma_f32_16x16x32_bf16 v[78:81], v[214:217], v[196:199], v[78:81]
	v_mfma_f32_16x16x32_bf16 v[74:77], v[222:225], v[196:199], v[74:77]
	v_mfma_f32_16x16x32_bf16 v[70:73], v[214:217], v[206:209], v[70:73]
	v_mfma_f32_16x16x32_bf16 v[66:69], v[222:225], v[206:209], v[66:69]
	v_mfma_f32_16x16x32_bf16 v[110:113], v[218:221], v[180:183], v[110:113]
	v_mfma_f32_16x16x32_bf16 v[106:109], v[228:231], v[180:183], v[106:109]
	v_mfma_f32_16x16x32_bf16 v[94:97], v[218:221], v[188:191], v[94:97]
	v_mfma_f32_16x16x32_bf16 v[90:93], v[228:231], v[188:191], v[90:93]
	v_mfma_f32_16x16x32_bf16 v[78:81], v[218:221], v[200:203], v[78:81]
	v_mfma_f32_16x16x32_bf16 v[74:77], v[228:231], v[200:203], v[74:77]
	v_mfma_f32_16x16x32_bf16 v[70:73], v[218:221], v[210:213], v[70:73]
	v_mfma_f32_16x16x32_bf16 v[66:69], v[228:231], v[210:213], v[66:69]
	s_setprio 0
	s_barrier
	ds_read_b128 v[176:179], v158 offset:49152
	ds_read_b128 v[180:183], v158 offset:50176
	ds_read_b128 v[184:187], v158 offset:51200
	ds_read_b128 v[188:191], v158 offset:52224
	ds_read_b128 v[196:199], v158 offset:53248
	ds_read_b128 v[200:203], v158 offset:54272
	ds_read_b128 v[206:209], v158 offset:55296
	ds_read_b128 v[210:213], v158 offset:56320
	s_barrier
	s_waitcnt lgkmcnt(0)
	s_setprio 1
	s_waitcnt lgkmcnt(0)
	v_mfma_f32_16x16x32_bf16 v[62:65], v[160:163], v[176:179], v[62:65]
	v_mfma_f32_16x16x32_bf16 v[58:61], v[168:171], v[176:179], v[58:61]
	v_mfma_f32_16x16x32_bf16 v[54:57], v[160:163], v[184:187], v[54:57]
	v_mfma_f32_16x16x32_bf16 v[50:53], v[168:171], v[184:187], v[50:53]
	v_mfma_f32_16x16x32_bf16 v[38:41], v[160:163], v[196:199], v[38:41]
	v_mfma_f32_16x16x32_bf16 v[34:37], v[168:171], v[196:199], v[34:37]
	v_mfma_f32_16x16x32_bf16 v[22:25], v[160:163], v[206:209], v[22:25]
	v_mfma_f32_16x16x32_bf16 v[18:21], v[168:171], v[206:209], v[18:21]
	v_mfma_f32_16x16x32_bf16 v[62:65], v[164:167], v[180:183], v[62:65]
	v_mfma_f32_16x16x32_bf16 v[58:61], v[172:175], v[180:183], v[58:61]
	v_mfma_f32_16x16x32_bf16 v[54:57], v[164:167], v[188:191], v[54:57]
	v_mfma_f32_16x16x32_bf16 v[50:53], v[172:175], v[188:191], v[50:53]
	v_mfma_f32_16x16x32_bf16 v[38:41], v[164:167], v[200:203], v[38:41]
	v_mfma_f32_16x16x32_bf16 v[34:37], v[172:175], v[200:203], v[34:37]
	v_mfma_f32_16x16x32_bf16 v[22:25], v[164:167], v[210:213], v[22:25]
	v_mfma_f32_16x16x32_bf16 v[18:21], v[172:175], v[210:213], v[18:21]
	s_setprio 0
	s_barrier
	s_add_u32 s2, s18, 0x400080
	s_addc_u32 s3, s19, 0
	s_add_i32 s14, s15, s36
	v_lshl_add_u64 v[160:161], s[2:3], 0, v[0:1]
	s_mov_b32 m0, s14
	s_nop 0
	global_load_lds_dwordx4 v[160:161], off
	v_lshl_add_u64 v[160:161], s[2:3], 0, v[130:131]
	s_add_i32 m0, s14, 0x2000
	s_nop 0
	global_load_lds_dwordx4 v[160:161], off
	s_waitcnt vmcnt(10)
	s_barrier
	s_setprio 1
	v_mfma_f32_16x16x32_bf16 v[46:49], v[214:217], v[176:179], v[46:49]
	v_mfma_f32_16x16x32_bf16 v[42:45], v[222:225], v[176:179], v[42:45]
	v_mfma_f32_16x16x32_bf16 v[30:33], v[214:217], v[184:187], v[30:33]
	v_mfma_f32_16x16x32_bf16 v[26:29], v[222:225], v[184:187], v[26:29]
	v_mfma_f32_16x16x32_bf16 v[14:17], v[214:217], v[196:199], v[14:17]
	v_mfma_f32_16x16x32_bf16 v[10:13], v[222:225], v[196:199], v[10:13]
	v_mfma_f32_16x16x32_bf16 v[6:9], v[214:217], v[206:209], v[6:9]
	v_mfma_f32_16x16x32_bf16 v[2:5], v[222:225], v[206:209], v[2:5]
	v_mfma_f32_16x16x32_bf16 v[46:49], v[218:221], v[180:183], v[46:49]
	v_mfma_f32_16x16x32_bf16 v[42:45], v[228:231], v[180:183], v[42:45]
	v_mfma_f32_16x16x32_bf16 v[30:33], v[218:221], v[188:191], v[30:33]
	v_mfma_f32_16x16x32_bf16 v[26:29], v[228:231], v[188:191], v[26:29]
	v_mfma_f32_16x16x32_bf16 v[14:17], v[218:221], v[200:203], v[14:17]
	v_mfma_f32_16x16x32_bf16 v[10:13], v[228:231], v[200:203], v[10:13]
	v_mfma_f32_16x16x32_bf16 v[6:9], v[218:221], v[210:213], v[6:9]
	v_mfma_f32_16x16x32_bf16 v[2:5], v[228:231], v[210:213], v[2:5]
	s_setprio 0
	s_add_i32 s53, s53, 2
	s_cmp_gt_u32 s53, 5
	s_mov_b64 s[14:15], s[16:17]
	s_barrier
	s_cbranch_scc0 .LBB0_495
	v_lshl_or_b32 v160, s13, 8, v157
	s_ashr_i32 s13, s12, 31
	s_lshl_b64 s[2:3], s[12:13], 18
	s_add_u32 s2, s40, s2
	s_addc_u32 s3, s54, s3
	v_ashrrev_i32_e32 v161, 31, v160
	v_lshl_add_u64 v[162:163], s[2:3], 0, v[136:137]
	v_lshlrev_b64 v[160:161], 1, v[160:161]
	v_cvt_pk_bf16_f32 v70, v70, v71
	v_cvt_pk_bf16_f32 v71, v72, v73
	v_cvt_pk_bf16_f32 v72, v66, v67
	v_lshl_add_u64 v[66:67], s[2:3], 0, v[144:145]
	v_lshl_add_u64 v[162:163], v[162:163], 0, v[160:161]
	v_cvt_pk_bf16_f32 v110, v110, v111
	v_cvt_pk_bf16_f32 v111, v112, v113
	v_cvt_pk_bf16_f32 v112, v106, v107
	v_cvt_pk_bf16_f32 v113, v108, v109
	v_lshl_add_u64 v[106:107], s[2:3], 0, v[138:139]
	v_lshl_add_u64 v[66:67], v[66:67], 0, v[160:161]
	v_cvt_pk_bf16_f32 v46, v46, v47
	v_cvt_pk_bf16_f32 v47, v48, v49
	v_cvt_pk_bf16_f32 v48, v42, v43
	v_cvt_pk_bf16_f32 v49, v44, v45
	v_lshl_add_u64 v[42:43], s[2:3], 0, v[146:147]
	global_store_dwordx4 v[162:163], v[110:113], off offset:256
	v_cvt_pk_bf16_f32 v94, v94, v95
	v_cvt_pk_bf16_f32 v95, v96, v97
	v_lshl_add_u64 v[110:111], v[106:107], 0, v[160:161]
	v_cvt_pk_bf16_f32 v96, v90, v91
	v_cvt_pk_bf16_f32 v97, v92, v93
	v_lshl_add_u64 v[90:91], s[2:3], 0, v[140:141]
	global_store_dwordx4 v[66:67], v[46:49], off offset:256
	v_cvt_pk_bf16_f32 v30, v30, v31
	v_cvt_pk_bf16_f32 v31, v32, v33
	v_lshl_add_u64 v[46:47], v[42:43], 0, v[160:161]
	v_cvt_pk_bf16_f32 v32, v26, v27
	v_cvt_pk_bf16_f32 v33, v28, v29
	v_lshl_add_u64 v[26:27], s[2:3], 0, v[148:149]
	global_store_dwordx4 v[110:111], v[94:97], off offset:256
	v_cvt_pk_bf16_f32 v78, v78, v79
	v_cvt_pk_bf16_f32 v79, v80, v81
	v_lshl_add_u64 v[94:95], v[90:91], 0, v[160:161]
	v_cvt_pk_bf16_f32 v80, v74, v75
	v_cvt_pk_bf16_f32 v81, v76, v77
	v_lshl_add_u64 v[74:75], s[2:3], 0, v[142:143]
	global_store_dwordx4 v[46:47], v[30:33], off offset:256
	v_cvt_pk_bf16_f32 v14, v14, v15
	v_cvt_pk_bf16_f32 v15, v16, v17
	v_lshl_add_u64 v[30:31], v[26:27], 0, v[160:161]
	v_cvt_pk_bf16_f32 v16, v10, v11
	v_cvt_pk_bf16_f32 v17, v12, v13
	v_lshl_add_u64 v[10:11], s[2:3], 0, v[150:151]
	v_cvt_pk_bf16_f32 v126, v126, v127
	v_cvt_pk_bf16_f32 v127, v128, v129
	v_cvt_pk_bf16_f32 v128, v122, v123
	v_cvt_pk_bf16_f32 v129, v124, v125
	v_cvt_pk_bf16_f32 v106, v118, v119
	v_cvt_pk_bf16_f32 v107, v120, v121
	v_cvt_pk_bf16_f32 v108, v114, v115
	v_cvt_pk_bf16_f32 v109, v116, v117
	v_cvt_pk_bf16_f32 v90, v102, v103
	v_cvt_pk_bf16_f32 v91, v104, v105
	v_cvt_pk_bf16_f32 v92, v98, v99
	v_cvt_pk_bf16_f32 v93, v100, v101
	global_store_dwordx4 v[94:95], v[78:81], off offset:256
	v_cvt_pk_bf16_f32 v76, v82, v83
	v_cvt_pk_bf16_f32 v77, v84, v85
	v_lshl_add_u64 v[78:79], v[74:75], 0, v[160:161]
	v_cvt_pk_bf16_f32 v74, v86, v87
	v_cvt_pk_bf16_f32 v75, v88, v89
	v_cvt_pk_bf16_f32 v73, v68, v69
	v_cvt_pk_bf16_f32 v62, v62, v63
	v_cvt_pk_bf16_f32 v63, v64, v65
	v_cvt_pk_bf16_f32 v64, v58, v59
	v_cvt_pk_bf16_f32 v65, v60, v61
	v_cvt_pk_bf16_f32 v42, v54, v55
	v_cvt_pk_bf16_f32 v43, v56, v57
	v_cvt_pk_bf16_f32 v44, v50, v51
	v_cvt_pk_bf16_f32 v45, v52, v53
	v_cvt_pk_bf16_f32 v26, v38, v39
	v_cvt_pk_bf16_f32 v27, v40, v41
	v_cvt_pk_bf16_f32 v28, v34, v35
	v_cvt_pk_bf16_f32 v29, v36, v37
	global_store_dwordx4 v[30:31], v[14:17], off offset:256
	v_cvt_pk_bf16_f32 v12, v18, v19
	v_cvt_pk_bf16_f32 v13, v20, v21
	v_lshl_add_u64 v[14:15], v[10:11], 0, v[160:161]
	v_cvt_pk_bf16_f32 v10, v22, v23
	v_cvt_pk_bf16_f32 v11, v24, v25
	v_cvt_pk_bf16_f32 v6, v6, v7
	v_cvt_pk_bf16_f32 v7, v8, v9
	v_cvt_pk_bf16_f32 v8, v2, v3
	v_cvt_pk_bf16_f32 v9, v4, v5
	s_and_b64 vcc, exec, s[8:9]
	s_mov_b32 s12, s0
	s_mov_b32 s13, s6
	s_mov_b64 s[2:3], s[10:11]
	global_store_dwordx4 v[162:163], v[126:129], off
	global_store_dwordx4 v[110:111], v[106:109], off
	global_store_dwordx4 v[94:95], v[90:93], off
	global_store_dwordx4 v[78:79], v[74:77], off
	global_store_dwordx4 v[78:79], v[70:73], off offset:256
	global_store_dwordx4 v[66:67], v[62:65], off
	global_store_dwordx4 v[46:47], v[42:45], off
	global_store_dwordx4 v[30:31], v[26:29], off
	global_store_dwordx4 v[14:15], v[10:13], off
	global_store_dwordx4 v[14:15], v[6:9], off offset:256
	s_cbranch_vccz .LBB0_492
	s_waitcnt vmcnt(0)
	s_cmpk_gt_u32 s5, 0xff
	s_cbranch_scc1 .LBB0_499
	s_barrier

.LBB0_553:
	s_add_u32 s2, s0, 0xfffe0080
	s_addc_u32 s3, s1, -1
	s_add_i32 s34, 0, 0x10000
	v_add_u32_e32 v0, s34, v156
	ds_read_b128 v[144:147], v0
	ds_read_b128 v[148:151], v0 offset:1024
	ds_read_b128 v[152:155], v0 offset:2048
	ds_read_b128 v[158:161], v0 offset:3072
	s_cmp_eq_u32 s50, 4
	s_cselect_b32 s3, s7, s3
	s_cselect_b32 s2, s13, s2
	s_cselect_b32 s15, s9, s17
	s_cselect_b32 s14, s8, s16
	v_lshl_add_u64 v[196:197], s[0:1], 0, v[140:141]
	s_add_i32 m0, s19, 0xc000
	ds_read_b128 v[162:165], v157
	ds_read_b128 v[166:169], v157 offset:1024
	ds_read_b128 v[170:173], v157 offset:2048
	ds_read_b128 v[174:177], v157 offset:3072
	ds_read_b128 v[178:181], v157 offset:4096
	ds_read_b128 v[182:185], v157 offset:5120
	ds_read_b128 v[186:189], v157 offset:6144
	ds_read_b128 v[190:193], v157 offset:7168
	global_load_lds_dwordx4 v[196:197], off
	v_lshl_add_u64 v[196:197], s[0:1], 0, v[142:143]
	s_add_i32 m0, s19, 0xe000
	s_nop 0
	global_load_lds_dwordx4 v[196:197], off
	s_waitcnt vmcnt(10)
	s_waitcnt lgkmcnt(8)
	s_barrier
	s_waitcnt lgkmcnt(0)
	s_setprio 1
	s_waitcnt lgkmcnt(0)
	v_mfma_f32_16x16x32_bf16 v[126:129], v[144:147], v[162:165], v[126:129]
	v_mfma_f32_16x16x32_bf16 v[122:125], v[152:155], v[162:165], v[122:125]
	v_mfma_f32_16x16x32_bf16 v[110:113], v[144:147], v[170:173], v[110:113]
	v_mfma_f32_16x16x32_bf16 v[106:109], v[152:155], v[170:173], v[106:109]
	v_mfma_f32_16x16x32_bf16 v[94:97], v[144:147], v[178:181], v[94:97]
	v_mfma_f32_16x16x32_bf16 v[90:93], v[152:155], v[178:181], v[90:93]
	v_mfma_f32_16x16x32_bf16 v[78:81], v[144:147], v[186:189], v[78:81]
	v_mfma_f32_16x16x32_bf16 v[74:77], v[152:155], v[186:189], v[74:77]
	v_mfma_f32_16x16x32_bf16 v[126:129], v[148:151], v[166:169], v[126:129]
	v_mfma_f32_16x16x32_bf16 v[122:125], v[158:161], v[166:169], v[122:125]
	v_mfma_f32_16x16x32_bf16 v[110:113], v[148:151], v[174:177], v[110:113]
	v_mfma_f32_16x16x32_bf16 v[106:109], v[158:161], v[174:177], v[106:109]
	v_mfma_f32_16x16x32_bf16 v[94:97], v[148:151], v[182:185], v[94:97]
	v_mfma_f32_16x16x32_bf16 v[90:93], v[158:161], v[182:185], v[90:93]
	v_mfma_f32_16x16x32_bf16 v[78:81], v[148:151], v[190:193], v[78:81]
	v_mfma_f32_16x16x32_bf16 v[74:77], v[158:161], v[190:193], v[74:77]
	s_setprio 0
	s_barrier
	s_add_i32 s40, 0, 0x14000
	s_add_i32 s34, s34, s18
	v_add_u32_e32 v0, s40, v156
	v_lshl_add_u64 v[196:197], s[14:15], 0, v[132:133]
	s_mov_b32 m0, s34
	ds_read_b128 v[200:203], v0
	ds_read_b128 v[206:209], v0 offset:1024
	ds_read_b128 v[210:213], v0 offset:2048
	ds_read_b128 v[214:217], v0 offset:3072
	global_load_lds_dwordx4 v[196:197], off
	v_lshl_add_u64 v[198:199], s[14:15], 0, v[136:137]
	s_add_i32 m0, s34, 0x2000
	s_nop 0
	global_load_lds_dwordx4 v[198:199], off
	s_mov_b32 m0, s19
	v_lshl_add_u64 v[218:219], s[2:3], 0, v[130:131]
	global_load_lds_dwordx4 v[218:219], off
	v_lshl_add_u64 v[220:221], s[2:3], 0, v[134:135]
	s_mov_b32 m0, s38
	s_nop 0
	global_load_lds_dwordx4 v[220:221], off
	s_waitcnt vmcnt(12)
	s_barrier
	s_waitcnt lgkmcnt(0)
	s_setprio 1
	s_waitcnt lgkmcnt(0)
	v_mfma_f32_16x16x32_bf16 v[118:121], v[200:203], v[162:165], v[118:121]
	v_mfma_f32_16x16x32_bf16 v[114:117], v[210:213], v[162:165], v[114:117]
	v_mfma_f32_16x16x32_bf16 v[102:105], v[200:203], v[170:173], v[102:105]
	v_mfma_f32_16x16x32_bf16 v[98:101], v[210:213], v[170:173], v[98:101]
	v_mfma_f32_16x16x32_bf16 v[86:89], v[200:203], v[178:181], v[86:89]
	v_mfma_f32_16x16x32_bf16 v[82:85], v[210:213], v[178:181], v[82:85]
	v_mfma_f32_16x16x32_bf16 v[70:73], v[200:203], v[186:189], v[70:73]
	v_mfma_f32_16x16x32_bf16 v[66:69], v[210:213], v[186:189], v[66:69]
	v_mfma_f32_16x16x32_bf16 v[118:121], v[206:209], v[166:169], v[118:121]
	v_mfma_f32_16x16x32_bf16 v[114:117], v[214:217], v[166:169], v[114:117]
	v_mfma_f32_16x16x32_bf16 v[102:105], v[206:209], v[174:177], v[102:105]
	v_mfma_f32_16x16x32_bf16 v[98:101], v[214:217], v[174:177], v[98:101]
	v_mfma_f32_16x16x32_bf16 v[86:89], v[206:209], v[182:185], v[86:89]
	v_mfma_f32_16x16x32_bf16 v[82:85], v[214:217], v[182:185], v[82:85]
	v_mfma_f32_16x16x32_bf16 v[70:73], v[206:209], v[190:193], v[70:73]
	v_mfma_f32_16x16x32_bf16 v[66:69], v[214:217], v[190:193], v[66:69]
	s_setprio 0
	s_barrier
	ds_read_b128 v[162:165], v157 offset:16384
	ds_read_b128 v[166:169], v157 offset:17408
	ds_read_b128 v[170:173], v157 offset:18432
	ds_read_b128 v[174:177], v157 offset:19456
	ds_read_b128 v[178:181], v157 offset:20480
	ds_read_b128 v[182:185], v157 offset:21504
	ds_read_b128 v[186:189], v157 offset:22528
	ds_read_b128 v[190:193], v157 offset:23552
	s_barrier
	s_waitcnt lgkmcnt(0)
	s_setprio 1
	s_waitcnt lgkmcnt(0)
	v_mfma_f32_16x16x32_bf16 v[62:65], v[144:147], v[162:165], v[62:65]
	v_mfma_f32_16x16x32_bf16 v[58:61], v[152:155], v[162:165], v[58:61]
	v_mfma_f32_16x16x32_bf16 v[46:49], v[144:147], v[170:173], v[46:49]
	v_mfma_f32_16x16x32_bf16 v[42:45], v[152:155], v[170:173], v[42:45]
	v_mfma_f32_16x16x32_bf16 v[30:33], v[144:147], v[178:181], v[30:33]
	v_mfma_f32_16x16x32_bf16 v[26:29], v[152:155], v[178:181], v[26:29]
	v_mfma_f32_16x16x32_bf16 v[14:17], v[144:147], v[186:189], v[14:17]
	v_mfma_f32_16x16x32_bf16 v[10:13], v[152:155], v[186:189], v[10:13]
	v_mfma_f32_16x16x32_bf16 v[62:65], v[148:151], v[166:169], v[62:65]
	v_mfma_f32_16x16x32_bf16 v[58:61], v[158:161], v[166:169], v[58:61]
	v_mfma_f32_16x16x32_bf16 v[46:49], v[148:151], v[174:177], v[46:49]
	v_mfma_f32_16x16x32_bf16 v[42:45], v[158:161], v[174:177], v[42:45]
	v_mfma_f32_16x16x32_bf16 v[30:33], v[148:151], v[182:185], v[30:33]
	v_mfma_f32_16x16x32_bf16 v[26:29], v[158:161], v[182:185], v[26:29]
	v_mfma_f32_16x16x32_bf16 v[14:17], v[148:151], v[190:193], v[14:17]
	v_mfma_f32_16x16x32_bf16 v[10:13], v[158:161], v[190:193], v[10:13]
	s_setprio 0
	s_barrier
	s_add_u32 s34, s14, 0xd0000
	s_addc_u32 s35, s15, 0
	s_add_i32 s40, s40, s18
	v_lshl_add_u64 v[144:145], s[34:35], 0, v[132:133]
	s_mov_b32 m0, s40
	s_nop 0
	global_load_lds_dwordx4 v[144:145], off
	v_lshl_add_u64 v[144:145], s[34:35], 0, v[136:137]
	s_add_i32 m0, s40, 0x2000
	s_nop 0
	global_load_lds_dwordx4 v[144:145], off
	s_waitcnt vmcnt(10)
	s_barrier
	s_setprio 1
	v_mfma_f32_16x16x32_bf16 v[54:57], v[200:203], v[162:165], v[54:57]
	v_mfma_f32_16x16x32_bf16 v[50:53], v[210:213], v[162:165], v[50:53]
	v_mfma_f32_16x16x32_bf16 v[38:41], v[200:203], v[170:173], v[38:41]
	v_mfma_f32_16x16x32_bf16 v[34:37], v[210:213], v[170:173], v[34:37]
	v_mfma_f32_16x16x32_bf16 v[22:25], v[200:203], v[178:181], v[22:25]
	v_mfma_f32_16x16x32_bf16 v[18:21], v[210:213], v[178:181], v[18:21]
	v_mfma_f32_16x16x32_bf16 v[6:9], v[200:203], v[186:189], v[6:9]
	v_mfma_f32_16x16x32_bf16 v[2:5], v[210:213], v[186:189], v[2:5]
	v_mfma_f32_16x16x32_bf16 v[54:57], v[206:209], v[166:169], v[54:57]
	v_mfma_f32_16x16x32_bf16 v[50:53], v[214:217], v[166:169], v[50:53]
	v_mfma_f32_16x16x32_bf16 v[38:41], v[206:209], v[174:177], v[38:41]
	v_mfma_f32_16x16x32_bf16 v[34:37], v[214:217], v[174:177], v[34:37]
	v_mfma_f32_16x16x32_bf16 v[22:25], v[206:209], v[182:185], v[22:25]
	v_mfma_f32_16x16x32_bf16 v[18:21], v[214:217], v[182:185], v[18:21]
	v_mfma_f32_16x16x32_bf16 v[6:9], v[206:209], v[190:193], v[6:9]
	v_mfma_f32_16x16x32_bf16 v[2:5], v[214:217], v[190:193], v[2:5]
	s_setprio 0
	s_add_i32 s34, 0, 0x18000
	v_add_u32_e32 v0, s34, v156
	s_barrier
	ds_read_b128 v[144:147], v0
	ds_read_b128 v[148:151], v0 offset:1024
	ds_read_b128 v[152:155], v0 offset:2048
	ds_read_b128 v[158:161], v0 offset:3072
	s_add_u32 s2, s2, 0x20000
	s_addc_u32 s3, s3, 0
	s_mov_b32 m0, s39
	v_lshl_add_u64 v[200:201], s[2:3], 0, v[130:131]
	ds_read_b128 v[162:165], v157 offset:32768
	ds_read_b128 v[166:169], v157 offset:33792
	ds_read_b128 v[170:173], v157 offset:34816
	ds_read_b128 v[174:177], v157 offset:35840
	ds_read_b128 v[178:181], v157 offset:36864
	ds_read_b128 v[182:185], v157 offset:37888
	ds_read_b128 v[186:189], v157 offset:38912
	ds_read_b128 v[190:193], v157 offset:39936
	global_load_lds_dwordx4 v[200:201], off
	v_lshl_add_u64 v[200:201], s[2:3], 0, v[134:135]
	s_mov_b32 m0, s44
	s_nop 0
	global_load_lds_dwordx4 v[200:201], off
	s_waitcnt vmcnt(10)
	s_waitcnt lgkmcnt(8)
	s_barrier
	s_waitcnt lgkmcnt(0)
	s_setprio 1
	s_waitcnt lgkmcnt(0)
	v_mfma_f32_16x16x32_bf16 v[126:129], v[144:147], v[162:165], v[126:129]
	v_mfma_f32_16x16x32_bf16 v[122:125], v[152:155], v[162:165], v[122:125]
	v_mfma_f32_16x16x32_bf16 v[110:113], v[144:147], v[170:173], v[110:113]
	v_mfma_f32_16x16x32_bf16 v[106:109], v[152:155], v[170:173], v[106:109]
	v_mfma_f32_16x16x32_bf16 v[94:97], v[144:147], v[178:181], v[94:97]
	v_mfma_f32_16x16x32_bf16 v[90:93], v[152:155], v[178:181], v[90:93]
	v_mfma_f32_16x16x32_bf16 v[78:81], v[144:147], v[186:189], v[78:81]
	v_mfma_f32_16x16x32_bf16 v[74:77], v[152:155], v[186:189], v[74:77]
	v_mfma_f32_16x16x32_bf16 v[126:129], v[148:151], v[166:169], v[126:129]
	v_mfma_f32_16x16x32_bf16 v[122:125], v[158:161], v[166:169], v[122:125]
	v_mfma_f32_16x16x32_bf16 v[110:113], v[148:151], v[174:177], v[110:113]
	v_mfma_f32_16x16x32_bf16 v[106:109], v[158:161], v[174:177], v[106:109]
	v_mfma_f32_16x16x32_bf16 v[94:97], v[148:151], v[182:185], v[94:97]
	v_mfma_f32_16x16x32_bf16 v[90:93], v[158:161], v[182:185], v[90:93]
	v_mfma_f32_16x16x32_bf16 v[78:81], v[148:151], v[190:193], v[78:81]
	v_mfma_f32_16x16x32_bf16 v[74:77], v[158:161], v[190:193], v[74:77]
	s_setprio 0
	s_barrier
	s_add_i32 s35, 0, 0x1c000
	s_add_i32 s2, s34, s18
	v_add_u32_e32 v0, s35, v156
	v_lshl_add_u64 v[196:197], v[196:197], 0, s[74:75]
	s_mov_b32 m0, s2
	ds_read_b128 v[200:203], v0
	ds_read_b128 v[206:209], v0 offset:1024
	ds_read_b128 v[210:213], v0 offset:2048
	ds_read_b128 v[214:217], v0 offset:3072
	global_load_lds_dwordx4 v[196:197], off
	v_lshl_add_u64 v[196:197], v[198:199], 0, s[74:75]
	s_add_i32 m0, s2, 0x2000
	s_nop 0
	global_load_lds_dwordx4 v[196:197], off
	s_mov_b32 m0, s51
	v_lshl_add_u64 v[196:197], v[218:219], 0, s[74:75]
	global_load_lds_dwordx4 v[196:197], off
	v_lshl_add_u64 v[196:197], v[220:221], 0, s[74:75]
	s_mov_b32 m0, s52
	s_nop 0
	global_load_lds_dwordx4 v[196:197], off
	s_waitcnt vmcnt(12)
	s_barrier
	s_waitcnt lgkmcnt(0)
	s_setprio 1
	s_waitcnt lgkmcnt(0)
	v_mfma_f32_16x16x32_bf16 v[118:121], v[200:203], v[162:165], v[118:121]
	v_mfma_f32_16x16x32_bf16 v[114:117], v[210:213], v[162:165], v[114:117]
	v_mfma_f32_16x16x32_bf16 v[102:105], v[200:203], v[170:173], v[102:105]
	v_mfma_f32_16x16x32_bf16 v[98:101], v[210:213], v[170:173], v[98:101]
	v_mfma_f32_16x16x32_bf16 v[86:89], v[200:203], v[178:181], v[86:89]
	v_mfma_f32_16x16x32_bf16 v[82:85], v[210:213], v[178:181], v[82:85]
	v_mfma_f32_16x16x32_bf16 v[70:73], v[200:203], v[186:189], v[70:73]
	v_mfma_f32_16x16x32_bf16 v[66:69], v[210:213], v[186:189], v[66:69]
	v_mfma_f32_16x16x32_bf16 v[118:121], v[206:209], v[166:169], v[118:121]
	v_mfma_f32_16x16x32_bf16 v[114:117], v[214:217], v[166:169], v[114:117]
	v_mfma_f32_16x16x32_bf16 v[102:105], v[206:209], v[174:177], v[102:105]
	v_mfma_f32_16x16x32_bf16 v[98:101], v[214:217], v[174:177], v[98:101]
	v_mfma_f32_16x16x32_bf16 v[86:89], v[206:209], v[182:185], v[86:89]
	v_mfma_f32_16x16x32_bf16 v[82:85], v[214:217], v[182:185], v[82:85]
	v_mfma_f32_16x16x32_bf16 v[70:73], v[206:209], v[190:193], v[70:73]
	v_mfma_f32_16x16x32_bf16 v[66:69], v[214:217], v[190:193], v[66:69]
	s_setprio 0
	s_barrier
	ds_read_b128 v[162:165], v157 offset:49152
	ds_read_b128 v[166:169], v157 offset:50176
	ds_read_b128 v[170:173], v157 offset:51200
	ds_read_b128 v[174:177], v157 offset:52224
	ds_read_b128 v[178:181], v157 offset:53248
	ds_read_b128 v[182:185], v157 offset:54272
	ds_read_b128 v[186:189], v157 offset:55296
	ds_read_b128 v[190:193], v157 offset:56320
	s_barrier
	s_waitcnt lgkmcnt(0)
	s_setprio 1
	s_waitcnt lgkmcnt(0)
	v_mfma_f32_16x16x32_bf16 v[62:65], v[144:147], v[162:165], v[62:65]
	v_mfma_f32_16x16x32_bf16 v[58:61], v[152:155], v[162:165], v[58:61]
	v_mfma_f32_16x16x32_bf16 v[46:49], v[144:147], v[170:173], v[46:49]
	v_mfma_f32_16x16x32_bf16 v[42:45], v[152:155], v[170:173], v[42:45]
	v_mfma_f32_16x16x32_bf16 v[30:33], v[144:147], v[178:181], v[30:33]
	v_mfma_f32_16x16x32_bf16 v[26:29], v[152:155], v[178:181], v[26:29]
	v_mfma_f32_16x16x32_bf16 v[14:17], v[144:147], v[186:189], v[14:17]
	v_mfma_f32_16x16x32_bf16 v[10:13], v[152:155], v[186:189], v[10:13]
	v_mfma_f32_16x16x32_bf16 v[62:65], v[148:151], v[166:169], v[62:65]
	v_mfma_f32_16x16x32_bf16 v[58:61], v[158:161], v[166:169], v[58:61]
	v_mfma_f32_16x16x32_bf16 v[46:49], v[148:151], v[174:177], v[46:49]
	v_mfma_f32_16x16x32_bf16 v[42:45], v[158:161], v[174:177], v[42:45]
	v_mfma_f32_16x16x32_bf16 v[30:33], v[148:151], v[182:185], v[30:33]
	v_mfma_f32_16x16x32_bf16 v[26:29], v[158:161], v[182:185], v[26:29]
	v_mfma_f32_16x16x32_bf16 v[14:17], v[148:151], v[190:193], v[14:17]
	v_mfma_f32_16x16x32_bf16 v[10:13], v[158:161], v[190:193], v[10:13]
	s_setprio 0
	s_barrier
	s_add_u32 s2, s14, 0xd0080
	s_addc_u32 s3, s15, 0
	s_add_i32 s14, s35, s18
	v_lshl_add_u64 v[144:145], s[2:3], 0, v[132:133]
	s_mov_b32 m0, s14
	s_nop 0
	global_load_lds_dwordx4 v[144:145], off
	v_lshl_add_u64 v[144:145], s[2:3], 0, v[136:137]
	s_add_i32 m0, s14, 0x2000
	s_nop 0
	global_load_lds_dwordx4 v[144:145], off
	s_waitcnt vmcnt(10)
	s_barrier
	s_setprio 1
	v_mfma_f32_16x16x32_bf16 v[54:57], v[200:203], v[162:165], v[54:57]
	v_mfma_f32_16x16x32_bf16 v[50:53], v[210:213], v[162:165], v[50:53]
	v_mfma_f32_16x16x32_bf16 v[38:41], v[200:203], v[170:173], v[38:41]
	v_mfma_f32_16x16x32_bf16 v[34:37], v[210:213], v[170:173], v[34:37]
	v_mfma_f32_16x16x32_bf16 v[22:25], v[200:203], v[178:181], v[22:25]
	v_mfma_f32_16x16x32_bf16 v[18:21], v[210:213], v[178:181], v[18:21]
	v_mfma_f32_16x16x32_bf16 v[6:9], v[200:203], v[186:189], v[6:9]
	v_mfma_f32_16x16x32_bf16 v[2:5], v[210:213], v[186:189], v[2:5]
	v_mfma_f32_16x16x32_bf16 v[54:57], v[206:209], v[166:169], v[54:57]
	v_mfma_f32_16x16x32_bf16 v[50:53], v[214:217], v[166:169], v[50:53]
	v_mfma_f32_16x16x32_bf16 v[38:41], v[206:209], v[174:177], v[38:41]
	v_mfma_f32_16x16x32_bf16 v[34:37], v[214:217], v[174:177], v[34:37]
	v_mfma_f32_16x16x32_bf16 v[22:25], v[206:209], v[182:185], v[22:25]
	v_mfma_f32_16x16x32_bf16 v[18:21], v[214:217], v[182:185], v[18:21]
	v_mfma_f32_16x16x32_bf16 v[6:9], v[206:209], v[190:193], v[6:9]
	v_mfma_f32_16x16x32_bf16 v[2:5], v[214:217], v[190:193], v[2:5]
	s_setprio 0
	s_add_i32 s50, s50, 2
	s_add_u32 s0, s0, 0x100
	s_addc_u32 s1, s1, 0
	s_add_u32 s16, s16, 0x100
	s_addc_u32 s17, s17, 0
	s_cmp_gt_u32 s50, 5
	s_barrier
	s_cbranch_scc0 .LBB0_553
	s_lshl_b32 s14, s12, 8
	s_lshl_b32 s12, s49, 9
	s_add_i32 s14, s14, s45
	s_add_i32 s0, s12, 0x7fffc000
	s_and_b32 s7, s0, 0x7ffff000
	s_ashr_i32 s0, s14, 1
	v_mov_b32_e32 v144, 0x4f
	s_and_b32 s0, s0, 0xffffff80
	v_bitop3_b32 v158, s14, v144, v139 bitop3:0xc8
	v_or_b32_e32 v148, s0, v158
	v_ashrrev_i32_e32 v149, 31, v148
	v_readlane_b32 s0, v250, 34
	v_lshl_or_b32 v0, s49, 8, v138
	v_lshlrev_b64 v[144:145], 14, v[148:149]
	v_readlane_b32 s1, v250, 35
	v_cmp_lt_i32_e32 vcc, s56, v0
	s_nop 0
	v_lshl_add_u64 v[150:151], s[0:1], 0, v[144:145]
	v_and_b32_e32 v144, 0x778, v0
	v_lshlrev_b32_e32 v144, 1, v144
	s_and_saveexec_b64 s[0:1], vcc
	s_xor_b64 s[0:1], exec, s[0:1]
	s_lshl_b32 s2, s7, 1
	s_mov_b32 s3, s4
	v_lshl_add_u64 v[146:147], v[150:151], 0, s[2:3]
	s_lshl_b32 s2, s53, 1
	v_lshl_add_u64 v[146:147], v[146:147], 0, s[2:3]
	v_mov_b32_e32 v145, v1
	v_lshl_add_u64 v[154:155], v[146:147], 0, v[144:145]
	s_or_saveexec_b64 s[0:1], s[0:1]
	v_readlane_b32 s2, v253, 61
	v_lshlrev_b64 v[146:147], 15, v[148:149]
	v_readlane_b32 s3, v253, 62
	s_ashr_i32 s13, s12, 31
	s_nop 0
	v_lshl_add_u64 v[146:147], s[2:3], 0, v[146:147]
	v_lshl_add_u64 v[152:153], s[12:13], 1, v[146:147]
	v_lshlrev_b32_e32 v146, 1, v138
	s_xor_b64 exec, exec, s[0:1]
	s_lshl_b32 s2, s59, 1
	s_mov_b32 s3, s4
	v_lshl_add_u64 v[154:155], v[152:153], 0, s[2:3]
	v_mov_b32_e32 v147, v1
	v_lshl_add_u64 v[154:155], v[154:155], 0, v[146:147]
	s_or_b64 exec, exec, s[0:1]
	v_cvt_pk_bf16_f32 v126, v126, v127
	v_cvt_pk_bf16_f32 v127, v128, v129
	v_cvt_pk_bf16_f32 v129, v124, v125
	v_or_b32_e32 v124, 0x80, v0
	v_cvt_pk_bf16_f32 v128, v122, v123
	v_cmp_lt_i32_e64 s[0:1], s56, v124
	global_store_dwordx4 v[154:155], v[126:129], off
	s_and_saveexec_b64 s[2:3], s[0:1]
	s_xor_b64 s[2:3], exec, s[2:3]
	s_lshl_b32 s16, s7, 1
	s_mov_b32 s17, s4
	v_lshl_add_u64 v[122:123], v[150:151], 0, s[16:17]
	s_lshl_b32 s16, s53, 1
	v_lshl_add_u64 v[122:123], v[122:123], 0, s[16:17]
	s_or_saveexec_b64 s[2:3], s[2:3]
	v_mov_b32_e32 v0, 0x7f8
	s_mov_b32 s35, 0x3fb8aa3b
	s_mov_b32 s34, 0xc2ce8ed0
	s_xor_b64 exec, exec, s[2:3]
	s_lshl_b32 s16, s59, 1
	s_mov_b32 s17, s4
	v_lshl_add_u64 v[122:123], v[152:153], 0, s[16:17]
	v_mov_b32_e32 v0, 0xf8
	s_or_b64 exec, exec, s[2:3]
	v_cvt_pk_bf16_f32 v118, v118, v119
	v_cvt_pk_bf16_f32 v119, v120, v121
	v_cvt_pk_bf16_f32 v121, v116, v117
	v_or_b32_e32 v116, 16, v148
	v_and_b32_e32 v0, v0, v124
	v_ashrrev_i32_e32 v117, 31, v116
	v_readlane_b32 s2, v250, 34
	v_lshlrev_b32_e32 v0, 1, v0
	v_cvt_pk_bf16_f32 v120, v114, v115
	v_lshlrev_b64 v[114:115], 14, v[116:117]
	v_readlane_b32 s3, v250, 35
	v_lshl_add_u64 v[122:123], v[122:123], 0, v[0:1]
	global_store_dwordx4 v[122:123], v[118:121], off
	v_lshl_add_u64 v[114:115], s[2:3], 0, v[114:115]
	s_and_saveexec_b64 s[2:3], vcc
	s_xor_b64 s[2:3], exec, s[2:3]
	s_lshl_b32 s16, s7, 1
	s_mov_b32 s17, s4
	v_lshl_add_u64 v[118:119], v[114:115], 0, s[16:17]
	s_lshl_b32 s16, s53, 1
	v_lshl_add_u64 v[118:119], v[118:119], 0, s[16:17]
	v_mov_b32_e32 v145, v1
	v_lshl_add_u64 v[118:119], v[118:119], 0, v[144:145]
	s_or_saveexec_b64 s[2:3], s[2:3]
	v_readlane_b32 s16, v253, 61
	v_lshlrev_b64 v[116:117], 15, v[116:117]
	v_readlane_b32 s17, v253, 62
	s_nop 1
	v_lshl_add_u64 v[116:117], s[16:17], 0, v[116:117]
	v_lshl_add_u64 v[116:117], s[12:13], 1, v[116:117]
	s_xor_b64 exec, exec, s[2:3]
	s_lshl_b32 s16, s59, 1
	s_mov_b32 s17, s4
	v_lshl_add_u64 v[118:119], v[116:117], 0, s[16:17]
	v_mov_b32_e32 v147, v1
	v_lshl_add_u64 v[118:119], v[118:119], 0, v[146:147]
	s_or_b64 exec, exec, s[2:3]
	v_cvt_pk_bf16_f32 v110, v110, v111
	v_cvt_pk_bf16_f32 v111, v112, v113
	v_cvt_pk_bf16_f32 v112, v106, v107
	v_cvt_pk_bf16_f32 v113, v108, v109
	global_store_dwordx4 v[118:119], v[110:113], off
	s_and_saveexec_b64 s[2:3], s[0:1]
	s_xor_b64 s[2:3], exec, s[2:3]
	s_lshl_b32 s16, s7, 1
	s_mov_b32 s17, s4
	v_lshl_add_u64 v[106:107], v[114:115], 0, s[16:17]
	s_lshl_b32 s16, s53, 1
	v_lshl_add_u64 v[106:107], v[106:107], 0, s[16:17]
	s_or_saveexec_b64 s[2:3], s[2:3]
	v_mov_b32_e32 v0, 0x7f8
	s_xor_b64 exec, exec, s[2:3]
	s_lshl_b32 s16, s59, 1
	s_mov_b32 s17, s4
	v_lshl_add_u64 v[106:107], v[116:117], 0, s[16:17]
	v_mov_b32_e32 v0, 0xf8
	s_or_b64 exec, exec, s[2:3]
	v_cvt_pk_bf16_f32 v102, v102, v103
	v_cvt_pk_bf16_f32 v103, v104, v105
	v_cvt_pk_bf16_f32 v105, v100, v101
	v_or_b32_e32 v100, 32, v148
	v_and_b32_e32 v0, v0, v124
	v_ashrrev_i32_e32 v101, 31, v100
	v_readlane_b32 s2, v250, 34
	v_lshlrev_b32_e32 v0, 1, v0
	v_cvt_pk_bf16_f32 v104, v98, v99
	v_lshlrev_b64 v[98:99], 14, v[100:101]
	v_readlane_b32 s3, v250, 35
	v_lshl_add_u64 v[106:107], v[106:107], 0, v[0:1]
	global_store_dwordx4 v[106:107], v[102:105], off
	v_lshl_add_u64 v[98:99], s[2:3], 0, v[98:99]
	s_and_saveexec_b64 s[2:3], vcc
	s_xor_b64 s[2:3], exec, s[2:3]
	s_lshl_b32 s16, s7, 1
	s_mov_b32 s17, s4
	v_lshl_add_u64 v[102:103], v[98:99], 0, s[16:17]
	s_lshl_b32 s16, s53, 1
	v_lshl_add_u64 v[102:103], v[102:103], 0, s[16:17]
	v_mov_b32_e32 v145, v1
	v_lshl_add_u64 v[102:103], v[102:103], 0, v[144:145]
	s_or_saveexec_b64 s[2:3], s[2:3]
	v_readlane_b32 s16, v253, 61
	v_lshlrev_b64 v[100:101], 15, v[100:101]
	v_readlane_b32 s17, v253, 62
	s_nop 1
	v_lshl_add_u64 v[100:101], s[16:17], 0, v[100:101]
	v_lshl_add_u64 v[100:101], s[12:13], 1, v[100:101]
	s_xor_b64 exec, exec, s[2:3]
	s_lshl_b32 s16, s59, 1
	s_mov_b32 s17, s4
	v_lshl_add_u64 v[102:103], v[100:101], 0, s[16:17]
	v_mov_b32_e32 v147, v1
	v_lshl_add_u64 v[102:103], v[102:103], 0, v[146:147]
	s_or_b64 exec, exec, s[2:3]
	v_cvt_pk_bf16_f32 v94, v94, v95
	v_cvt_pk_bf16_f32 v95, v96, v97
	v_cvt_pk_bf16_f32 v96, v90, v91
	v_cvt_pk_bf16_f32 v97, v92, v93
	global_store_dwordx4 v[102:103], v[94:97], off
	s_and_saveexec_b64 s[2:3], s[0:1]
	s_xor_b64 s[2:3], exec, s[2:3]
	s_lshl_b32 s16, s7, 1
	s_mov_b32 s17, s4
	v_lshl_add_u64 v[90:91], v[98:99], 0, s[16:17]
	s_lshl_b32 s16, s53, 1
	v_lshl_add_u64 v[90:91], v[90:91], 0, s[16:17]
	s_or_saveexec_b64 s[2:3], s[2:3]
	v_mov_b32_e32 v0, 0x7f8
	s_xor_b64 exec, exec, s[2:3]
	s_lshl_b32 s16, s59, 1
	s_mov_b32 s17, s4
	v_lshl_add_u64 v[90:91], v[100:101], 0, s[16:17]
	v_mov_b32_e32 v0, 0xf8
	s_or_b64 exec, exec, s[2:3]
	v_cvt_pk_bf16_f32 v86, v86, v87
	v_cvt_pk_bf16_f32 v87, v88, v89
	v_cvt_pk_bf16_f32 v89, v84, v85
	v_or_b32_e32 v84, 48, v148
	v_and_b32_e32 v0, v0, v124
	v_ashrrev_i32_e32 v85, 31, v84
	v_readlane_b32 s2, v250, 34
	v_lshlrev_b32_e32 v0, 1, v0
	v_cvt_pk_bf16_f32 v88, v82, v83
	v_lshlrev_b64 v[82:83], 14, v[84:85]
	v_readlane_b32 s3, v250, 35
	v_lshl_add_u64 v[90:91], v[90:91], 0, v[0:1]
	global_store_dwordx4 v[90:91], v[86:89], off
	v_lshl_add_u64 v[82:83], s[2:3], 0, v[82:83]
	s_and_saveexec_b64 s[2:3], vcc
	s_xor_b64 s[2:3], exec, s[2:3]
	s_lshl_b32 s16, s7, 1
	s_mov_b32 s17, s4
	v_lshl_add_u64 v[86:87], v[82:83], 0, s[16:17]
	s_lshl_b32 s16, s53, 1
	v_lshl_add_u64 v[86:87], v[86:87], 0, s[16:17]
	v_mov_b32_e32 v145, v1
	v_lshl_add_u64 v[86:87], v[86:87], 0, v[144:145]
	s_or_saveexec_b64 s[2:3], s[2:3]
	v_readlane_b32 s16, v253, 61
	v_lshlrev_b64 v[84:85], 15, v[84:85]
	v_readlane_b32 s17, v253, 62
	s_nop 1
	v_lshl_add_u64 v[84:85], s[16:17], 0, v[84:85]
	v_lshl_add_u64 v[84:85], s[12:13], 1, v[84:85]
	s_xor_b64 exec, exec, s[2:3]
	s_lshl_b32 s16, s59, 1
	s_mov_b32 s17, s4
	v_lshl_add_u64 v[86:87], v[84:85], 0, s[16:17]
	v_mov_b32_e32 v147, v1
	v_lshl_add_u64 v[86:87], v[86:87], 0, v[146:147]
	s_or_b64 exec, exec, s[2:3]
	v_cvt_pk_bf16_f32 v78, v78, v79
	v_cvt_pk_bf16_f32 v79, v80, v81
	v_cvt_pk_bf16_f32 v80, v74, v75
	v_cvt_pk_bf16_f32 v81, v76, v77
	global_store_dwordx4 v[86:87], v[78:81], off
	s_and_saveexec_b64 s[2:3], s[0:1]
	s_xor_b64 s[2:3], exec, s[2:3]
	s_lshl_b32 s16, s7, 1
	s_mov_b32 s17, s4
	v_lshl_add_u64 v[74:75], v[82:83], 0, s[16:17]
	s_lshl_b32 s16, s53, 1
	v_lshl_add_u64 v[74:75], v[74:75], 0, s[16:17]
	s_or_saveexec_b64 s[2:3], s[2:3]
	v_mov_b32_e32 v0, 0x7f8
	s_xor_b64 exec, exec, s[2:3]
	s_lshl_b32 s16, s59, 1
	s_mov_b32 s17, s4
	v_lshl_add_u64 v[74:75], v[84:85], 0, s[16:17]
	v_mov_b32_e32 v0, 0xf8
	s_or_b64 exec, exec, s[2:3]
	v_or_b32_e32 v76, s14, v139
	v_and_b32_e32 v0, v0, v124
	v_lshlrev_b32_e32 v0, 1, v0
	v_cvt_pk_bf16_f32 v70, v70, v71
	v_cvt_pk_bf16_f32 v71, v72, v73
	v_cvt_pk_bf16_f32 v72, v66, v67
	v_add_u32_e32 v66, 0x80, v76
	v_lshl_add_u64 v[74:75], v[74:75], 0, v[0:1]
	v_cvt_pk_bf16_f32 v73, v68, v69
	v_bfe_u32 v0, v66, 7, 1
	v_ashrrev_i32_e32 v66, 1, v66
	s_movk_i32 s2, 0xff80
	global_store_dwordx4 v[74:75], v[70:73], off
	v_lshlrev_b32_e32 v68, 11, v0
	s_nop 0
	v_and_or_b32 v70, v66, s2, v158
	v_ashrrev_i32_e32 v71, 31, v70
	v_readlane_b32 s2, v250, 34
	v_lshlrev_b64 v[66:67], 14, v[70:71]
	v_readlane_b32 s3, v250, 35
	s_nop 1
	v_lshl_add_u64 v[72:73], s[2:3], 0, v[66:67]
	v_lshlrev_b32_e32 v66, 1, v68
	s_and_saveexec_b64 s[2:3], vcc
	s_xor_b64 s[2:3], exec, s[2:3]
	s_lshl_b32 s14, s7, 1
	s_mov_b32 s15, s4
	v_lshl_add_u64 v[68:69], v[72:73], 0, s[14:15]
	v_mov_b32_e32 v67, v1
	v_lshl_add_u64 v[68:69], v[68:69], 0, v[66:67]
	v_mov_b32_e32 v145, v1
	v_lshl_add_u64 v[76:77], v[68:69], 0, v[144:145]
	s_or_saveexec_b64 s[2:3], s[2:3]
	v_readlane_b32 s14, v253, 61
	v_lshlrev_b64 v[68:69], 15, v[70:71]
	v_readlane_b32 s15, v253, 62
	v_lshlrev_b32_e32 v0, 8, v0
	s_nop 0
	v_lshl_add_u64 v[68:69], s[14:15], 0, v[68:69]
	v_lshl_add_u64 v[74:75], s[12:13], 1, v[68:69]
	v_lshlrev_b32_e32 v68, 1, v0
	s_xor_b64 exec, exec, s[2:3]
	v_mov_b32_e32 v69, v1
	v_lshl_add_u64 v[76:77], v[74:75], 0, v[68:69]
	v_mov_b32_e32 v147, v1
	v_lshl_add_u64 v[76:77], v[76:77], 0, v[146:147]
	s_or_b64 exec, exec, s[2:3]
	v_cvt_pk_bf16_f32 v62, v62, v63
	v_cvt_pk_bf16_f32 v63, v64, v65
	v_cvt_pk_bf16_f32 v64, v58, v59
	v_cvt_pk_bf16_f32 v65, v60, v61
	global_store_dwordx4 v[76:77], v[62:65], off
	s_and_saveexec_b64 s[2:3], s[0:1]
	s_xor_b64 s[2:3], exec, s[2:3]
	s_lshl_b32 s14, s7, 1
	s_mov_b32 s15, s4
	v_lshl_add_u64 v[58:59], v[72:73], 0, s[14:15]
	v_mov_b32_e32 v67, v1
	v_lshl_add_u64 v[58:59], v[58:59], 0, v[66:67]
	s_or_saveexec_b64 s[2:3], s[2:3]
	v_mov_b32_e32 v0, 0x7f8
	s_xor_b64 exec, exec, s[2:3]
	v_mov_b32_e32 v69, v1
	v_lshl_add_u64 v[58:59], v[74:75], 0, v[68:69]
	v_mov_b32_e32 v0, 0xf8
	s_or_b64 exec, exec, s[2:3]
	v_cvt_pk_bf16_f32 v54, v54, v55
	v_cvt_pk_bf16_f32 v55, v56, v57
	v_cvt_pk_bf16_f32 v57, v52, v53
	v_or_b32_e32 v52, 16, v70
	v_and_b32_e32 v0, v0, v124
	v_ashrrev_i32_e32 v53, 31, v52
	v_readlane_b32 s2, v250, 34
	v_lshlrev_b32_e32 v0, 1, v0
	v_cvt_pk_bf16_f32 v56, v50, v51
	v_lshlrev_b64 v[50:51], 14, v[52:53]
	v_readlane_b32 s3, v250, 35
	v_lshl_add_u64 v[58:59], v[58:59], 0, v[0:1]
	global_store_dwordx4 v[58:59], v[54:57], off
	v_lshl_add_u64 v[50:51], s[2:3], 0, v[50:51]
	s_and_saveexec_b64 s[2:3], vcc
	s_xor_b64 s[2:3], exec, s[2:3]
	s_lshl_b32 s14, s7, 1
	s_mov_b32 s15, s4
	v_lshl_add_u64 v[54:55], v[50:51], 0, s[14:15]
	v_mov_b32_e32 v67, v1
	v_lshl_add_u64 v[54:55], v[54:55], 0, v[66:67]
	v_mov_b32_e32 v145, v1
	v_lshl_add_u64 v[54:55], v[54:55], 0, v[144:145]
	s_or_saveexec_b64 s[2:3], s[2:3]
	v_readlane_b32 s14, v253, 61
	v_lshlrev_b64 v[52:53], 15, v[52:53]
	v_readlane_b32 s15, v253, 62
	s_nop 1
	v_lshl_add_u64 v[52:53], s[14:15], 0, v[52:53]
	v_lshl_add_u64 v[52:53], s[12:13], 1, v[52:53]
	s_xor_b64 exec, exec, s[2:3]
	v_mov_b32_e32 v69, v1
	v_lshl_add_u64 v[54:55], v[52:53], 0, v[68:69]
	v_mov_b32_e32 v147, v1
	v_lshl_add_u64 v[54:55], v[54:55], 0, v[146:147]
	s_or_b64 exec, exec, s[2:3]
	v_cvt_pk_bf16_f32 v46, v46, v47
	v_cvt_pk_bf16_f32 v47, v48, v49
	v_cvt_pk_bf16_f32 v48, v42, v43
	v_cvt_pk_bf16_f32 v49, v44, v45
	global_store_dwordx4 v[54:55], v[46:49], off
	s_and_saveexec_b64 s[2:3], s[0:1]
	s_xor_b64 s[2:3], exec, s[2:3]
	s_lshl_b32 s14, s7, 1
	s_mov_b32 s15, s4
	v_lshl_add_u64 v[42:43], v[50:51], 0, s[14:15]
	v_mov_b32_e32 v67, v1
	v_lshl_add_u64 v[42:43], v[42:43], 0, v[66:67]
	s_or_saveexec_b64 s[2:3], s[2:3]
	v_mov_b32_e32 v0, 0x7f8
	s_xor_b64 exec, exec, s[2:3]
	v_mov_b32_e32 v69, v1
	v_lshl_add_u64 v[42:43], v[52:53], 0, v[68:69]
	v_mov_b32_e32 v0, 0xf8
	s_or_b64 exec, exec, s[2:3]
	v_cvt_pk_bf16_f32 v38, v38, v39
	v_cvt_pk_bf16_f32 v39, v40, v41
	v_cvt_pk_bf16_f32 v41, v36, v37
	v_or_b32_e32 v36, 32, v70
	v_and_b32_e32 v0, v0, v124
	v_ashrrev_i32_e32 v37, 31, v36
	v_readlane_b32 s2, v250, 34
	v_lshlrev_b32_e32 v0, 1, v0
	v_cvt_pk_bf16_f32 v40, v34, v35
	v_lshlrev_b64 v[34:35], 14, v[36:37]
	v_readlane_b32 s3, v250, 35
	v_lshl_add_u64 v[42:43], v[42:43], 0, v[0:1]
	global_store_dwordx4 v[42:43], v[38:41], off
	v_lshl_add_u64 v[34:35], s[2:3], 0, v[34:35]
	s_and_saveexec_b64 s[2:3], vcc
	s_xor_b64 s[2:3], exec, s[2:3]
	s_lshl_b32 s14, s7, 1
	s_mov_b32 s15, s4
	v_lshl_add_u64 v[38:39], v[34:35], 0, s[14:15]
	v_mov_b32_e32 v67, v1
	v_lshl_add_u64 v[38:39], v[38:39], 0, v[66:67]
	v_mov_b32_e32 v145, v1
	v_lshl_add_u64 v[38:39], v[38:39], 0, v[144:145]
	s_or_saveexec_b64 s[2:3], s[2:3]
	v_readlane_b32 s14, v253, 61
	v_lshlrev_b64 v[36:37], 15, v[36:37]
	v_readlane_b32 s15, v253, 62
	s_nop 1
	v_lshl_add_u64 v[36:37], s[14:15], 0, v[36:37]
	v_lshl_add_u64 v[36:37], s[12:13], 1, v[36:37]
	s_xor_b64 exec, exec, s[2:3]
	v_mov_b32_e32 v69, v1
	v_lshl_add_u64 v[38:39], v[36:37], 0, v[68:69]
	v_mov_b32_e32 v147, v1
	v_lshl_add_u64 v[38:39], v[38:39], 0, v[146:147]
	s_or_b64 exec, exec, s[2:3]
	v_cvt_pk_bf16_f32 v30, v30, v31
	v_cvt_pk_bf16_f32 v31, v32, v33
	v_cvt_pk_bf16_f32 v32, v26, v27
	v_cvt_pk_bf16_f32 v33, v28, v29
	global_store_dwordx4 v[38:39], v[30:33], off
	s_and_saveexec_b64 s[2:3], s[0:1]
	s_xor_b64 s[2:3], exec, s[2:3]
	s_lshl_b32 s14, s7, 1
	s_mov_b32 s15, s4
	v_lshl_add_u64 v[26:27], v[34:35], 0, s[14:15]
	v_mov_b32_e32 v67, v1
	v_lshl_add_u64 v[26:27], v[26:27], 0, v[66:67]
	s_or_saveexec_b64 s[2:3], s[2:3]
	v_mov_b32_e32 v0, 0x7f8
	s_xor_b64 exec, exec, s[2:3]
	v_mov_b32_e32 v69, v1
	v_lshl_add_u64 v[26:27], v[36:37], 0, v[68:69]
	v_mov_b32_e32 v0, 0xf8
	s_or_b64 exec, exec, s[2:3]
	v_cvt_pk_bf16_f32 v22, v22, v23
	v_cvt_pk_bf16_f32 v23, v24, v25
	v_cvt_pk_bf16_f32 v25, v20, v21
	v_or_b32_e32 v20, 48, v70
	v_and_b32_e32 v0, v0, v124
	v_ashrrev_i32_e32 v21, 31, v20
	v_readlane_b32 s2, v250, 34
	v_lshlrev_b32_e32 v0, 1, v0
	v_cvt_pk_bf16_f32 v24, v18, v19
	v_lshlrev_b64 v[18:19], 14, v[20:21]
	v_readlane_b32 s3, v250, 35
	v_lshl_add_u64 v[26:27], v[26:27], 0, v[0:1]
	global_store_dwordx4 v[26:27], v[22:25], off
	v_lshl_add_u64 v[18:19], s[2:3], 0, v[18:19]
	s_and_saveexec_b64 s[2:3], vcc
	s_xor_b64 s[2:3], exec, s[2:3]
	s_lshl_b32 s14, s7, 1
	s_mov_b32 s15, s4
	v_lshl_add_u64 v[22:23], v[18:19], 0, s[14:15]
	v_mov_b32_e32 v67, v1
	v_lshl_add_u64 v[22:23], v[22:23], 0, v[66:67]
	v_mov_b32_e32 v145, v1
	v_lshl_add_u64 v[22:23], v[22:23], 0, v[144:145]
	s_or_saveexec_b64 s[2:3], s[2:3]
	v_readlane_b32 s14, v253, 61
	v_lshlrev_b64 v[20:21], 15, v[20:21]
	v_readlane_b32 s15, v253, 62
	s_nop 1
	v_lshl_add_u64 v[20:21], s[14:15], 0, v[20:21]
	v_lshl_add_u64 v[20:21], s[12:13], 1, v[20:21]
	s_xor_b64 exec, exec, s[2:3]
	v_mov_b32_e32 v69, v1
	v_lshl_add_u64 v[22:23], v[20:21], 0, v[68:69]
	v_mov_b32_e32 v147, v1
	v_lshl_add_u64 v[22:23], v[22:23], 0, v[146:147]
	s_or_b64 exec, exec, s[2:3]
	v_cvt_pk_bf16_f32 v14, v14, v15
	v_cvt_pk_bf16_f32 v15, v16, v17
	v_cvt_pk_bf16_f32 v16, v10, v11
	v_cvt_pk_bf16_f32 v17, v12, v13
	global_store_dwordx4 v[22:23], v[14:17], off
	s_and_saveexec_b64 s[2:3], s[0:1]
	s_xor_b64 s[0:1], exec, s[2:3]
	s_lshl_b32 s2, s7, 1
	s_mov_b32 s3, s4
	v_lshl_add_u64 v[10:11], v[18:19], 0, s[2:3]
	v_mov_b32_e32 v67, v1
	v_lshl_add_u64 v[10:11], v[10:11], 0, v[66:67]
	s_or_saveexec_b64 s[0:1], s[0:1]
	v_mov_b32_e32 v0, 0x7f8
	s_xor_b64 exec, exec, s[0:1]
	s_cbranch_execz .LBB0_547
	v_mov_b32_e32 v69, v1
	v_lshl_add_u64 v[10:11], v[20:21], 0, v[68:69]
	v_mov_b32_e32 v0, 0xf8
	s_branch .LBB0_547

.LBB0_644:
	s_add_u32 s2, s14, 0xfffc0080
	s_addc_u32 s3, s15, -1
	s_add_i32 s34, 0, 0x10000
	v_add_u32_e32 v0, s34, v161
	ds_read_b128 v[50:53], v0
	ds_read_b128 v[54:57], v0 offset:1024
	ds_read_b128 v[66:69], v0 offset:2048
	ds_read_b128 v[70:73], v0 offset:3072
	s_cmp_eq_u32 s50, 12
	s_cselect_b32 s3, s9, s3
	s_cselect_b32 s2, s52, s2
	s_cselect_b32 s17, s7, s55
	s_cselect_b32 s16, s53, s54
	v_lshl_add_u64 v[192:193], s[14:15], 0, v[156:157]
	s_add_i32 m0, s19, 0xc000
	ds_read_b128 v[164:167], v163
	ds_read_b128 v[168:171], v163 offset:1024
	ds_read_b128 v[172:175], v163 offset:2048
	ds_read_b128 v[176:179], v163 offset:3072
	ds_read_b128 v[180:183], v163 offset:4096
	ds_read_b128 v[184:187], v163 offset:5120
	ds_read_b128 v[188:191], v163 offset:6144
	ds_read_b128 v[206:209], v163 offset:7168
	global_load_lds_dwordx4 v[192:193], off
	v_lshl_add_u64 v[192:193], s[14:15], 0, v[158:159]
	s_add_i32 m0, s19, 0xe000
	s_nop 0
	global_load_lds_dwordx4 v[192:193], off
	s_waitcnt vmcnt(10)
	s_waitcnt lgkmcnt(8)
	s_barrier
	s_waitcnt lgkmcnt(0)
	s_setprio 1
	s_waitcnt lgkmcnt(0)
	v_mfma_f32_16x16x32_bf16 v[142:145], v[50:53], v[164:167], v[142:145]
	v_mfma_f32_16x16x32_bf16 v[138:141], v[66:69], v[164:167], v[138:141]
	v_mfma_f32_16x16x32_bf16 v[126:129], v[50:53], v[172:175], v[126:129]
	v_mfma_f32_16x16x32_bf16 v[122:125], v[66:69], v[172:175], v[122:125]
	v_mfma_f32_16x16x32_bf16 v[110:113], v[50:53], v[180:183], v[110:113]
	v_mfma_f32_16x16x32_bf16 v[106:109], v[66:69], v[180:183], v[106:109]
	v_mfma_f32_16x16x32_bf16 v[94:97], v[50:53], v[188:191], v[94:97]
	v_mfma_f32_16x16x32_bf16 v[90:93], v[66:69], v[188:191], v[90:93]
	v_mfma_f32_16x16x32_bf16 v[142:145], v[54:57], v[168:171], v[142:145]
	v_mfma_f32_16x16x32_bf16 v[138:141], v[70:73], v[168:171], v[138:141]
	v_mfma_f32_16x16x32_bf16 v[126:129], v[54:57], v[176:179], v[126:129]
	v_mfma_f32_16x16x32_bf16 v[122:125], v[70:73], v[176:179], v[122:125]
	v_mfma_f32_16x16x32_bf16 v[110:113], v[54:57], v[184:187], v[110:113]
	v_mfma_f32_16x16x32_bf16 v[106:109], v[70:73], v[184:187], v[106:109]
	v_mfma_f32_16x16x32_bf16 v[94:97], v[54:57], v[206:209], v[94:97]
	v_mfma_f32_16x16x32_bf16 v[90:93], v[70:73], v[206:209], v[90:93]
	s_setprio 0
	s_barrier
	s_add_i32 s40, 0, 0x14000
	s_add_i32 s34, s34, s18
	v_add_u32_e32 v0, s40, v161
	v_lshl_add_u64 v[192:193], s[16:17], 0, v[150:151]
	s_mov_b32 m0, s34
	ds_read_b128 v[210:213], v0
	ds_read_b128 v[214:217], v0 offset:1024
	ds_read_b128 v[218:221], v0 offset:2048
	ds_read_b128 v[200:203], v0 offset:3072
	global_load_lds_dwordx4 v[192:193], off
	v_lshl_add_u64 v[196:197], s[16:17], 0, v[146:147]
	s_add_i32 m0, s34, 0x2000
	s_nop 0
	global_load_lds_dwordx4 v[196:197], off
	s_mov_b32 m0, s19
	v_lshl_add_u64 v[198:199], s[2:3], 0, v[152:153]
	global_load_lds_dwordx4 v[198:199], off
	v_lshl_add_u64 v[222:223], s[2:3], 0, v[148:149]
	s_mov_b32 m0, s38
	s_nop 0
	global_load_lds_dwordx4 v[222:223], off
	s_waitcnt vmcnt(12)
	s_barrier
	s_waitcnt lgkmcnt(0)
	s_setprio 1
	s_waitcnt lgkmcnt(0)
	v_mfma_f32_16x16x32_bf16 v[134:137], v[210:213], v[164:167], v[134:137]
	v_mfma_f32_16x16x32_bf16 v[130:133], v[218:221], v[164:167], v[130:133]
	v_mfma_f32_16x16x32_bf16 v[118:121], v[210:213], v[172:175], v[118:121]
	v_mfma_f32_16x16x32_bf16 v[114:117], v[218:221], v[172:175], v[114:117]
	v_mfma_f32_16x16x32_bf16 v[102:105], v[210:213], v[180:183], v[102:105]
	v_mfma_f32_16x16x32_bf16 v[98:101], v[218:221], v[180:183], v[98:101]
	v_mfma_f32_16x16x32_bf16 v[86:89], v[210:213], v[188:191], v[86:89]
	v_mfma_f32_16x16x32_bf16 v[82:85], v[218:221], v[188:191], v[82:85]
	v_mfma_f32_16x16x32_bf16 v[134:137], v[214:217], v[168:171], v[134:137]
	v_mfma_f32_16x16x32_bf16 v[130:133], v[200:203], v[168:171], v[130:133]
	v_mfma_f32_16x16x32_bf16 v[118:121], v[214:217], v[176:179], v[118:121]
	v_mfma_f32_16x16x32_bf16 v[114:117], v[200:203], v[176:179], v[114:117]
	v_mfma_f32_16x16x32_bf16 v[102:105], v[214:217], v[184:187], v[102:105]
	v_mfma_f32_16x16x32_bf16 v[98:101], v[200:203], v[184:187], v[98:101]
	v_mfma_f32_16x16x32_bf16 v[86:89], v[214:217], v[206:209], v[86:89]
	v_mfma_f32_16x16x32_bf16 v[82:85], v[200:203], v[206:209], v[82:85]
	s_setprio 0
	s_barrier
	ds_read_b128 v[164:167], v163 offset:16384
	ds_read_b128 v[168:171], v163 offset:17408
	ds_read_b128 v[172:175], v163 offset:18432
	ds_read_b128 v[176:179], v163 offset:19456
	ds_read_b128 v[180:183], v163 offset:20480
	ds_read_b128 v[184:187], v163 offset:21504
	ds_read_b128 v[188:191], v163 offset:22528
	ds_read_b128 v[206:209], v163 offset:23552
	s_barrier
	s_waitcnt lgkmcnt(0)
	s_setprio 1
	s_waitcnt lgkmcnt(0)
	v_mfma_f32_16x16x32_bf16 v[78:81], v[50:53], v[164:167], v[78:81]
	v_mfma_f32_16x16x32_bf16 v[74:77], v[66:69], v[164:167], v[74:77]
	v_mfma_f32_16x16x32_bf16 v[46:49], v[50:53], v[172:175], v[46:49]
	v_mfma_f32_16x16x32_bf16 v[42:45], v[66:69], v[172:175], v[42:45]
	v_mfma_f32_16x16x32_bf16 v[30:33], v[50:53], v[180:183], v[30:33]
	v_mfma_f32_16x16x32_bf16 v[26:29], v[66:69], v[180:183], v[26:29]
	v_mfma_f32_16x16x32_bf16 v[14:17], v[50:53], v[188:191], v[14:17]
	v_mfma_f32_16x16x32_bf16 v[10:13], v[66:69], v[188:191], v[10:13]
	v_mfma_f32_16x16x32_bf16 v[78:81], v[54:57], v[168:171], v[78:81]
	v_mfma_f32_16x16x32_bf16 v[74:77], v[70:73], v[168:171], v[74:77]
	v_mfma_f32_16x16x32_bf16 v[46:49], v[54:57], v[176:179], v[46:49]
	v_mfma_f32_16x16x32_bf16 v[42:45], v[70:73], v[176:179], v[42:45]
	v_mfma_f32_16x16x32_bf16 v[30:33], v[54:57], v[184:187], v[30:33]
	v_mfma_f32_16x16x32_bf16 v[26:29], v[70:73], v[184:187], v[26:29]
	v_mfma_f32_16x16x32_bf16 v[14:17], v[54:57], v[206:209], v[14:17]
	v_mfma_f32_16x16x32_bf16 v[10:13], v[70:73], v[206:209], v[10:13]
	s_setprio 0
	s_barrier
	s_add_u32 s34, s16, 0x40000
	s_addc_u32 s35, s17, 0
	s_add_i32 s40, s40, s18
	v_lshl_add_u64 v[50:51], s[34:35], 0, v[150:151]
	s_mov_b32 m0, s40
	s_nop 0
	global_load_lds_dwordx4 v[50:51], off
	v_lshl_add_u64 v[50:51], s[34:35], 0, v[146:147]
	s_add_i32 m0, s40, 0x2000
	s_nop 0
	global_load_lds_dwordx4 v[50:51], off
	s_waitcnt vmcnt(10)
	s_barrier
	s_setprio 1
	v_mfma_f32_16x16x32_bf16 v[38:41], v[210:213], v[172:175], v[38:41]
	v_mfma_f32_16x16x32_bf16 v[34:37], v[218:221], v[172:175], v[34:37]
	v_mfma_f32_16x16x32_bf16 v[22:25], v[210:213], v[180:183], v[22:25]
	v_mfma_f32_16x16x32_bf16 v[18:21], v[218:221], v[180:183], v[18:21]
	v_mfma_f32_16x16x32_bf16 v[6:9], v[210:213], v[188:191], v[6:9]
	v_mfma_f32_16x16x32_bf16 v[2:5], v[218:221], v[188:191], v[2:5]
	v_mfma_f32_16x16x32_bf16 v[50:53], v[210:213], v[164:167], v[62:65]
	v_mfma_f32_16x16x32_bf16 v[54:57], v[218:221], v[164:167], v[58:61]
	v_mfma_f32_16x16x32_bf16 v[38:41], v[214:217], v[176:179], v[38:41]
	v_mfma_f32_16x16x32_bf16 v[34:37], v[200:203], v[176:179], v[34:37]
	v_mfma_f32_16x16x32_bf16 v[22:25], v[214:217], v[184:187], v[22:25]
	v_mfma_f32_16x16x32_bf16 v[18:21], v[200:203], v[184:187], v[18:21]
	v_mfma_f32_16x16x32_bf16 v[6:9], v[214:217], v[206:209], v[6:9]
	v_mfma_f32_16x16x32_bf16 v[2:5], v[200:203], v[206:209], v[2:5]
	v_mfma_f32_16x16x32_bf16 v[50:53], v[214:217], v[168:171], v[50:53]
	v_mfma_f32_16x16x32_bf16 v[54:57], v[200:203], v[168:171], v[54:57]
	s_setprio 0
	s_add_i32 s34, 0, 0x18000
	v_add_u32_e32 v0, s34, v161
	s_barrier
	ds_read_b128 v[58:61], v0
	ds_read_b128 v[62:65], v0 offset:1024
	ds_read_b128 v[66:69], v0 offset:2048
	ds_read_b128 v[70:73], v0 offset:3072
	s_add_u32 s2, s2, 0x40000
	s_addc_u32 s3, s3, 0
	s_mov_b32 m0, s39
	v_lshl_add_u64 v[206:207], s[2:3], 0, v[152:153]
	ds_read_b128 v[164:167], v163 offset:32768
	ds_read_b128 v[168:171], v163 offset:33792
	ds_read_b128 v[172:175], v163 offset:34816
	ds_read_b128 v[176:179], v163 offset:35840
	ds_read_b128 v[180:183], v163 offset:36864
	ds_read_b128 v[184:187], v163 offset:37888
	ds_read_b128 v[188:191], v163 offset:38912
	ds_read_b128 v[200:203], v163 offset:39936
	global_load_lds_dwordx4 v[206:207], off
	v_lshl_add_u64 v[206:207], s[2:3], 0, v[148:149]
	s_mov_b32 m0, s44
	s_nop 0
	global_load_lds_dwordx4 v[206:207], off
	s_waitcnt vmcnt(10)
	s_waitcnt lgkmcnt(8)
	s_barrier
	s_waitcnt lgkmcnt(0)
	s_setprio 1
	s_waitcnt lgkmcnt(0)
	v_mfma_f32_16x16x32_bf16 v[142:145], v[58:61], v[164:167], v[142:145]
	v_mfma_f32_16x16x32_bf16 v[138:141], v[66:69], v[164:167], v[138:141]
	v_mfma_f32_16x16x32_bf16 v[126:129], v[58:61], v[172:175], v[126:129]
	v_mfma_f32_16x16x32_bf16 v[122:125], v[66:69], v[172:175], v[122:125]
	v_mfma_f32_16x16x32_bf16 v[110:113], v[58:61], v[180:183], v[110:113]
	v_mfma_f32_16x16x32_bf16 v[106:109], v[66:69], v[180:183], v[106:109]
	v_mfma_f32_16x16x32_bf16 v[94:97], v[58:61], v[188:191], v[94:97]
	v_mfma_f32_16x16x32_bf16 v[90:93], v[66:69], v[188:191], v[90:93]
	v_mfma_f32_16x16x32_bf16 v[142:145], v[62:65], v[168:171], v[142:145]
	v_mfma_f32_16x16x32_bf16 v[138:141], v[70:73], v[168:171], v[138:141]
	v_mfma_f32_16x16x32_bf16 v[126:129], v[62:65], v[176:179], v[126:129]
	v_mfma_f32_16x16x32_bf16 v[122:125], v[70:73], v[176:179], v[122:125]
	v_mfma_f32_16x16x32_bf16 v[110:113], v[62:65], v[184:187], v[110:113]
	v_mfma_f32_16x16x32_bf16 v[106:109], v[70:73], v[184:187], v[106:109]
	v_mfma_f32_16x16x32_bf16 v[94:97], v[62:65], v[200:203], v[94:97]
	v_mfma_f32_16x16x32_bf16 v[90:93], v[70:73], v[200:203], v[90:93]
	s_setprio 0
	s_barrier
	s_add_i32 s35, 0, 0x1c000
	s_add_i32 s2, s34, s18
	v_add_u32_e32 v0, s35, v161
	v_lshl_add_u64 v[192:193], v[192:193], 0, s[74:75]
	s_mov_b32 m0, s2
	ds_read_b128 v[206:209], v0
	ds_read_b128 v[210:213], v0 offset:1024
	ds_read_b128 v[214:217], v0 offset:2048
	ds_read_b128 v[218:221], v0 offset:3072
	global_load_lds_dwordx4 v[192:193], off
	v_lshl_add_u64 v[192:193], v[196:197], 0, s[74:75]
	s_add_i32 m0, s2, 0x2000
	s_nop 0
	global_load_lds_dwordx4 v[192:193], off
	s_mov_b32 m0, s45
	v_lshl_add_u64 v[192:193], v[198:199], 0, s[74:75]
	global_load_lds_dwordx4 v[192:193], off
	v_lshl_add_u64 v[192:193], v[222:223], 0, s[74:75]
	s_mov_b32 m0, s67
	s_nop 0
	global_load_lds_dwordx4 v[192:193], off
	s_waitcnt vmcnt(12)
	s_barrier
	s_waitcnt lgkmcnt(0)
	s_setprio 1
	s_waitcnt lgkmcnt(0)
	v_mfma_f32_16x16x32_bf16 v[134:137], v[206:209], v[164:167], v[134:137]
	v_mfma_f32_16x16x32_bf16 v[130:133], v[214:217], v[164:167], v[130:133]
	v_mfma_f32_16x16x32_bf16 v[118:121], v[206:209], v[172:175], v[118:121]
	v_mfma_f32_16x16x32_bf16 v[114:117], v[214:217], v[172:175], v[114:117]
	v_mfma_f32_16x16x32_bf16 v[102:105], v[206:209], v[180:183], v[102:105]
	v_mfma_f32_16x16x32_bf16 v[98:101], v[214:217], v[180:183], v[98:101]
	v_mfma_f32_16x16x32_bf16 v[86:89], v[206:209], v[188:191], v[86:89]
	v_mfma_f32_16x16x32_bf16 v[82:85], v[214:217], v[188:191], v[82:85]
	v_mfma_f32_16x16x32_bf16 v[134:137], v[210:213], v[168:171], v[134:137]
	v_mfma_f32_16x16x32_bf16 v[130:133], v[218:221], v[168:171], v[130:133]
	v_mfma_f32_16x16x32_bf16 v[118:121], v[210:213], v[176:179], v[118:121]
	v_mfma_f32_16x16x32_bf16 v[114:117], v[218:221], v[176:179], v[114:117]
	v_mfma_f32_16x16x32_bf16 v[102:105], v[210:213], v[184:187], v[102:105]
	v_mfma_f32_16x16x32_bf16 v[98:101], v[218:221], v[184:187], v[98:101]
	v_mfma_f32_16x16x32_bf16 v[86:89], v[210:213], v[200:203], v[86:89]
	v_mfma_f32_16x16x32_bf16 v[82:85], v[218:221], v[200:203], v[82:85]
	s_setprio 0
	s_barrier
	ds_read_b128 v[164:167], v163 offset:49152
	ds_read_b128 v[168:171], v163 offset:50176
	ds_read_b128 v[172:175], v163 offset:51200
	ds_read_b128 v[176:179], v163 offset:52224
	ds_read_b128 v[180:183], v163 offset:53248
	ds_read_b128 v[184:187], v163 offset:54272
	ds_read_b128 v[188:191], v163 offset:55296
	ds_read_b128 v[200:203], v163 offset:56320
	s_barrier
	s_waitcnt lgkmcnt(0)
	s_setprio 1
	s_waitcnt lgkmcnt(0)
	v_mfma_f32_16x16x32_bf16 v[78:81], v[58:61], v[164:167], v[78:81]
	v_mfma_f32_16x16x32_bf16 v[74:77], v[66:69], v[164:167], v[74:77]
	v_mfma_f32_16x16x32_bf16 v[46:49], v[58:61], v[172:175], v[46:49]
	v_mfma_f32_16x16x32_bf16 v[42:45], v[66:69], v[172:175], v[42:45]
	v_mfma_f32_16x16x32_bf16 v[30:33], v[58:61], v[180:183], v[30:33]
	v_mfma_f32_16x16x32_bf16 v[26:29], v[66:69], v[180:183], v[26:29]
	v_mfma_f32_16x16x32_bf16 v[14:17], v[58:61], v[188:191], v[14:17]
	v_mfma_f32_16x16x32_bf16 v[10:13], v[66:69], v[188:191], v[10:13]
	v_mfma_f32_16x16x32_bf16 v[78:81], v[62:65], v[168:171], v[78:81]
	v_mfma_f32_16x16x32_bf16 v[74:77], v[70:73], v[168:171], v[74:77]
	v_mfma_f32_16x16x32_bf16 v[46:49], v[62:65], v[176:179], v[46:49]
	v_mfma_f32_16x16x32_bf16 v[42:45], v[70:73], v[176:179], v[42:45]
	v_mfma_f32_16x16x32_bf16 v[30:33], v[62:65], v[184:187], v[30:33]
	v_mfma_f32_16x16x32_bf16 v[26:29], v[70:73], v[184:187], v[26:29]
	v_mfma_f32_16x16x32_bf16 v[14:17], v[62:65], v[200:203], v[14:17]
	v_mfma_f32_16x16x32_bf16 v[10:13], v[70:73], v[200:203], v[10:13]
	s_setprio 0
	s_barrier
	s_add_u32 s2, s16, 0x40080
	s_addc_u32 s3, s17, 0
	s_add_i32 s16, s35, s18
	v_lshl_add_u64 v[58:59], s[2:3], 0, v[150:151]
	s_mov_b32 m0, s16
	s_nop 0
	global_load_lds_dwordx4 v[58:59], off
	v_lshl_add_u64 v[58:59], s[2:3], 0, v[146:147]
	s_add_i32 m0, s16, 0x2000
	s_nop 0
	global_load_lds_dwordx4 v[58:59], off
	s_waitcnt vmcnt(10)
	s_barrier
	s_setprio 1
	v_mfma_f32_16x16x32_bf16 v[50:53], v[206:209], v[164:167], v[50:53]
	v_mfma_f32_16x16x32_bf16 v[62:65], v[210:213], v[168:171], v[50:53]
	v_mfma_f32_16x16x32_bf16 v[50:53], v[214:217], v[164:167], v[54:57]
	v_mfma_f32_16x16x32_bf16 v[38:41], v[206:209], v[172:175], v[38:41]
	v_mfma_f32_16x16x32_bf16 v[34:37], v[214:217], v[172:175], v[34:37]
	v_mfma_f32_16x16x32_bf16 v[22:25], v[206:209], v[180:183], v[22:25]
	v_mfma_f32_16x16x32_bf16 v[18:21], v[214:217], v[180:183], v[18:21]
	v_mfma_f32_16x16x32_bf16 v[6:9], v[206:209], v[188:191], v[6:9]
	v_mfma_f32_16x16x32_bf16 v[2:5], v[214:217], v[188:191], v[2:5]
	v_mfma_f32_16x16x32_bf16 v[58:61], v[218:221], v[168:171], v[50:53]
	v_mfma_f32_16x16x32_bf16 v[38:41], v[210:213], v[176:179], v[38:41]
	v_mfma_f32_16x16x32_bf16 v[34:37], v[218:221], v[176:179], v[34:37]
	v_mfma_f32_16x16x32_bf16 v[22:25], v[210:213], v[184:187], v[22:25]
	v_mfma_f32_16x16x32_bf16 v[18:21], v[218:221], v[184:187], v[18:21]
	v_mfma_f32_16x16x32_bf16 v[6:9], v[210:213], v[200:203], v[6:9]
	v_mfma_f32_16x16x32_bf16 v[2:5], v[218:221], v[200:203], v[2:5]
	s_setprio 0
	s_add_i32 s50, s50, 2
	s_add_u32 s14, s14, 0x100
	s_addc_u32 s15, s15, 0
	s_add_u32 s54, s54, 0x100
	s_addc_u32 s55, s55, 0
	s_cmp_gt_u32 s50, 13
	s_barrier
	s_cbranch_scc0 .LBB0_644
	s_lshl_b32 s7, s49, 8
	s_mov_b64 s[2:3], -1
	s_cmp_lt_i32 s51, 13
	v_lshl_or_b32 v0, s51, 8, v162
	s_cbranch_scc0 .LBB0_647
	v_readlane_b32 s2, v249, 15
	v_readlane_b32 s3, v249, 16
	v_add_u32_e32 v68, s7, v160
	v_ashrrev_i32_e32 v53, 31, v0
	v_mov_b64_e32 v[54:55], s[2:3]
	v_mov_b32_e32 v52, v0
	v_mad_i64_i32 v[50:51], s[2:3], v68, s76, v[54:55]
	v_lshlrev_b64 v[56:57], 1, v[52:53]
	v_lshl_add_u64 v[66:67], v[50:51], 0, v[56:57]
	v_cvt_pk_bf16_f32 v50, v142, v143
	v_cvt_pk_bf16_f32 v51, v144, v145
	v_cvt_pk_bf16_f32 v52, v138, v139
	v_cvt_pk_bf16_f32 v53, v140, v141
	global_store_dwordx4 v[66:67], v[50:53], off
	s_nop 1
	v_cvt_pk_bf16_f32 v50, v134, v135
	v_cvt_pk_bf16_f32 v51, v136, v137
	v_cvt_pk_bf16_f32 v52, v130, v131
	v_cvt_pk_bf16_f32 v53, v132, v133
	global_store_dwordx4 v[66:67], v[50:53], off offset:256
	s_nop 1
	v_or_b32_e32 v50, 16, v68
	v_mad_i64_i32 v[50:51], s[2:3], v50, s76, v[54:55]
	v_lshl_add_u64 v[66:67], v[50:51], 0, v[56:57]
	v_cvt_pk_bf16_f32 v50, v126, v127
	v_cvt_pk_bf16_f32 v51, v128, v129
	v_cvt_pk_bf16_f32 v52, v122, v123
	v_cvt_pk_bf16_f32 v53, v124, v125
	global_store_dwordx4 v[66:67], v[50:53], off
	s_nop 1
	v_cvt_pk_bf16_f32 v50, v118, v119
	v_cvt_pk_bf16_f32 v51, v120, v121
	v_cvt_pk_bf16_f32 v52, v114, v115
	v_cvt_pk_bf16_f32 v53, v116, v117
	global_store_dwordx4 v[66:67], v[50:53], off offset:256
	s_nop 1
	v_or_b32_e32 v50, 32, v68
	v_mad_i64_i32 v[50:51], s[2:3], v50, s76, v[54:55]
	v_lshl_add_u64 v[66:67], v[50:51], 0, v[56:57]
	v_cvt_pk_bf16_f32 v50, v110, v111
	v_cvt_pk_bf16_f32 v51, v112, v113
	v_cvt_pk_bf16_f32 v52, v106, v107
	v_cvt_pk_bf16_f32 v53, v108, v109
	global_store_dwordx4 v[66:67], v[50:53], off
	s_nop 1
	v_cvt_pk_bf16_f32 v50, v102, v103
	v_cvt_pk_bf16_f32 v51, v104, v105
	v_cvt_pk_bf16_f32 v52, v98, v99
	v_cvt_pk_bf16_f32 v53, v100, v101
	global_store_dwordx4 v[66:67], v[50:53], off offset:256
	s_nop 1
	v_or_b32_e32 v50, 48, v68
	v_mad_i64_i32 v[50:51], s[2:3], v50, s76, v[54:55]
	v_lshl_add_u64 v[66:67], v[50:51], 0, v[56:57]
	v_cvt_pk_bf16_f32 v50, v94, v95
	v_cvt_pk_bf16_f32 v51, v96, v97
	v_cvt_pk_bf16_f32 v52, v90, v91
	v_cvt_pk_bf16_f32 v53, v92, v93
	global_store_dwordx4 v[66:67], v[50:53], off
	s_nop 1
	v_cvt_pk_bf16_f32 v50, v86, v87
	v_cvt_pk_bf16_f32 v51, v88, v89
	v_cvt_pk_bf16_f32 v52, v82, v83
	v_cvt_pk_bf16_f32 v53, v84, v85
	global_store_dwordx4 v[66:67], v[50:53], off offset:256
	s_nop 1
	v_add_u32_e32 v50, 0x80, v68
	v_mad_i64_i32 v[50:51], s[2:3], v50, s76, v[54:55]
	v_lshl_add_u64 v[66:67], v[50:51], 0, v[56:57]
	v_cvt_pk_bf16_f32 v50, v78, v79
	v_cvt_pk_bf16_f32 v51, v80, v81
	v_cvt_pk_bf16_f32 v52, v74, v75
	v_cvt_pk_bf16_f32 v53, v76, v77
	global_store_dwordx4 v[66:67], v[50:53], off
	s_nop 1
	v_cvt_pk_bf16_f32 v50, v62, v63
	v_cvt_pk_bf16_f32 v51, v64, v65
	v_cvt_pk_bf16_f32 v52, v58, v59
	v_cvt_pk_bf16_f32 v53, v60, v61
	global_store_dwordx4 v[66:67], v[50:53], off offset:256
	s_nop 1
	v_add_u32_e32 v50, 0x90, v68
	v_mad_i64_i32 v[50:51], s[2:3], v50, s76, v[54:55]
	v_lshl_add_u64 v[66:67], v[50:51], 0, v[56:57]
	v_cvt_pk_bf16_f32 v50, v46, v47
	v_cvt_pk_bf16_f32 v51, v48, v49
	v_cvt_pk_bf16_f32 v52, v42, v43
	v_cvt_pk_bf16_f32 v53, v44, v45
	global_store_dwordx4 v[66:67], v[50:53], off
	s_nop 1
	v_cvt_pk_bf16_f32 v50, v38, v39
	v_cvt_pk_bf16_f32 v51, v40, v41
	v_cvt_pk_bf16_f32 v52, v34, v35
	v_cvt_pk_bf16_f32 v53, v36, v37
	global_store_dwordx4 v[66:67], v[50:53], off offset:256
	s_nop 1
	v_add_u32_e32 v50, 0xa0, v68
	v_mad_i64_i32 v[50:51], s[2:3], v50, s76, v[54:55]
	v_lshl_add_u64 v[66:67], v[50:51], 0, v[56:57]
	v_cvt_pk_bf16_f32 v50, v30, v31
	v_cvt_pk_bf16_f32 v51, v32, v33
	v_cvt_pk_bf16_f32 v52, v26, v27
	v_cvt_pk_bf16_f32 v53, v28, v29
	global_store_dwordx4 v[66:67], v[50:53], off
	s_nop 1
	v_cvt_pk_bf16_f32 v50, v22, v23
	v_cvt_pk_bf16_f32 v51, v24, v25
	v_cvt_pk_bf16_f32 v52, v18, v19
	v_cvt_pk_bf16_f32 v53, v20, v21
	global_store_dwordx4 v[66:67], v[50:53], off offset:256
	s_nop 1
	v_add_u32_e32 v50, 0xb0, v68
	v_mad_i64_i32 v[50:51], s[2:3], v50, s76, v[54:55]
	v_lshl_add_u64 v[54:55], v[50:51], 0, v[56:57]
	v_cvt_pk_bf16_f32 v50, v14, v15
	v_cvt_pk_bf16_f32 v51, v16, v17
	v_cvt_pk_bf16_f32 v52, v10, v11
	v_cvt_pk_bf16_f32 v53, v12, v13
	global_store_dwordx4 v[54:55], v[50:53], off
	s_mov_b64 s[2:3], 0
	s_nop 0
	v_cvt_pk_bf16_f32 v50, v6, v7
	v_cvt_pk_bf16_f32 v51, v8, v9
	v_cvt_pk_bf16_f32 v52, v2, v3
	v_cvt_pk_bf16_f32 v53, v4, v5
	global_store_dwordx4 v[54:55], v[50:53], off offset:256
